# main-loop landing wait of phase 4 split into three vmcnt(10) waits before the pre-cluster barriers of phases 4,5,6 (the phase-8 wait kept)
# baseline (speedup 1.0000x reference)
.LBB0_403:
	s_add_u32 s14, s4, 0x100
	s_addc_u32 s15, s5, 0
	s_add_i32 s38, 0, 0x10000
	v_add_u32_e32 v12, s38, v193
	ds_read_b128 v[0:3], v12
	ds_read_b128 v[8:11], v12 offset:2048
	ds_read_b128 v[4:7], v12 offset:1024
	ds_read_b128 v[12:15], v12 offset:3072
	s_cmp_eq_u32 s37, 12
	s_cselect_b32 s19, s9, s15
	s_cselect_b32 s18, s8, s14
	s_cselect_b32 s17, s11, s36
	s_cselect_b32 s16, s10, s7
	v_lshl_add_u64 v[190:191], s[4:5], 0, v[186:187]
	s_add_i32 m0, s23, 0xc000
	ds_read_b128 v[16:19], v206
	ds_read_b128 v[24:27], v206 offset:2048
	ds_read_b128 v[162:165], v206 offset:4096
	ds_read_b128 v[170:173], v206 offset:6144
	ds_read_b128 v[20:23], v206 offset:1024
	ds_read_b128 v[28:31], v206 offset:3072
	ds_read_b128 v[166:169], v206 offset:5120
	ds_read_b128 v[174:177], v206 offset:7168
	global_load_lds_dwordx4 v[190:191], off
	v_lshl_add_u64 v[190:191], s[4:5], 0, v[188:189]
	s_add_i32 m0, s23, 0xe000
	s_nop 0
	global_load_lds_dwordx4 v[190:191], off
	s_waitcnt lgkmcnt(8)
	s_barrier
	s_waitcnt lgkmcnt(7)
	s_setprio 1
	v_mfma_f32_16x16x32_f16 v[158:161], v[0:3], v[16:19], v[158:161]
	v_mfma_f32_16x16x32_f16 v[142:145], v[8:11], v[16:19], v[142:145]
	s_waitcnt lgkmcnt(6)
	v_mfma_f32_16x16x32_f16 v[150:153], v[0:3], v[24:27], v[150:153]
	v_mfma_f32_16x16x32_f16 v[134:137], v[8:11], v[24:27], v[134:137]
	s_waitcnt lgkmcnt(5)
	v_mfma_f32_16x16x32_f16 v[154:157], v[0:3], v[162:165], v[154:157]
	v_mfma_f32_16x16x32_f16 v[138:141], v[8:11], v[162:165], v[138:141]
	s_waitcnt lgkmcnt(4)
	v_mfma_f32_16x16x32_f16 v[146:149], v[0:3], v[170:173], v[146:149]
	v_mfma_f32_16x16x32_f16 v[130:133], v[8:11], v[170:173], v[130:133]
	s_waitcnt lgkmcnt(3)
	v_mfma_f32_16x16x32_f16 v[158:161], v[4:7], v[20:23], v[158:161]
	v_mfma_f32_16x16x32_f16 v[142:145], v[12:15], v[20:23], v[142:145]
	s_waitcnt lgkmcnt(2)
	v_mfma_f32_16x16x32_f16 v[150:153], v[4:7], v[28:31], v[150:153]
	v_mfma_f32_16x16x32_f16 v[134:137], v[12:15], v[28:31], v[134:137]
	s_waitcnt lgkmcnt(1)
	v_mfma_f32_16x16x32_f16 v[154:157], v[4:7], v[166:169], v[154:157]
	v_mfma_f32_16x16x32_f16 v[138:141], v[12:15], v[166:169], v[138:141]
	s_waitcnt lgkmcnt(0)
	v_mfma_f32_16x16x32_f16 v[146:149], v[4:7], v[174:177], v[146:149]
	v_mfma_f32_16x16x32_f16 v[130:133], v[12:15], v[174:177], v[130:133]
	s_setprio 0
	s_barrier
	s_add_i32 s39, 0, 0x14000
	s_add_i32 s4, s38, s22
	v_add_u32_e32 v32, s39, v193
	v_lshl_add_u64 v[190:191], s[16:17], 0, v[178:179]
	s_mov_b32 m0, s4
	ds_read_b128 v[208:211], v32
	ds_read_b128 v[216:219], v32 offset:2048
	ds_read_b128 v[212:215], v32 offset:1024
	ds_read_b128 v[230:233], v32 offset:3072
	global_load_lds_dwordx4 v[190:191], off
	v_lshl_add_u64 v[238:239], s[16:17], 0, v[180:181]
	s_add_i32 m0, s4, 0x2000
	s_nop 0
	global_load_lds_dwordx4 v[238:239], off
	s_barrier
	s_waitcnt lgkmcnt(2)
	s_setprio 1
	v_mfma_f32_16x16x32_f16 v[94:97], v[208:211], v[16:19], v[94:97]
	v_mfma_f32_16x16x32_f16 v[16:19], v[216:219], v[16:19], v[78:81]
	s_waitcnt lgkmcnt(0)
	v_mfma_f32_16x16x32_f16 v[94:97], v[212:215], v[20:23], v[94:97]
	v_mfma_f32_16x16x32_f16 v[16:19], v[230:233], v[20:23], v[16:19]
	v_mfma_f32_16x16x32_f16 v[20:23], v[208:211], v[24:27], v[86:89]
	v_mfma_f32_16x16x32_f16 v[24:27], v[216:219], v[24:27], v[70:73]
	v_mfma_f32_16x16x32_f16 v[70:73], v[216:219], v[162:165], v[74:77]
	v_mfma_f32_16x16x32_f16 v[74:77], v[230:233], v[166:169], v[70:73]
	v_mfma_f32_16x16x32_f16 v[70:73], v[208:211], v[170:173], v[82:85]
	v_mfma_f32_16x16x32_f16 v[66:69], v[216:219], v[170:173], v[66:69]
	v_mfma_f32_16x16x32_f16 v[20:23], v[212:215], v[28:31], v[20:23]
	v_mfma_f32_16x16x32_f16 v[24:27], v[230:233], v[28:31], v[24:27]
	v_mfma_f32_16x16x32_f16 v[28:31], v[208:211], v[162:165], v[90:93]
	v_mfma_f32_16x16x32_f16 v[82:85], v[212:215], v[174:177], v[70:73]
	v_mfma_f32_16x16x32_f16 v[66:69], v[230:233], v[174:177], v[66:69]
	v_mfma_f32_16x16x32_f16 v[28:31], v[212:215], v[166:169], v[28:31]
	s_setprio 0
	s_mov_b32 m0, s23
	v_lshl_add_u64 v[240:241], s[18:19], 0, v[178:179]
	s_barrier
	ds_read_b128 v[70:73], v206 offset:16384
	ds_read_b128 v[86:89], v206 offset:18432
	ds_read_b128 v[162:165], v206 offset:20480
	ds_read_b128 v[170:173], v206 offset:22528
	ds_read_b128 v[78:81], v206 offset:17408
	ds_read_b128 v[90:93], v206 offset:19456
	ds_read_b128 v[166:169], v206 offset:21504
	ds_read_b128 v[174:177], v206 offset:23552
	global_load_lds_dwordx4 v[240:241], off
	v_lshl_add_u64 v[242:243], s[18:19], 0, v[180:181]
	s_mov_b32 m0, s24
	s_nop 0
	global_load_lds_dwordx4 v[242:243], off
	s_barrier
	s_waitcnt lgkmcnt(7)
	s_setprio 1
	v_mfma_f32_16x16x32_f16 v[126:129], v[0:3], v[70:73], v[126:129]
	v_mfma_f32_16x16x32_f16 v[110:113], v[8:11], v[70:73], v[110:113]
	s_waitcnt lgkmcnt(6)
	v_mfma_f32_16x16x32_f16 v[118:121], v[0:3], v[86:89], v[118:121]
	v_mfma_f32_16x16x32_f16 v[102:105], v[8:11], v[86:89], v[102:105]
	s_waitcnt lgkmcnt(5)
	v_mfma_f32_16x16x32_f16 v[122:125], v[0:3], v[162:165], v[122:125]
	v_mfma_f32_16x16x32_f16 v[106:109], v[8:11], v[162:165], v[106:109]
	s_waitcnt lgkmcnt(3)
	v_mfma_f32_16x16x32_f16 v[0:3], v[0:3], v[170:173], v[114:117]
	v_mfma_f32_16x16x32_f16 v[126:129], v[4:7], v[78:81], v[126:129]
	s_waitcnt lgkmcnt(2)
	v_mfma_f32_16x16x32_f16 v[110:113], v[12:15], v[78:81], v[110:113]
	v_mfma_f32_16x16x32_f16 v[118:121], v[4:7], v[90:93], v[118:121]
	s_waitcnt lgkmcnt(1)
	v_mfma_f32_16x16x32_f16 v[102:105], v[12:15], v[90:93], v[102:105]
	v_mfma_f32_16x16x32_f16 v[122:125], v[4:7], v[166:169], v[122:125]
	s_waitcnt lgkmcnt(0)
	v_mfma_f32_16x16x32_f16 v[106:109], v[12:15], v[166:169], v[106:109]
	v_mfma_f32_16x16x32_f16 v[0:3], v[4:7], v[174:177], v[0:3]
	v_mfma_f32_16x16x32_f16 v[4:7], v[8:11], v[170:173], v[98:101]
	v_mfma_f32_16x16x32_f16 v[4:7], v[12:15], v[174:177], v[4:7]
	s_setprio 0
	s_barrier
	s_add_u32 s4, s16, 0x40000
	s_addc_u32 s5, s17, 0
	s_add_i32 s38, s39, s22
	v_lshl_add_u64 v[8:9], s[4:5], 0, v[178:179]
	s_mov_b32 m0, s38
	s_nop 0
	global_load_lds_dwordx4 v[8:9], off
	v_lshl_add_u64 v[8:9], s[4:5], 0, v[180:181]
	s_add_i32 m0, s38, 0x2000
	s_nop 0
	global_load_lds_dwordx4 v[8:9], off
	s_waitcnt vmcnt(10)
	s_barrier
	s_setprio 1
	v_mfma_f32_16x16x32_f16 v[12:15], v[216:219], v[70:73], v[46:49]
	v_mfma_f32_16x16x32_f16 v[46:49], v[208:211], v[86:89], v[54:57]
	v_mfma_f32_16x16x32_f16 v[54:57], v[212:215], v[90:93], v[46:49]
	v_mfma_f32_16x16x32_f16 v[46:49], v[208:211], v[162:165], v[58:61]
	v_mfma_f32_16x16x32_f16 v[38:41], v[216:219], v[86:89], v[38:41]
	v_mfma_f32_16x16x32_f16 v[58:61], v[212:215], v[166:169], v[46:49]
	v_mfma_f32_16x16x32_f16 v[42:45], v[216:219], v[162:165], v[42:45]
	v_mfma_f32_16x16x32_f16 v[46:49], v[208:211], v[170:173], v[50:53]
	v_mfma_f32_16x16x32_f16 v[34:37], v[216:219], v[170:173], v[34:37]
	v_mfma_f32_16x16x32_f16 v[8:11], v[208:211], v[70:73], v[62:65]
	v_mfma_f32_16x16x32_f16 v[38:41], v[230:233], v[90:93], v[38:41]
	v_mfma_f32_16x16x32_f16 v[42:45], v[230:233], v[166:169], v[42:45]
	v_mfma_f32_16x16x32_f16 v[50:53], v[212:215], v[174:177], v[46:49]
	v_mfma_f32_16x16x32_f16 v[34:37], v[230:233], v[174:177], v[34:37]
	v_mfma_f32_16x16x32_f16 v[8:11], v[212:215], v[78:81], v[8:11]
	v_mfma_f32_16x16x32_f16 v[12:15], v[230:233], v[78:81], v[12:15]
	s_setprio 0
	s_add_i32 s38, 0, 0x18000
	v_add_u32_e32 v32, s38, v193
	s_barrier
	ds_read_b128 v[46:49], v32
	ds_read_b128 v[62:65], v32 offset:1024
	ds_read_b128 v[98:101], v32 offset:2048
	ds_read_b128 v[162:165], v32 offset:3072
	s_add_u32 s4, s18, 0x40000
	s_addc_u32 s5, s19, 0
	s_mov_b32 m0, s25
	v_lshl_add_u64 v[86:87], s[4:5], 0, v[178:179]
	ds_read_b128 v[70:73], v206 offset:32768
	ds_read_b128 v[78:81], v206 offset:33792
	ds_read_b128 v[90:93], v206 offset:34816
	ds_read_b128 v[114:117], v206 offset:35840
	ds_read_b128 v[166:169], v206 offset:36864
	ds_read_b128 v[170:173], v206 offset:37888
	ds_read_b128 v[174:177], v206 offset:38912
	ds_read_b128 v[208:211], v206 offset:39936
	global_load_lds_dwordx4 v[86:87], off
	v_lshl_add_u64 v[86:87], s[4:5], 0, v[180:181]
	s_mov_b32 m0, s26
	s_nop 0
	global_load_lds_dwordx4 v[86:87], off
	s_waitcnt lgkmcnt(8)
	s_waitcnt vmcnt(10)
	s_barrier
	s_waitcnt lgkmcnt(6)
	s_setprio 1
	v_mfma_f32_16x16x32_f16 v[86:89], v[46:49], v[70:73], v[158:161]
	v_mfma_f32_16x16x32_f16 v[158:161], v[62:65], v[78:81], v[86:89]
	v_mfma_f32_16x16x32_f16 v[86:89], v[98:101], v[70:73], v[142:145]
	v_mfma_f32_16x16x32_f16 v[142:145], v[162:165], v[78:81], v[86:89]
	s_waitcnt lgkmcnt(4)
	v_mfma_f32_16x16x32_f16 v[86:89], v[46:49], v[90:93], v[150:153]
	v_mfma_f32_16x16x32_f16 v[150:153], v[62:65], v[114:117], v[86:89]
	v_mfma_f32_16x16x32_f16 v[86:89], v[98:101], v[90:93], v[134:137]
	v_mfma_f32_16x16x32_f16 v[134:137], v[162:165], v[114:117], v[86:89]
	s_waitcnt lgkmcnt(2)
	v_mfma_f32_16x16x32_f16 v[86:89], v[46:49], v[166:169], v[154:157]
	v_mfma_f32_16x16x32_f16 v[154:157], v[62:65], v[170:173], v[86:89]
	v_mfma_f32_16x16x32_f16 v[86:89], v[98:101], v[166:169], v[138:141]
	v_mfma_f32_16x16x32_f16 v[138:141], v[162:165], v[170:173], v[86:89]
	s_waitcnt lgkmcnt(0)
	v_mfma_f32_16x16x32_f16 v[86:89], v[46:49], v[174:177], v[146:149]
	v_mfma_f32_16x16x32_f16 v[146:149], v[62:65], v[208:211], v[86:89]
	v_mfma_f32_16x16x32_f16 v[86:89], v[98:101], v[174:177], v[130:133]
	v_mfma_f32_16x16x32_f16 v[130:133], v[162:165], v[208:211], v[86:89]
	s_setprio 0
	s_barrier
	s_add_i32 s18, 0, 0x1c000
	s_add_i32 s4, s38, s22
	v_add_u32_e32 v32, s18, v193
	s_nop 1
	v_lshl_add_u64 v[86:87], v[190:191], 0, s[84:85]
	s_mov_b32 m0, s4
	ds_read_b128 v[212:215], v32
	ds_read_b128 v[230:233], v32 offset:2048
	ds_read_b128 v[216:219], v32 offset:1024
	ds_read_b128 v[234:237], v32 offset:3072
	global_load_lds_dwordx4 v[86:87], off
	v_lshl_add_u64 v[86:87], v[238:239], 0, s[84:85]
	s_add_i32 m0, s4, 0x2000
	s_nop 0
	global_load_lds_dwordx4 v[86:87], off
	s_waitcnt vmcnt(10)
	s_barrier
	s_waitcnt lgkmcnt(2)
	s_setprio 1
	v_mfma_f32_16x16x32_f16 v[86:89], v[212:215], v[70:73], v[94:97]
	v_mfma_f32_16x16x32_f16 v[16:19], v[230:233], v[70:73], v[16:19]
	s_waitcnt lgkmcnt(0)
	v_mfma_f32_16x16x32_f16 v[94:97], v[216:219], v[78:81], v[86:89]
	v_mfma_f32_16x16x32_f16 v[78:81], v[234:237], v[78:81], v[16:19]
	v_mfma_f32_16x16x32_f16 v[16:19], v[212:215], v[90:93], v[20:23]
	v_mfma_f32_16x16x32_f16 v[86:89], v[216:219], v[114:117], v[16:19]
	v_mfma_f32_16x16x32_f16 v[16:19], v[230:233], v[90:93], v[24:27]
	v_mfma_f32_16x16x32_f16 v[70:73], v[234:237], v[114:117], v[16:19]
	v_mfma_f32_16x16x32_f16 v[16:19], v[212:215], v[166:169], v[28:31]
	v_mfma_f32_16x16x32_f16 v[90:93], v[216:219], v[170:173], v[16:19]
	v_mfma_f32_16x16x32_f16 v[16:19], v[230:233], v[166:169], v[74:77]
	v_mfma_f32_16x16x32_f16 v[74:77], v[234:237], v[170:173], v[16:19]
	v_mfma_f32_16x16x32_f16 v[16:19], v[212:215], v[174:177], v[82:85]
	v_mfma_f32_16x16x32_f16 v[82:85], v[216:219], v[208:211], v[16:19]
	v_mfma_f32_16x16x32_f16 v[16:19], v[230:233], v[174:177], v[66:69]
	v_mfma_f32_16x16x32_f16 v[66:69], v[234:237], v[208:211], v[16:19]
	s_setprio 0
	s_mov_b32 m0, s28
	v_lshl_add_u64 v[114:115], v[240:241], 0, s[84:85]
	s_barrier
	s_nop 2
	ds_read_b128 v[16:19], v206 offset:49152
	ds_read_b128 v[20:23], v206 offset:50176
	ds_read_b128 v[24:27], v206 offset:51200
	ds_read_b128 v[28:31], v206 offset:52224
	ds_read_b128 v[166:169], v206 offset:53248
	ds_read_b128 v[174:177], v206 offset:55296
	ds_read_b128 v[170:173], v206 offset:54272
	ds_read_b128 v[208:211], v206 offset:56320
	global_load_lds_dwordx4 v[114:115], off
	v_lshl_add_u64 v[114:115], v[242:243], 0, s[84:85]
	s_mov_b32 m0, s29
	s_nop 0
	global_load_lds_dwordx4 v[114:115], off
	s_barrier
	s_waitcnt lgkmcnt(6)
	s_setprio 1
	v_mfma_f32_16x16x32_f16 v[114:117], v[46:49], v[16:19], v[126:129]
	v_mfma_f32_16x16x32_f16 v[126:129], v[62:65], v[20:23], v[114:117]
	s_waitcnt lgkmcnt(4)
	v_mfma_f32_16x16x32_f16 v[114:117], v[46:49], v[24:27], v[118:121]
	v_mfma_f32_16x16x32_f16 v[118:121], v[62:65], v[28:31], v[114:117]
	s_waitcnt lgkmcnt(2)
	v_mfma_f32_16x16x32_f16 v[114:117], v[46:49], v[166:169], v[122:125]
	v_mfma_f32_16x16x32_f16 v[0:3], v[46:49], v[174:177], v[0:3]
	v_mfma_f32_16x16x32_f16 v[110:113], v[98:101], v[16:19], v[110:113]
	v_mfma_f32_16x16x32_f16 v[102:105], v[98:101], v[24:27], v[102:105]
	s_waitcnt lgkmcnt(1)
	v_mfma_f32_16x16x32_f16 v[122:125], v[62:65], v[170:173], v[114:117]
	v_mfma_f32_16x16x32_f16 v[106:109], v[98:101], v[166:169], v[106:109]
	s_waitcnt lgkmcnt(0)
	v_mfma_f32_16x16x32_f16 v[114:117], v[62:65], v[208:211], v[0:3]
	v_mfma_f32_16x16x32_f16 v[0:3], v[98:101], v[174:177], v[4:7]
	v_mfma_f32_16x16x32_f16 v[110:113], v[162:165], v[20:23], v[110:113]
	v_mfma_f32_16x16x32_f16 v[102:105], v[162:165], v[28:31], v[102:105]
	v_mfma_f32_16x16x32_f16 v[106:109], v[162:165], v[170:173], v[106:109]
	v_mfma_f32_16x16x32_f16 v[98:101], v[162:165], v[208:211], v[0:3]
	s_setprio 0
	s_barrier
	s_add_u32 s4, s16, 0x40080
	s_addc_u32 s5, s17, 0
	s_add_i32 s16, s18, s22
	v_lshl_add_u64 v[0:1], s[4:5], 0, v[178:179]
	s_mov_b32 m0, s16
	s_nop 0
	global_load_lds_dwordx4 v[0:1], off
	v_lshl_add_u64 v[0:1], s[4:5], 0, v[180:181]
	s_add_i32 m0, s16, 0x2000
	s_nop 0
	global_load_lds_dwordx4 v[0:1], off
	s_waitcnt vmcnt(6)
	s_barrier
	s_setprio 1
	v_mfma_f32_16x16x32_f16 v[0:3], v[212:215], v[16:19], v[8:11]
	v_mfma_f32_16x16x32_f16 v[62:65], v[216:219], v[20:23], v[0:3]
	v_mfma_f32_16x16x32_f16 v[0:3], v[230:233], v[16:19], v[12:15]
	v_mfma_f32_16x16x32_f16 v[46:49], v[234:237], v[20:23], v[0:3]
	v_mfma_f32_16x16x32_f16 v[0:3], v[212:215], v[24:27], v[54:57]
	v_mfma_f32_16x16x32_f16 v[54:57], v[216:219], v[28:31], v[0:3]
	v_mfma_f32_16x16x32_f16 v[0:3], v[230:233], v[24:27], v[38:41]
	v_mfma_f32_16x16x32_f16 v[38:41], v[234:237], v[28:31], v[0:3]
	v_mfma_f32_16x16x32_f16 v[0:3], v[212:215], v[166:169], v[58:61]
	v_mfma_f32_16x16x32_f16 v[58:61], v[216:219], v[170:173], v[0:3]
	v_mfma_f32_16x16x32_f16 v[0:3], v[230:233], v[166:169], v[42:45]
	v_mfma_f32_16x16x32_f16 v[42:45], v[234:237], v[170:173], v[0:3]
	v_mfma_f32_16x16x32_f16 v[0:3], v[212:215], v[174:177], v[50:53]
	v_mfma_f32_16x16x32_f16 v[50:53], v[216:219], v[208:211], v[0:3]
	v_mfma_f32_16x16x32_f16 v[0:3], v[230:233], v[174:177], v[34:37]
	v_mfma_f32_16x16x32_f16 v[34:37], v[234:237], v[208:211], v[0:3]
	s_setprio 0
	s_add_i32 s37, s37, 2
	s_add_u32 s7, s7, 0x100
	s_addc_u32 s36, s36, 0
	s_cmp_gt_u32 s37, 13
	s_mov_b64 s[4:5], s[14:15]
	s_barrier
	s_cbranch_scc0 .LBB0_403
	s_lshl_b32 s7, s34, 8
	s_cmp_lt_i32 s35, 28
	s_mov_b64 s[4:5], -1
	s_cbranch_scc0 .LBB0_431
	s_add_i32 s16, s7, s27
	v_or_b32_e32 v207, s16, v192
	s_cmp_gt_i32 s35, 3
	s_cbranch_scc0 .LBB0_411
	s_add_i32 s4, s35, -12
	s_cmp_gt_u32 s4, 7
	s_mov_b64 s[4:5], -1
	s_cbranch_scc0 .LBB0_408
	s_lshl_b32 s4, s35, 8
	s_add_i32 s5, s4, 0xfffffc00
	s_cmp_lt_u32 s35, 12
	s_cselect_b32 s4, s4, s5
	v_and_b32_e32 v10, 7, v220
	v_and_b32_e32 v11, 8, v220
	v_cmp_ne_u32_e32 vcc, 0, v11
	v_and_b32_e32 v12, 0x60, v194
	v_lshlrev_b32_e32 v12, 1, v12
	v_lshl_or_b32 v12, v11, 2, v12
	v_and_b32_e32 v13, 0x18, v194
	v_or_b32_e32 v12, v12, v13
	v_or_b32_e32 v32, s4, v12
	v_or_b32_e32 v14, s16, v10
	v_mov_b64_e32 v[4:5], s[70:71]
	v_mad_i64_i32 v[0:1], s[4:5], v14, s33, v[4:5]
	v_lshlrev_b64 v[6:7], 1, v[32:33]
	v_lshl_add_u64 v[16:17], v[0:1], 0, v[6:7]
	v_mov_b32_e32 v32, 0x30000
	v_lshl_add_u64 v[18:19], v[16:17], 0, v[32:33]
	v_lshl_add_u64 v[20:21], v[18:19], 0, v[32:33]
	v_lshl_add_u64 v[22:23], v[20:21], 0, v[32:33]
	v_mov_b32_e32 v8, 0x180000
	v_mov_b32_e32 v9, 0
	v_lshl_add_u64 v[24:25], v[16:17], 0, v[8:9]
	v_lshl_add_u64 v[26:27], v[24:25], 0, v[32:33]
	v_lshl_add_u64 v[28:29], v[26:27], 0, v[32:33]
	v_lshl_add_u64 v[30:31], v[28:29], 0, v[32:33]
	v_mov_b32_e32 v8, 0x18000
	v_cvt_pk_f16_f32 v158, v158, v159
	v_cvt_pk_f16_f32 v159, v160, v161
	v_cvt_pk_f16_f32 v160, v142, v143
	v_cvt_pk_f16_f32 v161, v144, v145
	v_cvt_pk_f16_f32 v94, v94, v95
	v_cvt_pk_f16_f32 v95, v96, v97
	v_cvt_pk_f16_f32 v96, v78, v79
	v_cvt_pk_f16_f32 v97, v80, v81
	v_mov_b32_dpp v0, v158 row_ror:8 row_mask:0xf bank_mask:0xf
	v_mov_b32_dpp v1, v159 row_ror:8 row_mask:0xf bank_mask:0xf
	v_mov_b32_dpp v2, v160 row_ror:8 row_mask:0xf bank_mask:0xf
	v_mov_b32_dpp v3, v161 row_ror:8 row_mask:0xf bank_mask:0xf
	v_mov_b32_dpp v4, v94 row_ror:8 row_mask:0xf bank_mask:0xf
	v_mov_b32_dpp v5, v95 row_ror:8 row_mask:0xf bank_mask:0xf
	v_mov_b32_dpp v6, v96 row_ror:8 row_mask:0xf bank_mask:0xf
	v_mov_b32_dpp v7, v97 row_ror:8 row_mask:0xf bank_mask:0xf
	v_cndmask_b32_e32 v158, v158, v4, vcc
	v_cndmask_b32_e32 v159, v159, v5, vcc
	v_cndmask_b32_e32 v160, v160, v6, vcc
	v_cndmask_b32_e32 v161, v161, v7, vcc
	v_cndmask_b32_e32 v94, v0, v94, vcc
	v_cndmask_b32_e32 v95, v1, v95, vcc
	v_cndmask_b32_e32 v96, v2, v96, vcc
	v_cndmask_b32_e32 v97, v3, v97, vcc
	v_lshl_add_u64 v[10:11], v[16:17], 0, v[8:9]
	global_store_dwordx4 v[16:17], v[158:161], off
	global_store_dwordx4 v[10:11], v[94:97], off
	v_cvt_pk_f16_f32 v150, v150, v151
	v_cvt_pk_f16_f32 v151, v152, v153
	v_cvt_pk_f16_f32 v152, v134, v135
	v_cvt_pk_f16_f32 v153, v136, v137
	v_cvt_pk_f16_f32 v86, v86, v87
	v_cvt_pk_f16_f32 v87, v88, v89
	v_cvt_pk_f16_f32 v88, v70, v71
	v_cvt_pk_f16_f32 v89, v72, v73
	v_mov_b32_dpp v0, v150 row_ror:8 row_mask:0xf bank_mask:0xf
	v_mov_b32_dpp v1, v151 row_ror:8 row_mask:0xf bank_mask:0xf
	v_mov_b32_dpp v2, v152 row_ror:8 row_mask:0xf bank_mask:0xf
	v_mov_b32_dpp v3, v153 row_ror:8 row_mask:0xf bank_mask:0xf
	v_mov_b32_dpp v4, v86 row_ror:8 row_mask:0xf bank_mask:0xf
	v_mov_b32_dpp v5, v87 row_ror:8 row_mask:0xf bank_mask:0xf
	v_mov_b32_dpp v6, v88 row_ror:8 row_mask:0xf bank_mask:0xf
	v_mov_b32_dpp v7, v89 row_ror:8 row_mask:0xf bank_mask:0xf
	v_cndmask_b32_e32 v150, v150, v4, vcc
	v_cndmask_b32_e32 v151, v151, v5, vcc
	v_cndmask_b32_e32 v152, v152, v6, vcc
	v_cndmask_b32_e32 v153, v153, v7, vcc
	v_cndmask_b32_e32 v86, v0, v86, vcc
	v_cndmask_b32_e32 v87, v1, v87, vcc
	v_cndmask_b32_e32 v88, v2, v88, vcc
	v_cndmask_b32_e32 v89, v3, v89, vcc
	v_lshl_add_u64 v[10:11], v[18:19], 0, v[8:9]
	global_store_dwordx4 v[18:19], v[150:153], off
	global_store_dwordx4 v[10:11], v[86:89], off
	v_cvt_pk_f16_f32 v154, v154, v155
	v_cvt_pk_f16_f32 v155, v156, v157
	v_cvt_pk_f16_f32 v156, v138, v139
	v_cvt_pk_f16_f32 v157, v140, v141
	v_cvt_pk_f16_f32 v90, v90, v91
	v_cvt_pk_f16_f32 v91, v92, v93
	v_cvt_pk_f16_f32 v92, v74, v75
	v_cvt_pk_f16_f32 v93, v76, v77
	v_mov_b32_dpp v0, v154 row_ror:8 row_mask:0xf bank_mask:0xf
	v_mov_b32_dpp v1, v155 row_ror:8 row_mask:0xf bank_mask:0xf
	v_mov_b32_dpp v2, v156 row_ror:8 row_mask:0xf bank_mask:0xf
	v_mov_b32_dpp v3, v157 row_ror:8 row_mask:0xf bank_mask:0xf
	v_mov_b32_dpp v4, v90 row_ror:8 row_mask:0xf bank_mask:0xf
	v_mov_b32_dpp v5, v91 row_ror:8 row_mask:0xf bank_mask:0xf
	v_mov_b32_dpp v6, v92 row_ror:8 row_mask:0xf bank_mask:0xf
	v_mov_b32_dpp v7, v93 row_ror:8 row_mask:0xf bank_mask:0xf
	v_cndmask_b32_e32 v154, v154, v4, vcc
	v_cndmask_b32_e32 v155, v155, v5, vcc
	v_cndmask_b32_e32 v156, v156, v6, vcc
	v_cndmask_b32_e32 v157, v157, v7, vcc
	v_cndmask_b32_e32 v90, v0, v90, vcc
	v_cndmask_b32_e32 v91, v1, v91, vcc
	v_cndmask_b32_e32 v92, v2, v92, vcc
	v_cndmask_b32_e32 v93, v3, v93, vcc
	v_lshl_add_u64 v[10:11], v[20:21], 0, v[8:9]
	global_store_dwordx4 v[20:21], v[154:157], off
	global_store_dwordx4 v[10:11], v[90:93], off
	v_cvt_pk_f16_f32 v146, v146, v147
	v_cvt_pk_f16_f32 v147, v148, v149
	v_cvt_pk_f16_f32 v148, v130, v131
	v_cvt_pk_f16_f32 v149, v132, v133
	v_cvt_pk_f16_f32 v82, v82, v83
	v_cvt_pk_f16_f32 v83, v84, v85
	v_cvt_pk_f16_f32 v84, v66, v67
	v_cvt_pk_f16_f32 v85, v68, v69
	v_mov_b32_dpp v0, v146 row_ror:8 row_mask:0xf bank_mask:0xf
	v_mov_b32_dpp v1, v147 row_ror:8 row_mask:0xf bank_mask:0xf
	v_mov_b32_dpp v2, v148 row_ror:8 row_mask:0xf bank_mask:0xf
	v_mov_b32_dpp v3, v149 row_ror:8 row_mask:0xf bank_mask:0xf
	v_mov_b32_dpp v4, v82 row_ror:8 row_mask:0xf bank_mask:0xf
	v_mov_b32_dpp v5, v83 row_ror:8 row_mask:0xf bank_mask:0xf
	v_mov_b32_dpp v6, v84 row_ror:8 row_mask:0xf bank_mask:0xf
	v_mov_b32_dpp v7, v85 row_ror:8 row_mask:0xf bank_mask:0xf
	v_cndmask_b32_e32 v146, v146, v4, vcc
	v_cndmask_b32_e32 v147, v147, v5, vcc
	v_cndmask_b32_e32 v148, v148, v6, vcc
	v_cndmask_b32_e32 v149, v149, v7, vcc
	v_cndmask_b32_e32 v82, v0, v82, vcc
	v_cndmask_b32_e32 v83, v1, v83, vcc
	v_cndmask_b32_e32 v84, v2, v84, vcc
	v_cndmask_b32_e32 v85, v3, v85, vcc
	v_lshl_add_u64 v[10:11], v[22:23], 0, v[8:9]
	global_store_dwordx4 v[22:23], v[146:149], off
	global_store_dwordx4 v[10:11], v[82:85], off
	v_cvt_pk_f16_f32 v126, v126, v127
	v_cvt_pk_f16_f32 v127, v128, v129
	v_cvt_pk_f16_f32 v128, v110, v111
	v_cvt_pk_f16_f32 v129, v112, v113
	v_cvt_pk_f16_f32 v62, v62, v63
	v_cvt_pk_f16_f32 v63, v64, v65
	v_cvt_pk_f16_f32 v64, v46, v47
	v_cvt_pk_f16_f32 v65, v48, v49
	v_mov_b32_dpp v0, v126 row_ror:8 row_mask:0xf bank_mask:0xf
	v_mov_b32_dpp v1, v127 row_ror:8 row_mask:0xf bank_mask:0xf
	v_mov_b32_dpp v2, v128 row_ror:8 row_mask:0xf bank_mask:0xf
	v_mov_b32_dpp v3, v129 row_ror:8 row_mask:0xf bank_mask:0xf
	v_mov_b32_dpp v4, v62 row_ror:8 row_mask:0xf bank_mask:0xf
	v_mov_b32_dpp v5, v63 row_ror:8 row_mask:0xf bank_mask:0xf
	v_mov_b32_dpp v6, v64 row_ror:8 row_mask:0xf bank_mask:0xf
	v_mov_b32_dpp v7, v65 row_ror:8 row_mask:0xf bank_mask:0xf
	v_cndmask_b32_e32 v126, v126, v4, vcc
	v_cndmask_b32_e32 v127, v127, v5, vcc
	v_cndmask_b32_e32 v128, v128, v6, vcc
	v_cndmask_b32_e32 v129, v129, v7, vcc
	v_cndmask_b32_e32 v62, v0, v62, vcc
	v_cndmask_b32_e32 v63, v1, v63, vcc
	v_cndmask_b32_e32 v64, v2, v64, vcc
	v_cndmask_b32_e32 v65, v3, v65, vcc
	v_lshl_add_u64 v[10:11], v[24:25], 0, v[8:9]
	global_store_dwordx4 v[24:25], v[126:129], off
	global_store_dwordx4 v[10:11], v[62:65], off
	v_cvt_pk_f16_f32 v118, v118, v119
	v_cvt_pk_f16_f32 v119, v120, v121
	v_cvt_pk_f16_f32 v120, v102, v103
	v_cvt_pk_f16_f32 v121, v104, v105
	v_cvt_pk_f16_f32 v54, v54, v55
	v_cvt_pk_f16_f32 v55, v56, v57
	v_cvt_pk_f16_f32 v56, v38, v39
	v_cvt_pk_f16_f32 v57, v40, v41
	v_mov_b32_dpp v0, v118 row_ror:8 row_mask:0xf bank_mask:0xf
	v_mov_b32_dpp v1, v119 row_ror:8 row_mask:0xf bank_mask:0xf
	v_mov_b32_dpp v2, v120 row_ror:8 row_mask:0xf bank_mask:0xf
	v_mov_b32_dpp v3, v121 row_ror:8 row_mask:0xf bank_mask:0xf
	v_mov_b32_dpp v4, v54 row_ror:8 row_mask:0xf bank_mask:0xf
	v_mov_b32_dpp v5, v55 row_ror:8 row_mask:0xf bank_mask:0xf
	v_mov_b32_dpp v6, v56 row_ror:8 row_mask:0xf bank_mask:0xf
	v_mov_b32_dpp v7, v57 row_ror:8 row_mask:0xf bank_mask:0xf
	v_cndmask_b32_e32 v118, v118, v4, vcc
	v_cndmask_b32_e32 v119, v119, v5, vcc
	v_cndmask_b32_e32 v120, v120, v6, vcc
	v_cndmask_b32_e32 v121, v121, v7, vcc
	v_cndmask_b32_e32 v54, v0, v54, vcc
	v_cndmask_b32_e32 v55, v1, v55, vcc
	v_cndmask_b32_e32 v56, v2, v56, vcc
	v_cndmask_b32_e32 v57, v3, v57, vcc
	v_lshl_add_u64 v[10:11], v[26:27], 0, v[8:9]
	global_store_dwordx4 v[26:27], v[118:121], off
	global_store_dwordx4 v[10:11], v[54:57], off
	v_cvt_pk_f16_f32 v122, v122, v123
	v_cvt_pk_f16_f32 v123, v124, v125
	v_cvt_pk_f16_f32 v124, v106, v107
	v_cvt_pk_f16_f32 v125, v108, v109
	v_cvt_pk_f16_f32 v58, v58, v59
	v_cvt_pk_f16_f32 v59, v60, v61
	v_cvt_pk_f16_f32 v60, v42, v43
	v_cvt_pk_f16_f32 v61, v44, v45
	v_mov_b32_dpp v0, v122 row_ror:8 row_mask:0xf bank_mask:0xf
	v_mov_b32_dpp v1, v123 row_ror:8 row_mask:0xf bank_mask:0xf
	v_mov_b32_dpp v2, v124 row_ror:8 row_mask:0xf bank_mask:0xf
	v_mov_b32_dpp v3, v125 row_ror:8 row_mask:0xf bank_mask:0xf
	v_mov_b32_dpp v4, v58 row_ror:8 row_mask:0xf bank_mask:0xf
	v_mov_b32_dpp v5, v59 row_ror:8 row_mask:0xf bank_mask:0xf
	v_mov_b32_dpp v6, v60 row_ror:8 row_mask:0xf bank_mask:0xf
	v_mov_b32_dpp v7, v61 row_ror:8 row_mask:0xf bank_mask:0xf
	v_cndmask_b32_e32 v122, v122, v4, vcc
	v_cndmask_b32_e32 v123, v123, v5, vcc
	v_cndmask_b32_e32 v124, v124, v6, vcc
	v_cndmask_b32_e32 v125, v125, v7, vcc
	v_cndmask_b32_e32 v58, v0, v58, vcc
	v_cndmask_b32_e32 v59, v1, v59, vcc
	v_cndmask_b32_e32 v60, v2, v60, vcc
	v_cndmask_b32_e32 v61, v3, v61, vcc
	v_lshl_add_u64 v[10:11], v[28:29], 0, v[8:9]
	global_store_dwordx4 v[28:29], v[122:125], off
	global_store_dwordx4 v[10:11], v[58:61], off
	v_cvt_pk_f16_f32 v114, v114, v115
	v_cvt_pk_f16_f32 v115, v116, v117
	v_cvt_pk_f16_f32 v116, v98, v99
	v_cvt_pk_f16_f32 v117, v100, v101
	v_cvt_pk_f16_f32 v50, v50, v51
	v_cvt_pk_f16_f32 v51, v52, v53
	v_cvt_pk_f16_f32 v52, v34, v35
	v_cvt_pk_f16_f32 v53, v36, v37
	v_mov_b32_dpp v0, v114 row_ror:8 row_mask:0xf bank_mask:0xf
	v_mov_b32_dpp v1, v115 row_ror:8 row_mask:0xf bank_mask:0xf
	v_mov_b32_dpp v2, v116 row_ror:8 row_mask:0xf bank_mask:0xf
	v_mov_b32_dpp v3, v117 row_ror:8 row_mask:0xf bank_mask:0xf
	v_mov_b32_dpp v4, v50 row_ror:8 row_mask:0xf bank_mask:0xf
	v_mov_b32_dpp v5, v51 row_ror:8 row_mask:0xf bank_mask:0xf
	v_mov_b32_dpp v6, v52 row_ror:8 row_mask:0xf bank_mask:0xf
	v_mov_b32_dpp v7, v53 row_ror:8 row_mask:0xf bank_mask:0xf
	v_cndmask_b32_e32 v114, v114, v4, vcc
	v_cndmask_b32_e32 v115, v115, v5, vcc
	v_cndmask_b32_e32 v116, v116, v6, vcc
	v_cndmask_b32_e32 v117, v117, v7, vcc
	v_cndmask_b32_e32 v50, v0, v50, vcc
	v_cndmask_b32_e32 v51, v1, v51, vcc
	v_cndmask_b32_e32 v52, v2, v52, vcc
	v_cndmask_b32_e32 v53, v3, v53, vcc
	v_lshl_add_u64 v[10:11], v[30:31], 0, v[8:9]
	global_store_dwordx4 v[30:31], v[114:117], off
	global_store_dwordx4 v[10:11], v[50:53], off
	s_mov_b64 s[4:5], 0

.LBB0_940:
	s_add_u32 s20, s14, 0x100
	s_addc_u32 s21, s15, 0
	s_add_i32 s40, 0, 0x10000
	v_add_u32_e32 v32, s40, v209
	ds_read_b128 v[132:135], v32
	ds_read_b128 v[140:143], v32 offset:2048
	ds_read_b128 v[136:139], v32 offset:1024
	ds_read_b128 v[144:147], v32 offset:3072
	s_cmp_eq_u32 s11, 12
	s_cselect_b32 s25, s17, s21
	s_cselect_b32 s24, s16, s20
	s_cselect_b32 s23, s19, s3
	s_cselect_b32 s22, s18, s1
	v_lshl_add_u64 v[34:35], s[14:15], 0, v[200:201]
	s_add_i32 m0, s30, 0xc000
	ds_read_b128 v[148:151], v211
	ds_read_b128 v[156:159], v211 offset:2048
	ds_read_b128 v[164:167], v211 offset:4096
	ds_read_b128 v[172:175], v211 offset:6144
	ds_read_b128 v[152:155], v211 offset:1024
	ds_read_b128 v[160:163], v211 offset:3072
	ds_read_b128 v[168:171], v211 offset:5120
	ds_read_b128 v[176:179], v211 offset:7168
	global_load_lds_dwordx4 v[34:35], off
	v_lshl_add_u64 v[34:35], s[14:15], 0, v[202:203]
	s_add_i32 m0, s30, 0xe000
	s_nop 0
	global_load_lds_dwordx4 v[34:35], off
	s_waitcnt lgkmcnt(8)
	s_barrier
	s_waitcnt lgkmcnt(7)
	s_setprio 1
	v_mfma_f32_16x16x32_f16 v[128:131], v[132:135], v[148:151], v[128:131]
	v_mfma_f32_16x16x32_f16 v[124:127], v[140:143], v[148:151], v[124:127]
	s_waitcnt lgkmcnt(6)
	v_mfma_f32_16x16x32_f16 v[120:123], v[132:135], v[156:159], v[120:123]
	v_mfma_f32_16x16x32_f16 v[116:119], v[140:143], v[156:159], v[116:119]
	s_waitcnt lgkmcnt(5)
	v_mfma_f32_16x16x32_f16 v[112:115], v[132:135], v[164:167], v[112:115]
	v_mfma_f32_16x16x32_f16 v[108:111], v[140:143], v[164:167], v[108:111]
	s_waitcnt lgkmcnt(4)
	v_mfma_f32_16x16x32_f16 v[104:107], v[132:135], v[172:175], v[104:107]
	v_mfma_f32_16x16x32_f16 v[100:103], v[140:143], v[172:175], v[100:103]
	s_waitcnt lgkmcnt(3)
	v_mfma_f32_16x16x32_f16 v[128:131], v[136:139], v[152:155], v[128:131]
	v_mfma_f32_16x16x32_f16 v[124:127], v[144:147], v[152:155], v[124:127]
	s_waitcnt lgkmcnt(2)
	v_mfma_f32_16x16x32_f16 v[120:123], v[136:139], v[160:163], v[120:123]
	v_mfma_f32_16x16x32_f16 v[116:119], v[144:147], v[160:163], v[116:119]
	s_waitcnt lgkmcnt(1)
	v_mfma_f32_16x16x32_f16 v[112:115], v[136:139], v[168:171], v[112:115]
	v_mfma_f32_16x16x32_f16 v[108:111], v[144:147], v[168:171], v[108:111]
	s_waitcnt lgkmcnt(0)
	v_mfma_f32_16x16x32_f16 v[104:107], v[136:139], v[176:179], v[104:107]
	v_mfma_f32_16x16x32_f16 v[100:103], v[144:147], v[176:179], v[100:103]
	s_setprio 0
	s_barrier
	s_add_i32 s41, 0, 0x14000
	s_add_i32 s14, s40, s29
	v_add_u32_e32 v32, s41, v209
	v_lshl_add_u64 v[204:205], s[22:23], 0, v[196:197]
	s_mov_b32 m0, s14
	ds_read_b128 v[180:183], v32
	ds_read_b128 v[188:191], v32 offset:2048
	ds_read_b128 v[184:187], v32 offset:1024
	ds_read_b128 v[192:195], v32 offset:3072
	global_load_lds_dwordx4 v[204:205], off
	v_lshl_add_u64 v[206:207], s[22:23], 0, v[198:199]
	s_add_i32 m0, s14, 0x2000
	s_nop 0
	global_load_lds_dwordx4 v[206:207], off
	s_barrier
	s_waitcnt lgkmcnt(2)
	s_setprio 1
	v_mfma_f32_16x16x32_f16 v[96:99], v[180:183], v[148:151], v[96:99]
	v_mfma_f32_16x16x32_f16 v[92:95], v[188:191], v[148:151], v[92:95]
	v_mfma_f32_16x16x32_f16 v[88:91], v[180:183], v[156:159], v[88:91]
	v_mfma_f32_16x16x32_f16 v[84:87], v[188:191], v[156:159], v[84:87]
	v_mfma_f32_16x16x32_f16 v[80:83], v[180:183], v[164:167], v[80:83]
	v_mfma_f32_16x16x32_f16 v[76:79], v[188:191], v[164:167], v[76:79]
	v_mfma_f32_16x16x32_f16 v[72:75], v[180:183], v[172:175], v[72:75]
	v_mfma_f32_16x16x32_f16 v[68:71], v[188:191], v[172:175], v[68:71]
	s_waitcnt lgkmcnt(0)
	v_mfma_f32_16x16x32_f16 v[96:99], v[184:187], v[152:155], v[96:99]
	v_mfma_f32_16x16x32_f16 v[92:95], v[192:195], v[152:155], v[92:95]
	v_mfma_f32_16x16x32_f16 v[88:91], v[184:187], v[160:163], v[88:91]
	v_mfma_f32_16x16x32_f16 v[84:87], v[192:195], v[160:163], v[84:87]
	v_mfma_f32_16x16x32_f16 v[80:83], v[184:187], v[168:171], v[80:83]
	v_mfma_f32_16x16x32_f16 v[76:79], v[192:195], v[168:171], v[76:79]
	v_mfma_f32_16x16x32_f16 v[72:75], v[184:187], v[176:179], v[72:75]
	v_mfma_f32_16x16x32_f16 v[68:71], v[192:195], v[176:179], v[68:71]
	s_setprio 0
	s_mov_b32 m0, s30
	v_lshl_add_u64 v[212:213], s[24:25], 0, v[196:197]
	s_barrier
	ds_read_b128 v[148:151], v211 offset:16384
	ds_read_b128 v[156:159], v211 offset:18432
	ds_read_b128 v[164:167], v211 offset:20480
	ds_read_b128 v[172:175], v211 offset:22528
	ds_read_b128 v[152:155], v211 offset:17408
	ds_read_b128 v[160:163], v211 offset:19456
	ds_read_b128 v[168:171], v211 offset:21504
	ds_read_b128 v[176:179], v211 offset:23552
	global_load_lds_dwordx4 v[212:213], off
	v_lshl_add_u64 v[214:215], s[24:25], 0, v[198:199]
	s_mov_b32 m0, s31
	s_nop 0
	global_load_lds_dwordx4 v[214:215], off
	s_barrier
	s_waitcnt lgkmcnt(7)
	s_setprio 1
	v_mfma_f32_16x16x32_f16 v[64:67], v[132:135], v[148:151], v[64:67]
	v_mfma_f32_16x16x32_f16 v[60:63], v[140:143], v[148:151], v[60:63]
	s_waitcnt lgkmcnt(6)
	v_mfma_f32_16x16x32_f16 v[56:59], v[132:135], v[156:159], v[56:59]
	v_mfma_f32_16x16x32_f16 v[52:55], v[140:143], v[156:159], v[52:55]
	s_waitcnt lgkmcnt(5)
	v_mfma_f32_16x16x32_f16 v[48:51], v[132:135], v[164:167], v[48:51]
	v_mfma_f32_16x16x32_f16 v[44:47], v[140:143], v[164:167], v[44:47]
	s_waitcnt lgkmcnt(4)
	v_mfma_f32_16x16x32_f16 v[40:43], v[132:135], v[172:175], v[40:43]
	v_mfma_f32_16x16x32_f16 v[34:37], v[140:143], v[172:175], v[36:39]
	s_waitcnt lgkmcnt(3)
	v_mfma_f32_16x16x32_f16 v[64:67], v[136:139], v[152:155], v[64:67]
	v_mfma_f32_16x16x32_f16 v[60:63], v[144:147], v[152:155], v[60:63]
	s_waitcnt lgkmcnt(2)
	v_mfma_f32_16x16x32_f16 v[56:59], v[136:139], v[160:163], v[56:59]
	v_mfma_f32_16x16x32_f16 v[52:55], v[144:147], v[160:163], v[52:55]
	s_waitcnt lgkmcnt(1)
	v_mfma_f32_16x16x32_f16 v[48:51], v[136:139], v[168:171], v[48:51]
	v_mfma_f32_16x16x32_f16 v[44:47], v[144:147], v[168:171], v[44:47]
	s_waitcnt lgkmcnt(0)
	v_mfma_f32_16x16x32_f16 v[40:43], v[136:139], v[176:179], v[40:43]
	v_mfma_f32_16x16x32_f16 v[34:37], v[144:147], v[176:179], v[34:37]
	s_setprio 0
	s_barrier
	s_add_u32 s14, s22, 0x40000
	s_addc_u32 s15, s23, 0
	s_add_i32 s40, s41, s29
	v_lshl_add_u64 v[38:39], s[14:15], 0, v[196:197]
	s_mov_b32 m0, s40
	s_nop 0
	global_load_lds_dwordx4 v[38:39], off
	v_lshl_add_u64 v[38:39], s[14:15], 0, v[198:199]
	s_add_i32 m0, s40, 0x2000
	s_nop 0
	global_load_lds_dwordx4 v[38:39], off
	s_waitcnt vmcnt(10)
	s_barrier
	s_setprio 1
	v_mfma_f32_16x16x32_f16 v[28:31], v[180:183], v[148:151], v[28:31]
	v_mfma_f32_16x16x32_f16 v[24:27], v[188:191], v[148:151], v[24:27]
	v_mfma_f32_16x16x32_f16 v[20:23], v[180:183], v[156:159], v[20:23]
	v_mfma_f32_16x16x32_f16 v[16:19], v[188:191], v[156:159], v[16:19]
	v_mfma_f32_16x16x32_f16 v[12:15], v[180:183], v[164:167], v[12:15]
	v_mfma_f32_16x16x32_f16 v[8:11], v[188:191], v[164:167], v[8:11]
	v_mfma_f32_16x16x32_f16 v[4:7], v[180:183], v[172:175], v[4:7]
	v_mfma_f32_16x16x32_f16 v[0:3], v[188:191], v[172:175], v[0:3]
	v_mfma_f32_16x16x32_f16 v[28:31], v[184:187], v[152:155], v[28:31]
	v_mfma_f32_16x16x32_f16 v[24:27], v[192:195], v[152:155], v[24:27]
	v_mfma_f32_16x16x32_f16 v[20:23], v[184:187], v[160:163], v[20:23]
	v_mfma_f32_16x16x32_f16 v[16:19], v[192:195], v[160:163], v[16:19]
	v_mfma_f32_16x16x32_f16 v[12:15], v[184:187], v[168:171], v[12:15]
	v_mfma_f32_16x16x32_f16 v[8:11], v[192:195], v[168:171], v[8:11]
	v_mfma_f32_16x16x32_f16 v[4:7], v[184:187], v[176:179], v[4:7]
	v_mfma_f32_16x16x32_f16 v[0:3], v[192:195], v[176:179], v[0:3]
	s_setprio 0
	s_add_i32 s40, 0, 0x18000
	v_add_u32_e32 v32, s40, v209
	s_barrier
	ds_read_b128 v[132:135], v32
	ds_read_b128 v[140:143], v32 offset:2048
	ds_read_b128 v[136:139], v32 offset:1024
	ds_read_b128 v[144:147], v32 offset:3072
	s_add_u32 s14, s24, 0x40000
	s_addc_u32 s15, s25, 0
	s_mov_b32 m0, s34
	v_lshl_add_u64 v[38:39], s[14:15], 0, v[196:197]
	ds_read_b128 v[148:151], v211 offset:32768
	ds_read_b128 v[156:159], v211 offset:34816
	ds_read_b128 v[164:167], v211 offset:36864
	ds_read_b128 v[172:175], v211 offset:38912
	ds_read_b128 v[152:155], v211 offset:33792
	ds_read_b128 v[160:163], v211 offset:35840
	ds_read_b128 v[168:171], v211 offset:37888
	ds_read_b128 v[176:179], v211 offset:39936
	global_load_lds_dwordx4 v[38:39], off
	v_lshl_add_u64 v[38:39], s[14:15], 0, v[198:199]
	s_mov_b32 m0, s35
	s_nop 0
	global_load_lds_dwordx4 v[38:39], off
	s_waitcnt lgkmcnt(8)
	s_waitcnt vmcnt(10)
	s_barrier
	s_waitcnt lgkmcnt(7)
	s_setprio 1
	v_mfma_f32_16x16x32_f16 v[128:131], v[132:135], v[148:151], v[128:131]
	v_mfma_f32_16x16x32_f16 v[124:127], v[140:143], v[148:151], v[124:127]
	s_waitcnt lgkmcnt(6)
	v_mfma_f32_16x16x32_f16 v[120:123], v[132:135], v[156:159], v[120:123]
	v_mfma_f32_16x16x32_f16 v[116:119], v[140:143], v[156:159], v[116:119]
	s_waitcnt lgkmcnt(5)
	v_mfma_f32_16x16x32_f16 v[112:115], v[132:135], v[164:167], v[112:115]
	v_mfma_f32_16x16x32_f16 v[108:111], v[140:143], v[164:167], v[108:111]
	s_waitcnt lgkmcnt(4)
	v_mfma_f32_16x16x32_f16 v[104:107], v[132:135], v[172:175], v[104:107]
	v_mfma_f32_16x16x32_f16 v[100:103], v[140:143], v[172:175], v[100:103]
	s_waitcnt lgkmcnt(3)
	v_mfma_f32_16x16x32_f16 v[128:131], v[136:139], v[152:155], v[128:131]
	v_mfma_f32_16x16x32_f16 v[124:127], v[144:147], v[152:155], v[124:127]
	s_waitcnt lgkmcnt(2)
	v_mfma_f32_16x16x32_f16 v[120:123], v[136:139], v[160:163], v[120:123]
	v_mfma_f32_16x16x32_f16 v[116:119], v[144:147], v[160:163], v[116:119]
	s_waitcnt lgkmcnt(1)
	v_mfma_f32_16x16x32_f16 v[112:115], v[136:139], v[168:171], v[112:115]
	v_mfma_f32_16x16x32_f16 v[108:111], v[144:147], v[168:171], v[108:111]
	s_waitcnt lgkmcnt(0)
	v_mfma_f32_16x16x32_f16 v[104:107], v[136:139], v[176:179], v[104:107]
	v_mfma_f32_16x16x32_f16 v[100:103], v[144:147], v[176:179], v[100:103]
	s_setprio 0
	s_barrier
	s_add_i32 s24, 0, 0x1c000
	s_add_i32 s14, s40, s29
	v_add_u32_e32 v32, s24, v209
	v_lshl_add_u64 v[38:39], v[204:205], 0, s[84:85]
	s_mov_b32 m0, s14
	ds_read_b128 v[180:183], v32
	ds_read_b128 v[188:191], v32 offset:2048
	ds_read_b128 v[184:187], v32 offset:1024
	ds_read_b128 v[192:195], v32 offset:3072
	global_load_lds_dwordx4 v[38:39], off
	v_lshl_add_u64 v[38:39], v[206:207], 0, s[84:85]
	s_add_i32 m0, s14, 0x2000
	s_nop 0
	global_load_lds_dwordx4 v[38:39], off
	s_waitcnt vmcnt(10)
	s_barrier
	s_waitcnt lgkmcnt(2)
	s_setprio 1
	v_mfma_f32_16x16x32_f16 v[96:99], v[180:183], v[148:151], v[96:99]
	v_mfma_f32_16x16x32_f16 v[92:95], v[188:191], v[148:151], v[92:95]
	v_mfma_f32_16x16x32_f16 v[88:91], v[180:183], v[156:159], v[88:91]
	v_mfma_f32_16x16x32_f16 v[84:87], v[188:191], v[156:159], v[84:87]
	v_mfma_f32_16x16x32_f16 v[80:83], v[180:183], v[164:167], v[80:83]
	v_mfma_f32_16x16x32_f16 v[76:79], v[188:191], v[164:167], v[76:79]
	v_mfma_f32_16x16x32_f16 v[72:75], v[180:183], v[172:175], v[72:75]
	v_mfma_f32_16x16x32_f16 v[68:71], v[188:191], v[172:175], v[68:71]
	s_waitcnt lgkmcnt(0)
	v_mfma_f32_16x16x32_f16 v[96:99], v[184:187], v[152:155], v[96:99]
	v_mfma_f32_16x16x32_f16 v[92:95], v[192:195], v[152:155], v[92:95]
	v_mfma_f32_16x16x32_f16 v[88:91], v[184:187], v[160:163], v[88:91]
	v_mfma_f32_16x16x32_f16 v[84:87], v[192:195], v[160:163], v[84:87]
	v_mfma_f32_16x16x32_f16 v[80:83], v[184:187], v[168:171], v[80:83]
	v_mfma_f32_16x16x32_f16 v[76:79], v[192:195], v[168:171], v[76:79]
	v_mfma_f32_16x16x32_f16 v[72:75], v[184:187], v[176:179], v[72:75]
	v_mfma_f32_16x16x32_f16 v[68:71], v[192:195], v[176:179], v[68:71]
	s_setprio 0
	s_mov_b32 m0, s36
	v_lshl_add_u64 v[38:39], v[212:213], 0, s[84:85]
	s_barrier
	ds_read_b128 v[148:151], v211 offset:49152
	ds_read_b128 v[156:159], v211 offset:51200
	ds_read_b128 v[164:167], v211 offset:53248
	ds_read_b128 v[172:175], v211 offset:55296
	ds_read_b128 v[152:155], v211 offset:50176
	ds_read_b128 v[160:163], v211 offset:52224
	ds_read_b128 v[168:171], v211 offset:54272
	ds_read_b128 v[176:179], v211 offset:56320
	global_load_lds_dwordx4 v[38:39], off
	v_lshl_add_u64 v[38:39], v[214:215], 0, s[84:85]
	s_mov_b32 m0, s37
	s_nop 0
	global_load_lds_dwordx4 v[38:39], off
	s_barrier
	s_waitcnt lgkmcnt(7)
	s_setprio 1
	v_mfma_f32_16x16x32_f16 v[64:67], v[132:135], v[148:151], v[64:67]
	v_mfma_f32_16x16x32_f16 v[60:63], v[140:143], v[148:151], v[60:63]
	s_waitcnt lgkmcnt(6)
	v_mfma_f32_16x16x32_f16 v[56:59], v[132:135], v[156:159], v[56:59]
	v_mfma_f32_16x16x32_f16 v[52:55], v[140:143], v[156:159], v[52:55]
	s_waitcnt lgkmcnt(5)
	v_mfma_f32_16x16x32_f16 v[48:51], v[132:135], v[164:167], v[48:51]
	v_mfma_f32_16x16x32_f16 v[44:47], v[140:143], v[164:167], v[44:47]
	s_waitcnt lgkmcnt(4)
	v_mfma_f32_16x16x32_f16 v[38:41], v[132:135], v[172:175], v[40:43]
	v_mfma_f32_16x16x32_f16 v[34:37], v[140:143], v[172:175], v[34:37]
	s_waitcnt lgkmcnt(3)
	v_mfma_f32_16x16x32_f16 v[64:67], v[136:139], v[152:155], v[64:67]
	v_mfma_f32_16x16x32_f16 v[60:63], v[144:147], v[152:155], v[60:63]
	s_waitcnt lgkmcnt(2)
	v_mfma_f32_16x16x32_f16 v[56:59], v[136:139], v[160:163], v[56:59]
	v_mfma_f32_16x16x32_f16 v[52:55], v[144:147], v[160:163], v[52:55]
	s_waitcnt lgkmcnt(1)
	v_mfma_f32_16x16x32_f16 v[48:51], v[136:139], v[168:171], v[48:51]
	v_mfma_f32_16x16x32_f16 v[44:47], v[144:147], v[168:171], v[44:47]
	s_waitcnt lgkmcnt(0)
	v_mfma_f32_16x16x32_f16 v[40:43], v[136:139], v[176:179], v[38:41]
	v_mfma_f32_16x16x32_f16 v[36:39], v[144:147], v[176:179], v[34:37]
	s_setprio 0
	s_barrier
	s_add_u32 s14, s22, 0x40080
	s_addc_u32 s15, s23, 0
	s_add_i32 s22, s24, s29
	v_lshl_add_u64 v[34:35], s[14:15], 0, v[196:197]
	s_mov_b32 m0, s22
	s_nop 0
	global_load_lds_dwordx4 v[34:35], off
	v_lshl_add_u64 v[34:35], s[14:15], 0, v[198:199]
	s_add_i32 m0, s22, 0x2000
	s_nop 0
	global_load_lds_dwordx4 v[34:35], off
	s_waitcnt vmcnt(6)
	s_barrier
	s_setprio 1
	v_mfma_f32_16x16x32_f16 v[28:31], v[180:183], v[148:151], v[28:31]
	v_mfma_f32_16x16x32_f16 v[24:27], v[188:191], v[148:151], v[24:27]
	v_mfma_f32_16x16x32_f16 v[20:23], v[180:183], v[156:159], v[20:23]
	v_mfma_f32_16x16x32_f16 v[16:19], v[188:191], v[156:159], v[16:19]
	v_mfma_f32_16x16x32_f16 v[12:15], v[180:183], v[164:167], v[12:15]
	v_mfma_f32_16x16x32_f16 v[8:11], v[188:191], v[164:167], v[8:11]
	v_mfma_f32_16x16x32_f16 v[4:7], v[180:183], v[172:175], v[4:7]
	v_mfma_f32_16x16x32_f16 v[0:3], v[188:191], v[172:175], v[0:3]
	v_mfma_f32_16x16x32_f16 v[28:31], v[184:187], v[152:155], v[28:31]
	v_mfma_f32_16x16x32_f16 v[24:27], v[192:195], v[152:155], v[24:27]
	v_mfma_f32_16x16x32_f16 v[20:23], v[184:187], v[160:163], v[20:23]
	v_mfma_f32_16x16x32_f16 v[16:19], v[192:195], v[160:163], v[16:19]
	v_mfma_f32_16x16x32_f16 v[12:15], v[184:187], v[168:171], v[12:15]
	v_mfma_f32_16x16x32_f16 v[8:11], v[192:195], v[168:171], v[8:11]
	v_mfma_f32_16x16x32_f16 v[4:7], v[184:187], v[176:179], v[4:7]
	v_mfma_f32_16x16x32_f16 v[0:3], v[192:195], v[176:179], v[0:3]
	s_setprio 0
	s_add_i32 s11, s11, 2
	s_add_u32 s1, s1, 0x100
	s_addc_u32 s3, s3, 0
	s_cmp_gt_u32 s11, 13
	s_mov_b64 s[14:15], s[20:21]
	s_barrier
	s_cbranch_scc0 .LBB0_940
	v_lshl_add_u32 v34, s12, 8, v208
	v_lshl_or_b32 v156, s10, 8, v210
	s_cmp_lg_u32 s13, 0
	s_cselect_b64 s[10:11], -1, 0
	s_cmp_eq_u32 s13, 0
	v_ashrrev_i32_e32 v157, 31, v156
	v_ashrrev_i32_e32 v35, 31, v34
	v_mad_i64_i32 v[158:159], s[12:13], v34, s33, 0
	v_or_b32_e32 v160, 16, v34
	v_or_b32_e32 v162, 32, v34
	v_or_b32_e32 v164, 48, v34
	s_cbranch_scc1 .LBB0_946
	v_lshl_add_u64 v[132:133], s[70:71], 0, v[158:159]
	v_lshlrev_b64 v[166:167], 1, v[156:157]
	v_lshl_add_u64 v[132:133], v[132:133], 0, v[166:167]
	s_mov_b64 s[16:17], 0x2800
	v_mov_b64_e32 v[168:169], s[70:71]
	s_movk_i32 s1, 0x2000
	v_lshl_add_u64 v[134:135], v[132:133], 0, s[16:17]
	v_mad_i64_i32 v[136:137], s[12:13], v160, s33, v[168:169]
	v_add_co_u32_e32 v132, vcc, s1, v132
	v_lshl_add_u64 v[136:137], v[136:137], 0, v[166:167]
	s_nop 0
	v_addc_co_u32_e32 v133, vcc, 0, v133, vcc
	v_lshl_add_u64 v[138:139], v[136:137], 0, s[16:17]
	v_mad_i64_i32 v[140:141], s[12:13], v162, s33, v[168:169]
	v_add_co_u32_e32 v136, vcc, s1, v136
	v_lshl_add_u64 v[140:141], v[140:141], 0, v[166:167]
	s_nop 0
	v_addc_co_u32_e32 v137, vcc, 0, v137, vcc
	v_mad_i64_i32 v[144:145], s[12:13], v164, s33, v[168:169]
	global_load_dwordx4 v[170:173], v[132:133], off offset:2048
	global_load_dwordx4 v[152:155], v[136:137], off offset:2048
	global_load_dwordx4 v[174:177], v[134:135], off offset:256
	global_load_dwordx4 v[148:151], v[138:139], off offset:256
	v_add_co_u32_e32 v132, vcc, s1, v140
	v_lshl_add_u64 v[144:145], v[144:145], 0, v[166:167]
	s_nop 0
	v_addc_co_u32_e32 v133, vcc, 0, v141, vcc
	v_add_co_u32_e32 v134, vcc, s1, v144
	v_lshl_add_u64 v[142:143], v[140:141], 0, s[16:17]
	s_nop 0
	v_addc_co_u32_e32 v135, vcc, 0, v145, vcc
	v_lshl_add_u64 v[178:179], v[144:145], 0, s[16:17]
	global_load_dwordx4 v[144:147], v[132:133], off offset:2048
	global_load_dwordx4 v[136:139], v[134:135], off offset:2048
	s_nop 0
	global_load_dwordx4 v[140:143], v[142:143], off offset:256
	s_nop 0
	global_load_dwordx4 v[132:135], v[178:179], off offset:256
	v_ashrrev_i32_e32 v161, 31, v160
	v_ashrrev_i32_e32 v163, 31, v162
	v_ashrrev_i32_e32 v165, 31, v164
	s_waitcnt vmcnt(0)
	v_cvt_f32_f16_e32 v32, v170
	v_cvt_f32_f16_sdwa v170, v170 dst_sel:DWORD dst_unused:UNUSED_PAD src0_sel:WORD_1
	v_lshlrev_b64 v[178:179], 11, v[34:35]
	v_readlane_b32 s14, v252, 9
	v_max_f32_e32 v32, 0xc1f00000, v32
	v_max_f32_e32 v35, 0xc1f00000, v170
	v_cvt_f32_f16_e32 v170, v171
	v_cvt_f32_f16_sdwa v171, v171 dst_sel:DWORD dst_unused:UNUSED_PAD src0_sel:WORD_1
	v_mul_f32_e32 v35, 0xbfb8aa3b, v35
	v_exp_f32_e32 v35, v35
	v_max_f32_e32 v170, 0xc1f00000, v170
	v_mul_f32_e32 v170, 0xbfb8aa3b, v170
	v_exp_f32_e32 v180, v170
	v_max_f32_e32 v170, 0xc1f00000, v171
	v_mul_f32_e32 v170, 0xbfb8aa3b, v170
	v_cvt_f32_f16_e32 v171, v172
	v_exp_f32_e32 v181, v170
	v_cvt_f32_f16_sdwa v170, v172 dst_sel:DWORD dst_unused:UNUSED_PAD src0_sel:WORD_1
	v_mul_f32_e32 v32, 0xbfb8aa3b, v32
	v_max_f32_e32 v171, 0xc1f00000, v171
	v_mul_f32_e32 v171, 0xbfb8aa3b, v171
	v_max_f32_e32 v170, 0xc1f00000, v170
	v_mul_f32_e32 v170, 0xbfb8aa3b, v170
	v_exp_f32_e32 v182, v171
	v_cvt_f32_f16_e32 v171, v173
	v_exp_f32_e32 v183, v170
	v_cvt_f32_f16_sdwa v170, v173 dst_sel:DWORD dst_unused:UNUSED_PAD src0_sel:WORD_1
	v_exp_f32_e32 v32, v32
	v_max_f32_e32 v171, 0xc1f00000, v171
	v_mul_f32_e32 v171, 0xbfb8aa3b, v171
	v_max_f32_e32 v170, 0xc1f00000, v170
	v_mul_f32_e32 v170, 0xbfb8aa3b, v170
	v_add_f32_e32 v35, 1.0, v35
	v_exp_f32_e32 v184, v171
	v_exp_f32_e32 v185, v170
	v_rcp_f32_e32 v170, v35
	v_add_f32_e32 v35, 1.0, v180
	v_rcp_f32_e32 v171, v35
	v_add_f32_e32 v35, 1.0, v181
	v_add_f32_e32 v32, 1.0, v32
	v_rcp_f32_e32 v172, v35
	v_add_f32_e32 v35, 1.0, v182
	v_rcp_f32_e32 v32, v32
	v_rcp_f32_e32 v173, v35
	v_add_f32_e32 v35, 1.0, v183
	v_rcp_f32_e32 v180, v35
	v_add_f32_e32 v35, 1.0, v184
	v_rcp_f32_e32 v181, v35
	v_mov_b32_e32 v182, v129
	v_mov_b32_e32 v183, v130
	v_pk_mul_f32 v[170:171], v[182:183], v[170:171]
	v_pk_mov_b32 v[182:183], v[130:131], v[124:125] op_sel:[1,0]
	v_add_f32_e32 v35, 1.0, v185
	v_fma_mixlo_f16 v32, v128, v32, 0
	v_cvt_pk_f16_f32 v171, v170, v171
	v_pk_mul_f32 v[172:173], v[182:183], v[172:173]
	v_rcp_f32_e32 v35, v35
	v_pack_b32_f16 v170, v32, v171
	v_cvt_pk_f16_f32 v32, v172, v173
	v_mov_b32_e32 v172, v125
	v_mov_b32_e32 v173, v126
	v_pk_mul_f32 v[172:173], v[172:173], v[180:181]
	v_readlane_b32 s15, v252, 10
	v_cvt_pk_f16_f32 v173, v172, v173
	v_alignbit_b32 v172, v173, v32, 16
	v_lshrrev_b32_e32 v173, 16, v173
	v_lshl_add_u64 v[178:179], s[14:15], 0, v[178:179]
	v_alignbit_b32 v171, v32, v171, 16
	v_fma_mixhi_f16 v173, v127, v35, 0
	v_lshl_add_u64 v[178:179], v[178:179], 0, v[166:167]
	global_store_dwordx4 v[178:179], v[170:173], off
	v_cvt_f32_f16_sdwa v35, v174 dst_sel:DWORD dst_unused:UNUSED_PAD src0_sel:WORD_1
	v_cvt_f32_f16_e32 v32, v174
	v_cvt_f32_f16_e32 v170, v175
	v_cvt_f32_f16_sdwa v171, v175 dst_sel:DWORD dst_unused:UNUSED_PAD src0_sel:WORD_1
	v_max_f32_e32 v35, 0xc1f00000, v35
	v_mul_f32_e32 v35, 0xbfb8aa3b, v35
	v_max_f32_e32 v170, 0xc1f00000, v170
	v_mul_f32_e32 v170, 0xbfb8aa3b, v170
	v_exp_f32_e32 v172, v170
	v_max_f32_e32 v170, 0xc1f00000, v171
	v_mul_f32_e32 v170, 0xbfb8aa3b, v170
	v_cvt_f32_f16_e32 v171, v176
	v_exp_f32_e32 v173, v170
	v_cvt_f32_f16_sdwa v170, v176 dst_sel:DWORD dst_unused:UNUSED_PAD src0_sel:WORD_1
	v_exp_f32_e32 v35, v35
	v_max_f32_e32 v171, 0xc1f00000, v171
	v_mul_f32_e32 v171, 0xbfb8aa3b, v171
	v_max_f32_e32 v170, 0xc1f00000, v170
	v_mul_f32_e32 v170, 0xbfb8aa3b, v170
	v_exp_f32_e32 v174, v171
	v_cvt_f32_f16_e32 v171, v177
	v_exp_f32_e32 v175, v170
	v_cvt_f32_f16_sdwa v170, v177 dst_sel:DWORD dst_unused:UNUSED_PAD src0_sel:WORD_1
	v_max_f32_e32 v32, 0xc1f00000, v32
	v_mul_f32_e32 v32, 0xbfb8aa3b, v32
	v_exp_f32_e32 v32, v32
	v_max_f32_e32 v171, 0xc1f00000, v171
	v_max_f32_e32 v170, 0xc1f00000, v170
	v_mul_f32_e32 v171, 0xbfb8aa3b, v171
	v_mul_f32_e32 v170, 0xbfb8aa3b, v170
	v_add_f32_e32 v35, 1.0, v35
	v_exp_f32_e32 v176, v171
	v_exp_f32_e32 v177, v170
	v_rcp_f32_e32 v170, v35
	v_add_f32_e32 v35, 1.0, v172
	v_rcp_f32_e32 v171, v35
	v_add_f32_e32 v35, 1.0, v173
	v_add_f32_e32 v32, 1.0, v32
	v_rcp_f32_e32 v172, v35
	v_add_f32_e32 v35, 1.0, v174
	v_rcp_f32_e32 v32, v32
	v_rcp_f32_e32 v173, v35
	v_add_f32_e32 v35, 1.0, v175
	v_rcp_f32_e32 v174, v35
	v_add_f32_e32 v35, 1.0, v176
	v_rcp_f32_e32 v175, v35
	v_add_f32_e32 v35, 1.0, v177
	v_mov_b32_e32 v176, v97
	v_mov_b32_e32 v177, v98
	v_pk_mul_f32 v[170:171], v[176:177], v[170:171]
	v_pk_mov_b32 v[176:177], v[98:99], v[92:93] op_sel:[1,0]
	v_fma_mixlo_f16 v32, v96, v32, 0
	v_cvt_pk_f16_f32 v171, v170, v171
	v_pk_mul_f32 v[172:173], v[176:177], v[172:173]
	v_rcp_f32_e32 v35, v35
	v_pack_b32_f16 v170, v32, v171
	v_cvt_pk_f16_f32 v32, v172, v173
	v_mov_b32_e32 v172, v93
	v_mov_b32_e32 v173, v94
	v_pk_mul_f32 v[172:173], v[172:173], v[174:175]
	v_alignbit_b32 v171, v32, v171, 16
	v_cvt_pk_f16_f32 v173, v172, v173
	v_alignbit_b32 v172, v173, v32, 16
	v_lshrrev_b32_e32 v173, 16, v173
	v_fma_mixhi_f16 v173, v95, v35, 0
	v_cvt_f32_f16_e32 v32, v152
	v_cvt_f32_f16_sdwa v35, v152 dst_sel:DWORD dst_unused:UNUSED_PAD src0_sel:WORD_1
	v_cvt_f32_f16_e32 v152, v153
	v_cvt_f32_f16_sdwa v153, v153 dst_sel:DWORD dst_unused:UNUSED_PAD src0_sel:WORD_1
	global_store_dwordx4 v[178:179], v[170:173], off offset:256
	v_max_f32_e32 v35, 0xc1f00000, v35
	v_max_f32_e32 v152, 0xc1f00000, v152
	v_mul_f32_e32 v152, 0xbfb8aa3b, v152
	v_lshlrev_b64 v[170:171], 11, v[160:161]
	v_exp_f32_e32 v161, v152
	v_max_f32_e32 v152, 0xc1f00000, v153
	v_mul_f32_e32 v152, 0xbfb8aa3b, v152
	v_cvt_f32_f16_e32 v153, v154
	v_exp_f32_e32 v172, v152
	v_cvt_f32_f16_sdwa v152, v154 dst_sel:DWORD dst_unused:UNUSED_PAD src0_sel:WORD_1
	v_mul_f32_e32 v35, 0xbfb8aa3b, v35
	v_max_f32_e32 v153, 0xc1f00000, v153
	v_mul_f32_e32 v153, 0xbfb8aa3b, v153
	v_max_f32_e32 v152, 0xc1f00000, v152
	v_mul_f32_e32 v152, 0xbfb8aa3b, v152
	v_exp_f32_e32 v173, v153
	v_cvt_f32_f16_e32 v153, v155
	v_exp_f32_e32 v174, v152
	v_cvt_f32_f16_sdwa v152, v155 dst_sel:DWORD dst_unused:UNUSED_PAD src0_sel:WORD_1
	v_exp_f32_e32 v35, v35
	v_max_f32_e32 v32, 0xc1f00000, v32
	v_mul_f32_e32 v32, 0xbfb8aa3b, v32
	v_exp_f32_e32 v32, v32
	v_max_f32_e32 v153, 0xc1f00000, v153
	v_max_f32_e32 v152, 0xc1f00000, v152
	v_mul_f32_e32 v153, 0xbfb8aa3b, v153
	v_mul_f32_e32 v152, 0xbfb8aa3b, v152
	v_add_f32_e32 v35, 1.0, v35
	v_exp_f32_e32 v175, v153
	v_exp_f32_e32 v176, v152
	v_rcp_f32_e32 v152, v35
	v_add_f32_e32 v35, 1.0, v161
	v_rcp_f32_e32 v153, v35
	v_add_f32_e32 v35, 1.0, v172
	v_add_f32_e32 v32, 1.0, v32
	v_rcp_f32_e32 v154, v35
	v_add_f32_e32 v35, 1.0, v173
	v_rcp_f32_e32 v32, v32
	v_rcp_f32_e32 v155, v35
	v_add_f32_e32 v35, 1.0, v174
	v_rcp_f32_e32 v172, v35
	v_add_f32_e32 v35, 1.0, v175
	v_rcp_f32_e32 v173, v35
	v_mov_b32_e32 v174, v121
	v_mov_b32_e32 v175, v122
	v_pk_mul_f32 v[152:153], v[174:175], v[152:153]
	v_pk_mov_b32 v[174:175], v[122:123], v[116:117] op_sel:[1,0]
	v_add_f32_e32 v35, 1.0, v176
	v_fma_mixlo_f16 v32, v120, v32, 0
	v_cvt_pk_f16_f32 v153, v152, v153
	v_pk_mul_f32 v[154:155], v[174:175], v[154:155]
	v_rcp_f32_e32 v35, v35
	v_pack_b32_f16 v152, v32, v153
	v_cvt_pk_f16_f32 v32, v154, v155
	v_mov_b32_e32 v154, v117
	v_mov_b32_e32 v155, v118
	v_pk_mul_f32 v[154:155], v[154:155], v[172:173]
	v_alignbit_b32 v153, v32, v153, 16
	v_cvt_pk_f16_f32 v155, v154, v155
	v_alignbit_b32 v154, v155, v32, 16
	v_lshrrev_b32_e32 v155, 16, v155
	v_fma_mixhi_f16 v155, v119, v35, 0
	v_cvt_f32_f16_e32 v32, v148
	v_cvt_f32_f16_sdwa v35, v148 dst_sel:DWORD dst_unused:UNUSED_PAD src0_sel:WORD_1
	v_cvt_f32_f16_e32 v148, v149
	v_cvt_f32_f16_sdwa v149, v149 dst_sel:DWORD dst_unused:UNUSED_PAD src0_sel:WORD_1
	v_lshl_add_u64 v[170:171], s[14:15], 0, v[170:171]
	v_lshl_add_u64 v[170:171], v[170:171], 0, v[166:167]
	v_max_f32_e32 v148, 0xc1f00000, v148
	v_mul_f32_e32 v148, 0xbfb8aa3b, v148
	global_store_dwordx4 v[170:171], v[152:155], off
	v_max_f32_e32 v35, 0xc1f00000, v35
	v_mul_f32_e32 v35, 0xbfb8aa3b, v35
	v_exp_f32_e32 v152, v148
	v_max_f32_e32 v148, 0xc1f00000, v149
	v_mul_f32_e32 v148, 0xbfb8aa3b, v148
	v_cvt_f32_f16_e32 v149, v150
	v_exp_f32_e32 v153, v148
	v_cvt_f32_f16_sdwa v148, v150 dst_sel:DWORD dst_unused:UNUSED_PAD src0_sel:WORD_1
	v_exp_f32_e32 v35, v35
	v_max_f32_e32 v149, 0xc1f00000, v149
	v_mul_f32_e32 v149, 0xbfb8aa3b, v149
	v_max_f32_e32 v148, 0xc1f00000, v148
	v_mul_f32_e32 v148, 0xbfb8aa3b, v148
	v_exp_f32_e32 v154, v149
	v_cvt_f32_f16_e32 v149, v151
	v_exp_f32_e32 v155, v148
	v_cvt_f32_f16_sdwa v148, v151 dst_sel:DWORD dst_unused:UNUSED_PAD src0_sel:WORD_1
	v_max_f32_e32 v32, 0xc1f00000, v32
	v_mul_f32_e32 v32, 0xbfb8aa3b, v32
	v_exp_f32_e32 v32, v32
	v_max_f32_e32 v149, 0xc1f00000, v149
	v_max_f32_e32 v148, 0xc1f00000, v148
	v_mul_f32_e32 v149, 0xbfb8aa3b, v149
	v_mul_f32_e32 v148, 0xbfb8aa3b, v148
	v_add_f32_e32 v35, 1.0, v35
	v_exp_f32_e32 v161, v149
	v_exp_f32_e32 v172, v148
	v_rcp_f32_e32 v148, v35
	v_add_f32_e32 v35, 1.0, v152
	v_rcp_f32_e32 v149, v35
	v_add_f32_e32 v35, 1.0, v153
	v_add_f32_e32 v32, 1.0, v32
	v_rcp_f32_e32 v150, v35
	v_add_f32_e32 v35, 1.0, v154
	v_rcp_f32_e32 v32, v32
	v_rcp_f32_e32 v151, v35
	v_add_f32_e32 v35, 1.0, v155
	v_rcp_f32_e32 v152, v35
	v_add_f32_e32 v35, 1.0, v161
	v_rcp_f32_e32 v153, v35
	v_mov_b32_e32 v154, v89
	v_mov_b32_e32 v155, v90
	v_pk_mul_f32 v[148:149], v[154:155], v[148:149]
	v_pk_mov_b32 v[154:155], v[90:91], v[84:85] op_sel:[1,0]
	v_add_f32_e32 v35, 1.0, v172
	v_fma_mixlo_f16 v32, v88, v32, 0
	v_cvt_pk_f16_f32 v149, v148, v149
	v_pk_mul_f32 v[150:151], v[154:155], v[150:151]
	v_rcp_f32_e32 v35, v35
	v_pack_b32_f16 v148, v32, v149
	v_cvt_pk_f16_f32 v32, v150, v151
	v_mov_b32_e32 v150, v85
	v_mov_b32_e32 v151, v86
	v_pk_mul_f32 v[150:151], v[150:151], v[152:153]
	v_alignbit_b32 v149, v32, v149, 16
	v_cvt_pk_f16_f32 v151, v150, v151
	v_alignbit_b32 v150, v151, v32, 16
	v_lshrrev_b32_e32 v151, 16, v151
	v_fma_mixhi_f16 v151, v87, v35, 0
	v_cvt_f32_f16_e32 v32, v144
	v_cvt_f32_f16_sdwa v35, v144 dst_sel:DWORD dst_unused:UNUSED_PAD src0_sel:WORD_1
	v_cvt_f32_f16_e32 v144, v145
	v_cvt_f32_f16_sdwa v145, v145 dst_sel:DWORD dst_unused:UNUSED_PAD src0_sel:WORD_1
	global_store_dwordx4 v[170:171], v[148:151], off offset:256
	v_max_f32_e32 v35, 0xc1f00000, v35
	v_max_f32_e32 v144, 0xc1f00000, v144
	v_mul_f32_e32 v144, 0xbfb8aa3b, v144
	v_exp_f32_e32 v150, v144
	v_max_f32_e32 v144, 0xc1f00000, v145
	v_mul_f32_e32 v144, 0xbfb8aa3b, v144
	v_cvt_f32_f16_e32 v145, v146
	v_exp_f32_e32 v151, v144
	v_cvt_f32_f16_sdwa v144, v146 dst_sel:DWORD dst_unused:UNUSED_PAD src0_sel:WORD_1
	v_mul_f32_e32 v35, 0xbfb8aa3b, v35
	v_max_f32_e32 v145, 0xc1f00000, v145
	v_mul_f32_e32 v145, 0xbfb8aa3b, v145
	v_max_f32_e32 v144, 0xc1f00000, v144
	v_mul_f32_e32 v144, 0xbfb8aa3b, v144
	v_exp_f32_e32 v152, v145
	v_cvt_f32_f16_e32 v145, v147
	v_exp_f32_e32 v153, v144
	v_cvt_f32_f16_sdwa v144, v147 dst_sel:DWORD dst_unused:UNUSED_PAD src0_sel:WORD_1
	v_exp_f32_e32 v35, v35
	v_max_f32_e32 v32, 0xc1f00000, v32
	v_mul_f32_e32 v32, 0xbfb8aa3b, v32
	v_exp_f32_e32 v32, v32
	v_max_f32_e32 v145, 0xc1f00000, v145
	v_max_f32_e32 v144, 0xc1f00000, v144
	v_mul_f32_e32 v145, 0xbfb8aa3b, v145
	v_mul_f32_e32 v144, 0xbfb8aa3b, v144
	v_add_f32_e32 v35, 1.0, v35
	v_exp_f32_e32 v154, v145
	v_exp_f32_e32 v155, v144
	v_rcp_f32_e32 v144, v35
	v_add_f32_e32 v35, 1.0, v150
	v_rcp_f32_e32 v145, v35
	v_add_f32_e32 v35, 1.0, v151
	v_add_f32_e32 v32, 1.0, v32
	v_rcp_f32_e32 v146, v35
	v_add_f32_e32 v35, 1.0, v152
	v_rcp_f32_e32 v32, v32
	v_rcp_f32_e32 v147, v35
	v_add_f32_e32 v35, 1.0, v153
	v_rcp_f32_e32 v150, v35
	v_add_f32_e32 v35, 1.0, v154
	v_rcp_f32_e32 v151, v35
	v_mov_b32_e32 v152, v113
	v_mov_b32_e32 v153, v114
	v_pk_mul_f32 v[144:145], v[152:153], v[144:145]
	v_pk_mov_b32 v[152:153], v[114:115], v[108:109] op_sel:[1,0]
	v_add_f32_e32 v35, 1.0, v155
	v_fma_mixlo_f16 v32, v112, v32, 0
	v_cvt_pk_f16_f32 v145, v144, v145
	v_pk_mul_f32 v[146:147], v[152:153], v[146:147]
	v_rcp_f32_e32 v35, v35
	v_pack_b32_f16 v144, v32, v145
	v_cvt_pk_f16_f32 v32, v146, v147
	v_mov_b32_e32 v146, v109
	v_mov_b32_e32 v147, v110
	v_pk_mul_f32 v[146:147], v[146:147], v[150:151]
	v_alignbit_b32 v145, v32, v145, 16
	v_cvt_pk_f16_f32 v147, v146, v147
	v_alignbit_b32 v146, v147, v32, 16
	v_lshrrev_b32_e32 v147, 16, v147
	v_fma_mixhi_f16 v147, v111, v35, 0
	v_cvt_f32_f16_e32 v32, v140
	v_cvt_f32_f16_sdwa v35, v140 dst_sel:DWORD dst_unused:UNUSED_PAD src0_sel:WORD_1
	v_cvt_f32_f16_e32 v140, v141
	v_cvt_f32_f16_sdwa v141, v141 dst_sel:DWORD dst_unused:UNUSED_PAD src0_sel:WORD_1
	v_lshlrev_b64 v[148:149], 11, v[162:163]
	v_lshl_add_u64 v[148:149], s[14:15], 0, v[148:149]
	v_max_f32_e32 v140, 0xc1f00000, v140
	v_lshl_add_u64 v[148:149], v[148:149], 0, v[166:167]
	v_mul_f32_e32 v140, 0xbfb8aa3b, v140
	global_store_dwordx4 v[148:149], v[144:147], off
	v_max_f32_e32 v35, 0xc1f00000, v35
	v_mul_f32_e32 v35, 0xbfb8aa3b, v35
	v_exp_f32_e32 v144, v140
	v_max_f32_e32 v140, 0xc1f00000, v141
	v_mul_f32_e32 v140, 0xbfb8aa3b, v140
	v_cvt_f32_f16_e32 v141, v142
	v_exp_f32_e32 v145, v140
	v_cvt_f32_f16_sdwa v140, v142 dst_sel:DWORD dst_unused:UNUSED_PAD src0_sel:WORD_1
	v_exp_f32_e32 v35, v35
	v_max_f32_e32 v141, 0xc1f00000, v141
	v_mul_f32_e32 v141, 0xbfb8aa3b, v141
	v_max_f32_e32 v140, 0xc1f00000, v140
	v_mul_f32_e32 v140, 0xbfb8aa3b, v140
	v_exp_f32_e32 v146, v141
	v_cvt_f32_f16_e32 v141, v143
	v_exp_f32_e32 v147, v140
	v_cvt_f32_f16_sdwa v140, v143 dst_sel:DWORD dst_unused:UNUSED_PAD src0_sel:WORD_1
	v_max_f32_e32 v32, 0xc1f00000, v32
	v_mul_f32_e32 v32, 0xbfb8aa3b, v32
	v_exp_f32_e32 v32, v32
	v_max_f32_e32 v141, 0xc1f00000, v141
	v_max_f32_e32 v140, 0xc1f00000, v140
	v_mul_f32_e32 v141, 0xbfb8aa3b, v141
	v_mul_f32_e32 v140, 0xbfb8aa3b, v140
	v_add_f32_e32 v35, 1.0, v35
	v_exp_f32_e32 v150, v141
	v_exp_f32_e32 v151, v140
	v_rcp_f32_e32 v140, v35
	v_add_f32_e32 v35, 1.0, v144
	v_rcp_f32_e32 v141, v35
	v_add_f32_e32 v35, 1.0, v145
	v_add_f32_e32 v32, 1.0, v32
	v_rcp_f32_e32 v142, v35
	v_add_f32_e32 v35, 1.0, v146
	v_rcp_f32_e32 v32, v32
	v_rcp_f32_e32 v143, v35
	v_add_f32_e32 v35, 1.0, v147
	v_rcp_f32_e32 v144, v35
	v_add_f32_e32 v35, 1.0, v150
	v_rcp_f32_e32 v145, v35
	v_mov_b32_e32 v146, v81
	v_mov_b32_e32 v147, v82
	v_pk_mul_f32 v[140:141], v[146:147], v[140:141]
	v_pk_mov_b32 v[146:147], v[82:83], v[76:77] op_sel:[1,0]
	v_add_f32_e32 v35, 1.0, v151
	v_fma_mixlo_f16 v32, v80, v32, 0
	v_cvt_pk_f16_f32 v141, v140, v141
	v_pk_mul_f32 v[142:143], v[146:147], v[142:143]
	v_rcp_f32_e32 v35, v35
	v_pack_b32_f16 v140, v32, v141
	v_cvt_pk_f16_f32 v32, v142, v143
	v_mov_b32_e32 v142, v77
	v_mov_b32_e32 v143, v78
	v_pk_mul_f32 v[142:143], v[142:143], v[144:145]
	v_alignbit_b32 v141, v32, v141, 16
	v_cvt_pk_f16_f32 v143, v142, v143
	v_alignbit_b32 v142, v143, v32, 16
	v_lshrrev_b32_e32 v143, 16, v143
	v_fma_mixhi_f16 v143, v79, v35, 0
	v_cvt_f32_f16_e32 v32, v136
	v_cvt_f32_f16_sdwa v35, v136 dst_sel:DWORD dst_unused:UNUSED_PAD src0_sel:WORD_1
	v_cvt_f32_f16_e32 v136, v137
	v_cvt_f32_f16_sdwa v137, v137 dst_sel:DWORD dst_unused:UNUSED_PAD src0_sel:WORD_1
	global_store_dwordx4 v[148:149], v[140:143], off offset:256
	v_max_f32_e32 v35, 0xc1f00000, v35
	v_max_f32_e32 v136, 0xc1f00000, v136
	v_mul_f32_e32 v136, 0xbfb8aa3b, v136
	v_exp_f32_e32 v142, v136
	v_max_f32_e32 v136, 0xc1f00000, v137
	v_mul_f32_e32 v136, 0xbfb8aa3b, v136
	v_cvt_f32_f16_e32 v137, v138
	v_exp_f32_e32 v143, v136
	v_cvt_f32_f16_sdwa v136, v138 dst_sel:DWORD dst_unused:UNUSED_PAD src0_sel:WORD_1
	v_mul_f32_e32 v35, 0xbfb8aa3b, v35
	v_max_f32_e32 v137, 0xc1f00000, v137
	v_mul_f32_e32 v137, 0xbfb8aa3b, v137
	v_max_f32_e32 v136, 0xc1f00000, v136
	v_mul_f32_e32 v136, 0xbfb8aa3b, v136
	v_exp_f32_e32 v144, v137
	v_cvt_f32_f16_e32 v137, v139
	v_exp_f32_e32 v145, v136
	v_cvt_f32_f16_sdwa v136, v139 dst_sel:DWORD dst_unused:UNUSED_PAD src0_sel:WORD_1
	v_exp_f32_e32 v35, v35
	v_max_f32_e32 v32, 0xc1f00000, v32
	v_mul_f32_e32 v32, 0xbfb8aa3b, v32
	v_exp_f32_e32 v32, v32
	v_max_f32_e32 v137, 0xc1f00000, v137
	v_max_f32_e32 v136, 0xc1f00000, v136
	v_mul_f32_e32 v137, 0xbfb8aa3b, v137
	v_mul_f32_e32 v136, 0xbfb8aa3b, v136
	v_add_f32_e32 v35, 1.0, v35
	v_exp_f32_e32 v146, v137
	v_exp_f32_e32 v147, v136
	v_rcp_f32_e32 v136, v35
	v_add_f32_e32 v35, 1.0, v142
	v_rcp_f32_e32 v137, v35
	v_add_f32_e32 v35, 1.0, v143
	v_add_f32_e32 v32, 1.0, v32
	v_rcp_f32_e32 v138, v35
	v_add_f32_e32 v35, 1.0, v144
	v_rcp_f32_e32 v32, v32
	v_rcp_f32_e32 v139, v35
	v_add_f32_e32 v35, 1.0, v145
	v_rcp_f32_e32 v142, v35
	v_add_f32_e32 v35, 1.0, v146
	v_rcp_f32_e32 v143, v35
	v_mov_b32_e32 v144, v105
	v_mov_b32_e32 v145, v106
	v_pk_mul_f32 v[136:137], v[144:145], v[136:137]
	v_pk_mov_b32 v[144:145], v[106:107], v[100:101] op_sel:[1,0]
	v_add_f32_e32 v35, 1.0, v147
	v_fma_mixlo_f16 v32, v104, v32, 0
	v_cvt_pk_f16_f32 v137, v136, v137
	v_pk_mul_f32 v[138:139], v[144:145], v[138:139]
	v_rcp_f32_e32 v35, v35
	v_pack_b32_f16 v136, v32, v137
	v_cvt_pk_f16_f32 v32, v138, v139
	v_mov_b32_e32 v138, v101
	v_mov_b32_e32 v139, v102
	v_pk_mul_f32 v[138:139], v[138:139], v[142:143]
	v_alignbit_b32 v137, v32, v137, 16
	v_cvt_pk_f16_f32 v139, v138, v139
	v_alignbit_b32 v138, v139, v32, 16
	v_lshrrev_b32_e32 v139, 16, v139
	v_fma_mixhi_f16 v139, v103, v35, 0
	v_cvt_f32_f16_e32 v32, v132
	v_cvt_f32_f16_sdwa v35, v132 dst_sel:DWORD dst_unused:UNUSED_PAD src0_sel:WORD_1
	v_cvt_f32_f16_e32 v132, v133
	v_cvt_f32_f16_sdwa v133, v133 dst_sel:DWORD dst_unused:UNUSED_PAD src0_sel:WORD_1
	v_lshlrev_b64 v[140:141], 11, v[164:165]
	v_lshl_add_u64 v[140:141], s[14:15], 0, v[140:141]
	v_max_f32_e32 v132, 0xc1f00000, v132
	v_lshl_add_u64 v[140:141], v[140:141], 0, v[166:167]
	v_mul_f32_e32 v132, 0xbfb8aa3b, v132
	global_store_dwordx4 v[140:141], v[136:139], off
	v_max_f32_e32 v35, 0xc1f00000, v35
	v_mul_f32_e32 v35, 0xbfb8aa3b, v35
	v_exp_f32_e32 v136, v132
	v_max_f32_e32 v132, 0xc1f00000, v133
	v_mul_f32_e32 v132, 0xbfb8aa3b, v132
	v_cvt_f32_f16_e32 v133, v134
	v_exp_f32_e32 v137, v132
	v_cvt_f32_f16_sdwa v132, v134 dst_sel:DWORD dst_unused:UNUSED_PAD src0_sel:WORD_1
	v_exp_f32_e32 v35, v35
	v_max_f32_e32 v133, 0xc1f00000, v133
	v_mul_f32_e32 v133, 0xbfb8aa3b, v133
	v_max_f32_e32 v132, 0xc1f00000, v132
	v_mul_f32_e32 v132, 0xbfb8aa3b, v132
	v_exp_f32_e32 v138, v133
	v_cvt_f32_f16_e32 v133, v135
	v_exp_f32_e32 v139, v132
	v_cvt_f32_f16_sdwa v132, v135 dst_sel:DWORD dst_unused:UNUSED_PAD src0_sel:WORD_1
	v_max_f32_e32 v32, 0xc1f00000, v32
	v_mul_f32_e32 v32, 0xbfb8aa3b, v32
	v_exp_f32_e32 v32, v32
	v_max_f32_e32 v133, 0xc1f00000, v133
	v_max_f32_e32 v132, 0xc1f00000, v132
	v_mul_f32_e32 v133, 0xbfb8aa3b, v133
	v_mul_f32_e32 v132, 0xbfb8aa3b, v132
	v_add_f32_e32 v35, 1.0, v35
	v_exp_f32_e32 v142, v133
	v_exp_f32_e32 v143, v132
	v_rcp_f32_e32 v132, v35
	v_add_f32_e32 v35, 1.0, v136
	v_rcp_f32_e32 v133, v35
	v_add_f32_e32 v35, 1.0, v137
	v_add_f32_e32 v32, 1.0, v32
	v_rcp_f32_e32 v134, v35
	v_add_f32_e32 v35, 1.0, v138
	v_rcp_f32_e32 v32, v32
	v_rcp_f32_e32 v135, v35
	v_add_f32_e32 v35, 1.0, v139
	v_rcp_f32_e32 v136, v35
	v_add_f32_e32 v35, 1.0, v142
	v_rcp_f32_e32 v137, v35
	v_mov_b32_e32 v138, v73
	v_mov_b32_e32 v139, v74
	v_pk_mul_f32 v[132:133], v[138:139], v[132:133]
	v_pk_mov_b32 v[138:139], v[74:75], v[68:69] op_sel:[1,0]
	v_add_f32_e32 v35, 1.0, v143
	v_fma_mixlo_f16 v32, v72, v32, 0
	v_cvt_pk_f16_f32 v133, v132, v133
	v_pk_mul_f32 v[134:135], v[138:139], v[134:135]
	v_rcp_f32_e32 v35, v35
	v_pack_b32_f16 v132, v32, v133
	v_cvt_pk_f16_f32 v32, v134, v135
	v_mov_b32_e32 v134, v69
	v_mov_b32_e32 v135, v70
	v_pk_mul_f32 v[134:135], v[134:135], v[136:137]
	v_alignbit_b32 v133, v32, v133, 16
	v_cvt_pk_f16_f32 v135, v134, v135
	v_alignbit_b32 v134, v135, v32, 16
	v_lshrrev_b32_e32 v135, 16, v135
	v_fma_mixhi_f16 v135, v71, v35, 0
	global_store_dwordx4 v[140:141], v[132:135], off offset:256
	v_add_u32_e32 v184, 0x80, v34
	s_nop 0
	v_mad_i64_i32 v[132:133], s[12:13], v184, s33, v[168:169]
	v_lshl_add_u64 v[132:133], v[132:133], 0, v[166:167]
	v_add_u32_e32 v174, 0x90, v34
	v_lshl_add_u64 v[134:135], v[132:133], 0, s[16:17]
	v_mad_i64_i32 v[136:137], s[12:13], v174, s33, v[168:169]
	v_add_co_u32_e32 v132, vcc, s1, v132
	v_lshl_add_u64 v[136:137], v[136:137], 0, v[166:167]
	v_add_u32_e32 v172, 0xa0, v34
	v_addc_co_u32_e32 v133, vcc, 0, v133, vcc
	v_lshl_add_u64 v[138:139], v[136:137], 0, s[16:17]
	v_mad_i64_i32 v[140:141], s[12:13], v172, s33, v[168:169]
	v_add_co_u32_e32 v136, vcc, s1, v136
	v_lshl_add_u64 v[140:141], v[140:141], 0, v[166:167]
	v_add_u32_e32 v170, 0xb0, v34
	v_addc_co_u32_e32 v137, vcc, 0, v137, vcc
	v_mad_i64_i32 v[144:145], s[12:13], v170, s33, v[168:169]
	global_load_dwordx4 v[176:179], v[132:133], off offset:2048
	global_load_dwordx4 v[152:155], v[136:137], off offset:2048
	global_load_dwordx4 v[180:183], v[134:135], off offset:256
	global_load_dwordx4 v[148:151], v[138:139], off offset:256
	v_add_co_u32_e32 v132, vcc, s1, v140
	v_lshl_add_u64 v[144:145], v[144:145], 0, v[166:167]
	s_nop 0
	v_addc_co_u32_e32 v133, vcc, 0, v141, vcc
	v_add_co_u32_e32 v134, vcc, s1, v144
	v_lshl_add_u64 v[142:143], v[140:141], 0, s[16:17]
	s_nop 0
	v_addc_co_u32_e32 v135, vcc, 0, v145, vcc
	v_lshl_add_u64 v[168:169], v[144:145], 0, s[16:17]
	global_load_dwordx4 v[144:147], v[132:133], off offset:2048
	global_load_dwordx4 v[136:139], v[134:135], off offset:2048
	s_nop 0
	global_load_dwordx4 v[140:143], v[142:143], off offset:256
	s_nop 0
	global_load_dwordx4 v[132:135], v[168:169], off offset:256
	v_ashrrev_i32_e32 v185, 31, v184
	v_ashrrev_i32_e32 v175, 31, v174
	v_ashrrev_i32_e32 v173, 31, v172
	v_ashrrev_i32_e32 v171, 31, v170
	s_waitcnt vmcnt(0)
	v_cvt_f32_f16_e32 v32, v176
	v_cvt_f32_f16_sdwa v35, v176 dst_sel:DWORD dst_unused:UNUSED_PAD src0_sel:WORD_1
	v_cvt_f32_f16_sdwa v176, v178 dst_sel:DWORD dst_unused:UNUSED_PAD src0_sel:WORD_1
	v_cvt_f32_f16_e32 v161, v177
	v_cvt_f32_f16_sdwa v163, v177 dst_sel:DWORD dst_unused:UNUSED_PAD src0_sel:WORD_1
	v_cvt_f32_f16_e32 v165, v178
	v_max_f32_e32 v176, 0xc1f00000, v176
	v_max_f32_e32 v35, 0xc1f00000, v35
	v_mul_f32_e32 v176, 0xbfb8aa3b, v176
	v_lshlrev_b64 v[168:169], 11, v[184:185]
	v_mul_f32_e32 v35, 0xbfb8aa3b, v35
	v_max_f32_e32 v161, 0xc1f00000, v161
	v_cvt_f32_f16_e32 v177, v179
	v_exp_f32_e32 v184, v176
	v_cvt_f32_f16_sdwa v176, v179 dst_sel:DWORD dst_unused:UNUSED_PAD src0_sel:WORD_1
	v_exp_f32_e32 v35, v35
	v_mul_f32_e32 v161, 0xbfb8aa3b, v161
	v_max_f32_e32 v163, 0xc1f00000, v163
	v_max_f32_e32 v32, 0xc1f00000, v32
	v_exp_f32_e32 v161, v161
	v_mul_f32_e32 v163, 0xbfb8aa3b, v163
	v_max_f32_e32 v165, 0xc1f00000, v165
	v_mul_f32_e32 v32, 0xbfb8aa3b, v32
	v_exp_f32_e32 v163, v163
	v_mul_f32_e32 v165, 0xbfb8aa3b, v165
	v_exp_f32_e32 v32, v32
	v_exp_f32_e32 v165, v165
	v_max_f32_e32 v177, 0xc1f00000, v177
	v_max_f32_e32 v176, 0xc1f00000, v176
	v_mul_f32_e32 v177, 0xbfb8aa3b, v177
	v_mul_f32_e32 v176, 0xbfb8aa3b, v176
	v_add_f32_e32 v35, 1.0, v35
	v_exp_f32_e32 v185, v177
	v_exp_f32_e32 v186, v176
	v_rcp_f32_e32 v176, v35
	v_add_f32_e32 v35, 1.0, v161
	v_rcp_f32_e32 v177, v35
	v_add_f32_e32 v35, 1.0, v163
	v_add_f32_e32 v32, 1.0, v32
	v_rcp_f32_e32 v178, v35
	v_add_f32_e32 v35, 1.0, v165
	v_rcp_f32_e32 v32, v32
	v_rcp_f32_e32 v179, v35
	v_add_f32_e32 v35, 1.0, v184
	v_rcp_f32_e32 v184, v35
	v_add_f32_e32 v35, 1.0, v185
	v_rcp_f32_e32 v185, v35
	v_add_f32_e32 v35, 1.0, v186
	v_mov_b32_e32 v186, v65
	v_mov_b32_e32 v187, v66
	v_pk_mul_f32 v[176:177], v[186:187], v[176:177]
	v_pk_mov_b32 v[186:187], v[66:67], v[60:61] op_sel:[1,0]
	v_fma_mixlo_f16 v32, v64, v32, 0
	v_cvt_pk_f16_f32 v161, v176, v177
	v_pk_mul_f32 v[178:179], v[186:187], v[178:179]
	v_rcp_f32_e32 v35, v35
	v_pack_b32_f16 v176, v32, v161
	v_cvt_pk_f16_f32 v32, v178, v179
	v_mov_b32_e32 v178, v61
	v_mov_b32_e32 v179, v62
	v_pk_mul_f32 v[178:179], v[178:179], v[184:185]
	v_alignbit_b32 v177, v32, v161, 16
	v_cvt_pk_f16_f32 v161, v178, v179
	v_lshrrev_b32_e32 v179, 16, v161
	v_lshl_add_u64 v[168:169], s[14:15], 0, v[168:169]
	v_alignbit_b32 v178, v161, v32, 16
	v_fma_mixhi_f16 v179, v63, v35, 0
	v_lshl_add_u64 v[168:169], v[168:169], 0, v[166:167]
	global_store_dwordx4 v[168:169], v[176:179], off
	v_cvt_f32_f16_sdwa v35, v180 dst_sel:DWORD dst_unused:UNUSED_PAD src0_sel:WORD_1
	v_cvt_f32_f16_e32 v161, v181
	v_cvt_f32_f16_sdwa v176, v182 dst_sel:DWORD dst_unused:UNUSED_PAD src0_sel:WORD_1
	v_cvt_f32_f16_sdwa v163, v181 dst_sel:DWORD dst_unused:UNUSED_PAD src0_sel:WORD_1
	v_cvt_f32_f16_e32 v32, v180
	v_cvt_f32_f16_e32 v165, v182
	v_max_f32_e32 v176, 0xc1f00000, v176
	v_max_f32_e32 v35, 0xc1f00000, v35
	v_mul_f32_e32 v176, 0xbfb8aa3b, v176
	v_mul_f32_e32 v35, 0xbfb8aa3b, v35
	v_max_f32_e32 v161, 0xc1f00000, v161
	v_cvt_f32_f16_e32 v177, v183
	v_exp_f32_e32 v180, v176
	v_cvt_f32_f16_sdwa v176, v183 dst_sel:DWORD dst_unused:UNUSED_PAD src0_sel:WORD_1
	v_exp_f32_e32 v35, v35
	v_mul_f32_e32 v161, 0xbfb8aa3b, v161
	v_max_f32_e32 v163, 0xc1f00000, v163
	v_max_f32_e32 v32, 0xc1f00000, v32
	v_exp_f32_e32 v161, v161
	v_mul_f32_e32 v163, 0xbfb8aa3b, v163
	v_max_f32_e32 v165, 0xc1f00000, v165
	v_mul_f32_e32 v32, 0xbfb8aa3b, v32
	v_exp_f32_e32 v163, v163
	v_mul_f32_e32 v165, 0xbfb8aa3b, v165
	v_exp_f32_e32 v32, v32
	v_exp_f32_e32 v165, v165
	v_max_f32_e32 v177, 0xc1f00000, v177
	v_max_f32_e32 v176, 0xc1f00000, v176
	v_mul_f32_e32 v177, 0xbfb8aa3b, v177
	v_mul_f32_e32 v176, 0xbfb8aa3b, v176
	v_add_f32_e32 v35, 1.0, v35
	v_exp_f32_e32 v181, v177
	v_exp_f32_e32 v182, v176
	v_rcp_f32_e32 v176, v35
	v_add_f32_e32 v35, 1.0, v161
	v_rcp_f32_e32 v177, v35
	v_add_f32_e32 v35, 1.0, v163
	v_add_f32_e32 v32, 1.0, v32
	v_rcp_f32_e32 v178, v35
	v_add_f32_e32 v35, 1.0, v165
	v_rcp_f32_e32 v32, v32
	v_rcp_f32_e32 v179, v35
	v_add_f32_e32 v35, 1.0, v180
	v_rcp_f32_e32 v180, v35
	v_add_f32_e32 v35, 1.0, v181
	v_rcp_f32_e32 v181, v35
	v_add_f32_e32 v35, 1.0, v182
	v_mov_b32_e32 v182, v29
	v_mov_b32_e32 v183, v30
	v_pk_mul_f32 v[176:177], v[182:183], v[176:177]
	v_pk_mov_b32 v[182:183], v[30:31], v[24:25] op_sel:[1,0]
	v_fma_mixlo_f16 v32, v28, v32, 0
	v_cvt_pk_f16_f32 v161, v176, v177
	v_pk_mul_f32 v[178:179], v[182:183], v[178:179]
	v_rcp_f32_e32 v35, v35
	v_pack_b32_f16 v176, v32, v161
	v_cvt_pk_f16_f32 v32, v178, v179
	v_mov_b32_e32 v178, v25
	v_mov_b32_e32 v179, v26
	v_pk_mul_f32 v[178:179], v[178:179], v[180:181]
	v_alignbit_b32 v177, v32, v161, 16
	v_cvt_pk_f16_f32 v161, v178, v179
	v_lshrrev_b32_e32 v179, 16, v161
	v_alignbit_b32 v178, v161, v32, 16
	v_fma_mixhi_f16 v179, v27, v35, 0
	v_cvt_f32_f16_e32 v32, v152
	v_cvt_f32_f16_sdwa v35, v152 dst_sel:DWORD dst_unused:UNUSED_PAD src0_sel:WORD_1
	v_cvt_f32_f16_e32 v152, v153
	v_cvt_f32_f16_sdwa v153, v153 dst_sel:DWORD dst_unused:UNUSED_PAD src0_sel:WORD_1
	global_store_dwordx4 v[168:169], v[176:179], off offset:256
	v_max_f32_e32 v35, 0xc1f00000, v35
	v_max_f32_e32 v152, 0xc1f00000, v152
	v_mul_f32_e32 v152, 0xbfb8aa3b, v152
	v_exp_f32_e32 v161, v152
	v_max_f32_e32 v152, 0xc1f00000, v153
	v_mul_f32_e32 v152, 0xbfb8aa3b, v152
	v_cvt_f32_f16_e32 v153, v154
	v_exp_f32_e32 v163, v152
	v_cvt_f32_f16_sdwa v152, v154 dst_sel:DWORD dst_unused:UNUSED_PAD src0_sel:WORD_1
	v_lshlrev_b64 v[168:169], 11, v[174:175]
	v_max_f32_e32 v153, 0xc1f00000, v153
	v_mul_f32_e32 v153, 0xbfb8aa3b, v153
	v_max_f32_e32 v152, 0xc1f00000, v152
	v_mul_f32_e32 v152, 0xbfb8aa3b, v152
	v_mul_f32_e32 v35, 0xbfb8aa3b, v35
	v_exp_f32_e32 v165, v153
	v_cvt_f32_f16_e32 v153, v155
	v_exp_f32_e32 v174, v152
	v_cvt_f32_f16_sdwa v152, v155 dst_sel:DWORD dst_unused:UNUSED_PAD src0_sel:WORD_1
	v_exp_f32_e32 v35, v35
	v_max_f32_e32 v32, 0xc1f00000, v32
	v_mul_f32_e32 v32, 0xbfb8aa3b, v32
	v_exp_f32_e32 v32, v32
	v_max_f32_e32 v153, 0xc1f00000, v153
	v_max_f32_e32 v152, 0xc1f00000, v152
	v_mul_f32_e32 v153, 0xbfb8aa3b, v153
	v_mul_f32_e32 v152, 0xbfb8aa3b, v152
	v_add_f32_e32 v35, 1.0, v35
	v_exp_f32_e32 v175, v153
	v_exp_f32_e32 v176, v152
	v_rcp_f32_e32 v152, v35
	v_add_f32_e32 v35, 1.0, v161
	v_rcp_f32_e32 v153, v35
	v_add_f32_e32 v35, 1.0, v163
	v_add_f32_e32 v32, 1.0, v32
	v_rcp_f32_e32 v154, v35
	v_add_f32_e32 v35, 1.0, v165
	v_rcp_f32_e32 v32, v32
	v_rcp_f32_e32 v155, v35
	v_add_f32_e32 v35, 1.0, v174
	v_rcp_f32_e32 v174, v35
	v_add_f32_e32 v35, 1.0, v175
	v_rcp_f32_e32 v175, v35
	v_add_f32_e32 v35, 1.0, v176
	v_mov_b32_e32 v176, v57
	v_mov_b32_e32 v177, v58
	v_pk_mul_f32 v[152:153], v[176:177], v[152:153]
	v_pk_mov_b32 v[176:177], v[58:59], v[52:53] op_sel:[1,0]
	v_fma_mixlo_f16 v32, v56, v32, 0
	v_cvt_pk_f16_f32 v153, v152, v153
	v_pk_mul_f32 v[154:155], v[176:177], v[154:155]
	v_rcp_f32_e32 v35, v35
	v_pack_b32_f16 v152, v32, v153
	v_cvt_pk_f16_f32 v32, v154, v155
	v_mov_b32_e32 v154, v53
	v_mov_b32_e32 v155, v54
	v_pk_mul_f32 v[154:155], v[154:155], v[174:175]
	v_alignbit_b32 v153, v32, v153, 16
	v_cvt_pk_f16_f32 v155, v154, v155
	v_alignbit_b32 v154, v155, v32, 16
	v_lshrrev_b32_e32 v155, 16, v155
	v_fma_mixhi_f16 v155, v55, v35, 0
	v_cvt_f32_f16_e32 v32, v148
	v_cvt_f32_f16_sdwa v35, v148 dst_sel:DWORD dst_unused:UNUSED_PAD src0_sel:WORD_1
	v_cvt_f32_f16_e32 v148, v149
	v_cvt_f32_f16_sdwa v149, v149 dst_sel:DWORD dst_unused:UNUSED_PAD src0_sel:WORD_1
	v_lshl_add_u64 v[168:169], s[14:15], 0, v[168:169]
	v_lshl_add_u64 v[168:169], v[168:169], 0, v[166:167]
	v_max_f32_e32 v148, 0xc1f00000, v148
	v_mul_f32_e32 v148, 0xbfb8aa3b, v148
	global_store_dwordx4 v[168:169], v[152:155], off
	v_max_f32_e32 v35, 0xc1f00000, v35
	v_mul_f32_e32 v35, 0xbfb8aa3b, v35
	v_exp_f32_e32 v152, v148
	v_max_f32_e32 v148, 0xc1f00000, v149
	v_mul_f32_e32 v148, 0xbfb8aa3b, v148
	v_cvt_f32_f16_e32 v149, v150
	v_exp_f32_e32 v153, v148
	v_cvt_f32_f16_sdwa v148, v150 dst_sel:DWORD dst_unused:UNUSED_PAD src0_sel:WORD_1
	v_exp_f32_e32 v35, v35
	v_max_f32_e32 v149, 0xc1f00000, v149
	v_mul_f32_e32 v149, 0xbfb8aa3b, v149
	v_max_f32_e32 v148, 0xc1f00000, v148
	v_mul_f32_e32 v148, 0xbfb8aa3b, v148
	v_exp_f32_e32 v154, v149
	v_cvt_f32_f16_e32 v149, v151
	v_exp_f32_e32 v155, v148
	v_cvt_f32_f16_sdwa v148, v151 dst_sel:DWORD dst_unused:UNUSED_PAD src0_sel:WORD_1
	v_max_f32_e32 v32, 0xc1f00000, v32
	v_mul_f32_e32 v32, 0xbfb8aa3b, v32
	v_exp_f32_e32 v32, v32
	v_max_f32_e32 v149, 0xc1f00000, v149
	v_max_f32_e32 v148, 0xc1f00000, v148
	v_mul_f32_e32 v149, 0xbfb8aa3b, v149
	v_mul_f32_e32 v148, 0xbfb8aa3b, v148
	v_add_f32_e32 v35, 1.0, v35
	v_exp_f32_e32 v161, v149
	v_exp_f32_e32 v163, v148
	v_rcp_f32_e32 v148, v35
	v_add_f32_e32 v35, 1.0, v152
	v_rcp_f32_e32 v149, v35
	v_add_f32_e32 v35, 1.0, v153
	v_add_f32_e32 v32, 1.0, v32
	v_rcp_f32_e32 v150, v35
	v_add_f32_e32 v35, 1.0, v154
	v_rcp_f32_e32 v32, v32
	v_rcp_f32_e32 v151, v35
	v_add_f32_e32 v35, 1.0, v155
	v_rcp_f32_e32 v152, v35
	v_add_f32_e32 v35, 1.0, v161
	v_rcp_f32_e32 v153, v35
	v_mov_b32_e32 v154, v21
	v_mov_b32_e32 v155, v22
	v_pk_mul_f32 v[148:149], v[154:155], v[148:149]
	v_pk_mov_b32 v[154:155], v[22:23], v[16:17] op_sel:[1,0]
	v_add_f32_e32 v35, 1.0, v163
	v_fma_mixlo_f16 v32, v20, v32, 0
	v_cvt_pk_f16_f32 v149, v148, v149
	v_pk_mul_f32 v[150:151], v[154:155], v[150:151]
	v_rcp_f32_e32 v35, v35
	v_pack_b32_f16 v148, v32, v149
	v_cvt_pk_f16_f32 v32, v150, v151
	v_mov_b32_e32 v150, v17
	v_mov_b32_e32 v151, v18
	v_pk_mul_f32 v[150:151], v[150:151], v[152:153]
	v_alignbit_b32 v149, v32, v149, 16
	v_cvt_pk_f16_f32 v151, v150, v151
	v_alignbit_b32 v150, v151, v32, 16
	v_lshrrev_b32_e32 v151, 16, v151
	v_fma_mixhi_f16 v151, v19, v35, 0
	v_cvt_f32_f16_e32 v32, v144
	v_cvt_f32_f16_sdwa v35, v144 dst_sel:DWORD dst_unused:UNUSED_PAD src0_sel:WORD_1
	v_cvt_f32_f16_e32 v144, v145
	v_cvt_f32_f16_sdwa v145, v145 dst_sel:DWORD dst_unused:UNUSED_PAD src0_sel:WORD_1
	global_store_dwordx4 v[168:169], v[148:151], off offset:256
	v_max_f32_e32 v35, 0xc1f00000, v35
	v_max_f32_e32 v144, 0xc1f00000, v144
	v_mul_f32_e32 v144, 0xbfb8aa3b, v144
	v_exp_f32_e32 v150, v144
	v_max_f32_e32 v144, 0xc1f00000, v145
	v_mul_f32_e32 v144, 0xbfb8aa3b, v144
	v_cvt_f32_f16_e32 v145, v146
	v_exp_f32_e32 v151, v144
	v_cvt_f32_f16_sdwa v144, v146 dst_sel:DWORD dst_unused:UNUSED_PAD src0_sel:WORD_1
	v_mul_f32_e32 v35, 0xbfb8aa3b, v35
	v_max_f32_e32 v145, 0xc1f00000, v145
	v_mul_f32_e32 v145, 0xbfb8aa3b, v145
	v_max_f32_e32 v144, 0xc1f00000, v144
	v_mul_f32_e32 v144, 0xbfb8aa3b, v144
	v_exp_f32_e32 v152, v145
	v_cvt_f32_f16_e32 v145, v147
	v_exp_f32_e32 v153, v144
	v_cvt_f32_f16_sdwa v144, v147 dst_sel:DWORD dst_unused:UNUSED_PAD src0_sel:WORD_1
	v_exp_f32_e32 v35, v35
	v_max_f32_e32 v32, 0xc1f00000, v32
	v_mul_f32_e32 v32, 0xbfb8aa3b, v32
	v_exp_f32_e32 v32, v32
	v_max_f32_e32 v145, 0xc1f00000, v145
	v_max_f32_e32 v144, 0xc1f00000, v144
	v_mul_f32_e32 v145, 0xbfb8aa3b, v145
	v_mul_f32_e32 v144, 0xbfb8aa3b, v144
	v_add_f32_e32 v35, 1.0, v35
	v_exp_f32_e32 v154, v145
	v_exp_f32_e32 v155, v144
	v_rcp_f32_e32 v144, v35
	v_add_f32_e32 v35, 1.0, v150
	v_rcp_f32_e32 v145, v35
	v_add_f32_e32 v35, 1.0, v151
	v_add_f32_e32 v32, 1.0, v32
	v_rcp_f32_e32 v146, v35
	v_add_f32_e32 v35, 1.0, v152
	v_rcp_f32_e32 v32, v32
	v_rcp_f32_e32 v147, v35
	v_add_f32_e32 v35, 1.0, v153
	v_rcp_f32_e32 v150, v35
	v_add_f32_e32 v35, 1.0, v154
	v_rcp_f32_e32 v151, v35
	v_mov_b32_e32 v152, v49
	v_mov_b32_e32 v153, v50
	v_pk_mul_f32 v[144:145], v[152:153], v[144:145]
	v_pk_mov_b32 v[152:153], v[50:51], v[44:45] op_sel:[1,0]
	v_add_f32_e32 v35, 1.0, v155
	v_fma_mixlo_f16 v32, v48, v32, 0
	v_cvt_pk_f16_f32 v145, v144, v145
	v_pk_mul_f32 v[146:147], v[152:153], v[146:147]
	v_rcp_f32_e32 v35, v35
	v_pack_b32_f16 v144, v32, v145
	v_cvt_pk_f16_f32 v32, v146, v147
	v_mov_b32_e32 v146, v45
	v_mov_b32_e32 v147, v46
	v_pk_mul_f32 v[146:147], v[146:147], v[150:151]
	v_alignbit_b32 v145, v32, v145, 16
	v_cvt_pk_f16_f32 v147, v146, v147
	v_alignbit_b32 v146, v147, v32, 16
	v_lshrrev_b32_e32 v147, 16, v147
	v_fma_mixhi_f16 v147, v47, v35, 0
	v_cvt_f32_f16_e32 v32, v140
	v_cvt_f32_f16_sdwa v35, v140 dst_sel:DWORD dst_unused:UNUSED_PAD src0_sel:WORD_1
	v_cvt_f32_f16_e32 v140, v141
	v_cvt_f32_f16_sdwa v141, v141 dst_sel:DWORD dst_unused:UNUSED_PAD src0_sel:WORD_1
	v_lshlrev_b64 v[148:149], 11, v[172:173]
	v_lshl_add_u64 v[148:149], s[14:15], 0, v[148:149]
	v_max_f32_e32 v140, 0xc1f00000, v140
	v_lshl_add_u64 v[148:149], v[148:149], 0, v[166:167]
	v_mul_f32_e32 v140, 0xbfb8aa3b, v140
	global_store_dwordx4 v[148:149], v[144:147], off
	v_max_f32_e32 v35, 0xc1f00000, v35
	v_mul_f32_e32 v35, 0xbfb8aa3b, v35
	v_exp_f32_e32 v144, v140
	v_max_f32_e32 v140, 0xc1f00000, v141
	v_mul_f32_e32 v140, 0xbfb8aa3b, v140
	v_cvt_f32_f16_e32 v141, v142
	v_exp_f32_e32 v145, v140
	v_cvt_f32_f16_sdwa v140, v142 dst_sel:DWORD dst_unused:UNUSED_PAD src0_sel:WORD_1
	v_exp_f32_e32 v35, v35
	v_max_f32_e32 v141, 0xc1f00000, v141
	v_mul_f32_e32 v141, 0xbfb8aa3b, v141
	v_max_f32_e32 v140, 0xc1f00000, v140
	v_mul_f32_e32 v140, 0xbfb8aa3b, v140
	v_exp_f32_e32 v146, v141
	v_cvt_f32_f16_e32 v141, v143
	v_exp_f32_e32 v147, v140
	v_cvt_f32_f16_sdwa v140, v143 dst_sel:DWORD dst_unused:UNUSED_PAD src0_sel:WORD_1
	v_max_f32_e32 v32, 0xc1f00000, v32
	v_mul_f32_e32 v32, 0xbfb8aa3b, v32
	v_exp_f32_e32 v32, v32
	v_max_f32_e32 v141, 0xc1f00000, v141
	v_max_f32_e32 v140, 0xc1f00000, v140
	v_mul_f32_e32 v141, 0xbfb8aa3b, v141
	v_mul_f32_e32 v140, 0xbfb8aa3b, v140
	v_add_f32_e32 v35, 1.0, v35
	v_exp_f32_e32 v150, v141
	v_exp_f32_e32 v151, v140
	v_rcp_f32_e32 v140, v35
	v_add_f32_e32 v35, 1.0, v144
	v_rcp_f32_e32 v141, v35
	v_add_f32_e32 v35, 1.0, v145
	v_add_f32_e32 v32, 1.0, v32
	v_rcp_f32_e32 v142, v35
	v_add_f32_e32 v35, 1.0, v146
	v_rcp_f32_e32 v32, v32
	v_rcp_f32_e32 v143, v35
	v_add_f32_e32 v35, 1.0, v147
	v_rcp_f32_e32 v144, v35
	v_add_f32_e32 v35, 1.0, v150
	v_rcp_f32_e32 v145, v35
	v_mov_b32_e32 v146, v13
	v_mov_b32_e32 v147, v14
	v_pk_mul_f32 v[140:141], v[146:147], v[140:141]
	v_pk_mov_b32 v[146:147], v[14:15], v[8:9] op_sel:[1,0]
	v_add_f32_e32 v35, 1.0, v151
	v_fma_mixlo_f16 v32, v12, v32, 0
	v_cvt_pk_f16_f32 v141, v140, v141
	v_pk_mul_f32 v[142:143], v[146:147], v[142:143]
	v_rcp_f32_e32 v35, v35
	v_pack_b32_f16 v140, v32, v141
	v_cvt_pk_f16_f32 v32, v142, v143
	v_mov_b32_e32 v142, v9
	v_mov_b32_e32 v143, v10
	v_pk_mul_f32 v[142:143], v[142:143], v[144:145]
	v_alignbit_b32 v141, v32, v141, 16
	v_cvt_pk_f16_f32 v143, v142, v143
	v_alignbit_b32 v142, v143, v32, 16
	v_lshrrev_b32_e32 v143, 16, v143
	v_fma_mixhi_f16 v143, v11, v35, 0
	v_cvt_f32_f16_e32 v32, v136
	v_cvt_f32_f16_sdwa v35, v136 dst_sel:DWORD dst_unused:UNUSED_PAD src0_sel:WORD_1
	v_cvt_f32_f16_e32 v136, v137
	v_cvt_f32_f16_sdwa v137, v137 dst_sel:DWORD dst_unused:UNUSED_PAD src0_sel:WORD_1
	global_store_dwordx4 v[148:149], v[140:143], off offset:256
	v_max_f32_e32 v35, 0xc1f00000, v35
	v_max_f32_e32 v136, 0xc1f00000, v136
	v_mul_f32_e32 v136, 0xbfb8aa3b, v136
	v_exp_f32_e32 v142, v136
	v_max_f32_e32 v136, 0xc1f00000, v137
	v_mul_f32_e32 v136, 0xbfb8aa3b, v136
	v_cvt_f32_f16_e32 v137, v138
	v_exp_f32_e32 v143, v136
	v_cvt_f32_f16_sdwa v136, v138 dst_sel:DWORD dst_unused:UNUSED_PAD src0_sel:WORD_1
	v_mul_f32_e32 v35, 0xbfb8aa3b, v35
	v_max_f32_e32 v137, 0xc1f00000, v137
	v_mul_f32_e32 v137, 0xbfb8aa3b, v137
	v_max_f32_e32 v136, 0xc1f00000, v136
	v_mul_f32_e32 v136, 0xbfb8aa3b, v136
	v_exp_f32_e32 v144, v137
	v_cvt_f32_f16_e32 v137, v139
	v_exp_f32_e32 v145, v136
	v_cvt_f32_f16_sdwa v136, v139 dst_sel:DWORD dst_unused:UNUSED_PAD src0_sel:WORD_1
	v_exp_f32_e32 v35, v35
	v_max_f32_e32 v32, 0xc1f00000, v32
	v_mul_f32_e32 v32, 0xbfb8aa3b, v32
	v_exp_f32_e32 v32, v32
	v_max_f32_e32 v137, 0xc1f00000, v137
	v_max_f32_e32 v136, 0xc1f00000, v136
	v_mul_f32_e32 v137, 0xbfb8aa3b, v137
	v_mul_f32_e32 v136, 0xbfb8aa3b, v136
	v_add_f32_e32 v35, 1.0, v35
	v_exp_f32_e32 v146, v137
	v_exp_f32_e32 v147, v136
	v_rcp_f32_e32 v136, v35
	v_add_f32_e32 v35, 1.0, v142
	v_rcp_f32_e32 v137, v35
	v_add_f32_e32 v35, 1.0, v143
	v_add_f32_e32 v32, 1.0, v32
	v_rcp_f32_e32 v138, v35
	v_add_f32_e32 v35, 1.0, v144
	v_rcp_f32_e32 v32, v32
	v_rcp_f32_e32 v139, v35
	v_add_f32_e32 v35, 1.0, v145
	v_rcp_f32_e32 v142, v35
	v_add_f32_e32 v35, 1.0, v146
	v_rcp_f32_e32 v143, v35
	v_mov_b32_e32 v144, v41
	v_mov_b32_e32 v145, v42
	v_pk_mul_f32 v[136:137], v[144:145], v[136:137]
	v_pk_mov_b32 v[144:145], v[42:43], v[36:37] op_sel:[1,0]
	v_add_f32_e32 v35, 1.0, v147
	v_fma_mixlo_f16 v32, v40, v32, 0
	v_cvt_pk_f16_f32 v137, v136, v137
	v_pk_mul_f32 v[138:139], v[144:145], v[138:139]
	v_rcp_f32_e32 v35, v35
	v_pack_b32_f16 v136, v32, v137
	v_cvt_pk_f16_f32 v32, v138, v139
	v_mov_b32_e32 v138, v37
	v_mov_b32_e32 v139, v38
	v_pk_mul_f32 v[138:139], v[138:139], v[142:143]
	v_alignbit_b32 v137, v32, v137, 16
	v_cvt_pk_f16_f32 v139, v138, v139
	v_alignbit_b32 v138, v139, v32, 16
	v_lshrrev_b32_e32 v139, 16, v139
	v_fma_mixhi_f16 v139, v39, v35, 0
	v_cvt_f32_f16_e32 v32, v132
	v_cvt_f32_f16_sdwa v35, v132 dst_sel:DWORD dst_unused:UNUSED_PAD src0_sel:WORD_1
	v_cvt_f32_f16_e32 v132, v133
	v_cvt_f32_f16_sdwa v133, v133 dst_sel:DWORD dst_unused:UNUSED_PAD src0_sel:WORD_1
	v_lshlrev_b64 v[140:141], 11, v[170:171]
	v_lshl_add_u64 v[140:141], s[14:15], 0, v[140:141]
	v_max_f32_e32 v132, 0xc1f00000, v132
	v_lshl_add_u64 v[140:141], v[140:141], 0, v[166:167]
	v_mul_f32_e32 v132, 0xbfb8aa3b, v132
	global_store_dwordx4 v[140:141], v[136:139], off
	v_max_f32_e32 v35, 0xc1f00000, v35
	v_mul_f32_e32 v35, 0xbfb8aa3b, v35
	v_exp_f32_e32 v136, v132
	v_max_f32_e32 v132, 0xc1f00000, v133
	v_mul_f32_e32 v132, 0xbfb8aa3b, v132
	v_cvt_f32_f16_e32 v133, v134
	v_exp_f32_e32 v137, v132
	v_cvt_f32_f16_sdwa v132, v134 dst_sel:DWORD dst_unused:UNUSED_PAD src0_sel:WORD_1
	v_exp_f32_e32 v35, v35
	v_max_f32_e32 v133, 0xc1f00000, v133
	v_mul_f32_e32 v133, 0xbfb8aa3b, v133
	v_max_f32_e32 v132, 0xc1f00000, v132
	v_mul_f32_e32 v132, 0xbfb8aa3b, v132
	v_exp_f32_e32 v138, v133
	v_cvt_f32_f16_e32 v133, v135
	v_exp_f32_e32 v139, v132
	v_cvt_f32_f16_sdwa v132, v135 dst_sel:DWORD dst_unused:UNUSED_PAD src0_sel:WORD_1
	v_max_f32_e32 v32, 0xc1f00000, v32
	v_mul_f32_e32 v32, 0xbfb8aa3b, v32
	v_exp_f32_e32 v32, v32
	v_max_f32_e32 v133, 0xc1f00000, v133
	v_max_f32_e32 v132, 0xc1f00000, v132
	v_mul_f32_e32 v133, 0xbfb8aa3b, v133
	v_mul_f32_e32 v132, 0xbfb8aa3b, v132
	v_add_f32_e32 v35, 1.0, v35
	v_exp_f32_e32 v142, v133
	v_exp_f32_e32 v143, v132
	v_rcp_f32_e32 v132, v35
	v_add_f32_e32 v35, 1.0, v136
	v_rcp_f32_e32 v133, v35
	v_add_f32_e32 v35, 1.0, v137
	v_add_f32_e32 v32, 1.0, v32
	v_rcp_f32_e32 v134, v35
	v_add_f32_e32 v35, 1.0, v138
	v_rcp_f32_e32 v32, v32
	v_rcp_f32_e32 v135, v35
	v_add_f32_e32 v35, 1.0, v139
	v_rcp_f32_e32 v136, v35
	v_add_f32_e32 v35, 1.0, v142
	v_rcp_f32_e32 v137, v35
	v_mov_b32_e32 v138, v5
	v_mov_b32_e32 v139, v6
	v_pk_mul_f32 v[132:133], v[138:139], v[132:133]
	v_pk_mov_b32 v[138:139], v[6:7], v[0:1] op_sel:[1,0]
	v_add_f32_e32 v35, 1.0, v143
	v_fma_mixlo_f16 v32, v4, v32, 0
	v_cvt_pk_f16_f32 v133, v132, v133
	v_pk_mul_f32 v[134:135], v[138:139], v[134:135]
	v_rcp_f32_e32 v35, v35
	v_pack_b32_f16 v132, v32, v133
	v_cvt_pk_f16_f32 v32, v134, v135
	v_mov_b32_e32 v134, v1
	v_mov_b32_e32 v135, v2
	v_pk_mul_f32 v[134:135], v[134:135], v[136:137]
	v_alignbit_b32 v133, v32, v133, 16
	v_cvt_pk_f16_f32 v135, v134, v135
	v_alignbit_b32 v134, v135, v32, 16
	v_lshrrev_b32_e32 v135, 16, v135
	v_fma_mixhi_f16 v135, v3, v35, 0
	global_store_dwordx4 v[140:141], v[132:135], off offset:256
	s_cbranch_execnz .LBB0_944

.LBB0_958:
	s_add_u32 s12, s10, 0x100
	s_addc_u32 s13, s11, 0
	s_add_i32 s38, 0, 0x10000
	v_add_u32_e32 v142, s38, v196
	ds_read_b128 v[122:125], v142
	ds_read_b128 v[138:141], v142 offset:2048
	ds_read_b128 v[130:133], v142 offset:1024
	ds_read_b128 v[142:145], v142 offset:3072
	s_cmp_eq_u32 s37, 12
	s_cselect_b32 s17, s7, s13
	s_cselect_b32 s16, s6, s12
	s_cselect_b32 s15, s9, s36
	s_cselect_b32 s14, s8, s35
	v_lshl_add_u64 v[230:231], s[10:11], 0, v[188:189]
	s_add_i32 m0, s21, 0xc000
	ds_read_b128 v[146:149], v198
	ds_read_b128 v[192:195], v198 offset:2048
	ds_read_b128 v[204:207], v198 offset:4096
	ds_read_b128 v[212:215], v198 offset:6144
	ds_read_b128 v[150:153], v198 offset:1024
	ds_read_b128 v[200:203], v198 offset:3072
	ds_read_b128 v[208:211], v198 offset:5120
	ds_read_b128 v[216:219], v198 offset:7168
	global_load_lds_dwordx4 v[230:231], off
	v_lshl_add_u64 v[230:231], s[10:11], 0, v[190:191]
	s_add_i32 m0, s21, 0xe000
	s_nop 0
	global_load_lds_dwordx4 v[230:231], off
	s_waitcnt lgkmcnt(8)
	s_barrier
	s_waitcnt lgkmcnt(7)
	s_setprio 1
	v_mfma_f32_16x16x32_f16 v[134:137], v[122:125], v[146:149], v[134:137]
	v_mfma_f32_16x16x32_f16 v[126:129], v[138:141], v[146:149], v[126:129]
	s_waitcnt lgkmcnt(6)
	v_mfma_f32_16x16x32_f16 v[110:113], v[122:125], v[192:195], v[110:113]
	v_mfma_f32_16x16x32_f16 v[106:109], v[138:141], v[192:195], v[106:109]
	s_waitcnt lgkmcnt(5)
	v_mfma_f32_16x16x32_f16 v[94:97], v[122:125], v[204:207], v[94:97]
	v_mfma_f32_16x16x32_f16 v[90:93], v[138:141], v[204:207], v[90:93]
	s_waitcnt lgkmcnt(4)
	v_mfma_f32_16x16x32_f16 v[78:81], v[122:125], v[212:215], v[78:81]
	v_mfma_f32_16x16x32_f16 v[74:77], v[138:141], v[212:215], v[74:77]
	s_waitcnt lgkmcnt(3)
	v_mfma_f32_16x16x32_f16 v[134:137], v[130:133], v[150:153], v[134:137]
	v_mfma_f32_16x16x32_f16 v[126:129], v[142:145], v[150:153], v[126:129]
	s_waitcnt lgkmcnt(2)
	v_mfma_f32_16x16x32_f16 v[110:113], v[130:133], v[200:203], v[110:113]
	v_mfma_f32_16x16x32_f16 v[106:109], v[142:145], v[200:203], v[106:109]
	s_waitcnt lgkmcnt(1)
	v_mfma_f32_16x16x32_f16 v[94:97], v[130:133], v[208:211], v[94:97]
	v_mfma_f32_16x16x32_f16 v[90:93], v[142:145], v[208:211], v[90:93]
	s_waitcnt lgkmcnt(0)
	v_mfma_f32_16x16x32_f16 v[78:81], v[130:133], v[216:219], v[78:81]
	v_mfma_f32_16x16x32_f16 v[74:77], v[142:145], v[216:219], v[74:77]
	s_setprio 0
	s_barrier
	s_add_i32 s39, 0, 0x14000
	s_add_i32 s10, s38, s20
	v_add_u32_e32 v199, s39, v196
	v_lshl_add_u64 v[246:247], s[14:15], 0, v[32:33]
	s_mov_b32 m0, s10
	ds_read_b128 v[230:233], v199
	ds_read_b128 v[238:241], v199 offset:2048
	ds_read_b128 v[234:237], v199 offset:1024
	ds_read_b128 v[242:245], v199 offset:3072
	global_load_lds_dwordx4 v[246:247], off
	v_lshl_add_u64 v[248:249], s[14:15], 0, v[154:155]
	s_add_i32 m0, s10, 0x2000
	s_nop 0
	global_load_lds_dwordx4 v[248:249], off
	s_barrier
	s_waitcnt lgkmcnt(2)
	s_setprio 1
	v_mfma_f32_16x16x32_f16 v[118:121], v[230:233], v[146:149], v[118:121]
	v_mfma_f32_16x16x32_f16 v[114:117], v[238:241], v[146:149], v[114:117]
	v_mfma_f32_16x16x32_f16 v[102:105], v[230:233], v[192:195], v[102:105]
	v_mfma_f32_16x16x32_f16 v[98:101], v[238:241], v[192:195], v[98:101]
	v_mfma_f32_16x16x32_f16 v[86:89], v[230:233], v[204:207], v[86:89]
	v_mfma_f32_16x16x32_f16 v[82:85], v[238:241], v[204:207], v[82:85]
	v_mfma_f32_16x16x32_f16 v[70:73], v[230:233], v[212:215], v[70:73]
	v_mfma_f32_16x16x32_f16 v[66:69], v[238:241], v[212:215], v[66:69]
	s_waitcnt lgkmcnt(0)
	v_mfma_f32_16x16x32_f16 v[118:121], v[234:237], v[150:153], v[118:121]
	v_mfma_f32_16x16x32_f16 v[114:117], v[242:245], v[150:153], v[114:117]
	v_mfma_f32_16x16x32_f16 v[102:105], v[234:237], v[200:203], v[102:105]
	v_mfma_f32_16x16x32_f16 v[98:101], v[242:245], v[200:203], v[98:101]
	v_mfma_f32_16x16x32_f16 v[86:89], v[234:237], v[208:211], v[86:89]
	v_mfma_f32_16x16x32_f16 v[82:85], v[242:245], v[208:211], v[82:85]
	v_mfma_f32_16x16x32_f16 v[70:73], v[234:237], v[216:219], v[70:73]
	v_mfma_f32_16x16x32_f16 v[66:69], v[242:245], v[216:219], v[66:69]
	s_setprio 0
	s_mov_b32 m0, s21
	v_lshl_add_u64 v[228:229], s[16:17], 0, v[32:33]
	s_barrier
	ds_read_b128 v[146:149], v198 offset:16384
	ds_read_b128 v[192:195], v198 offset:18432
	ds_read_b128 v[204:207], v198 offset:20480
	ds_read_b128 v[212:215], v198 offset:22528
	ds_read_b128 v[150:153], v198 offset:17408
	ds_read_b128 v[200:203], v198 offset:19456
	ds_read_b128 v[208:211], v198 offset:21504
	ds_read_b128 v[216:219], v198 offset:23552
	global_load_lds_dwordx4 v[228:229], off
	v_lshl_add_u64 v[222:223], s[16:17], 0, v[154:155]
	s_mov_b32 m0, s22
	s_nop 0
	global_load_lds_dwordx4 v[222:223], off
	s_barrier
	s_waitcnt lgkmcnt(7)
	s_setprio 1
	v_mfma_f32_16x16x32_f16 v[62:65], v[122:125], v[146:149], v[62:65]
	v_mfma_f32_16x16x32_f16 v[58:61], v[138:141], v[146:149], v[58:61]
	s_waitcnt lgkmcnt(6)
	v_mfma_f32_16x16x32_f16 v[46:49], v[122:125], v[192:195], v[46:49]
	v_mfma_f32_16x16x32_f16 v[42:45], v[138:141], v[192:195], v[42:45]
	s_waitcnt lgkmcnt(5)
	v_mfma_f32_16x16x32_f16 v[28:31], v[122:125], v[204:207], v[28:31]
	v_mfma_f32_16x16x32_f16 v[24:27], v[138:141], v[204:207], v[24:27]
	s_waitcnt lgkmcnt(4)
	v_mfma_f32_16x16x32_f16 v[12:15], v[122:125], v[212:215], v[12:15]
	v_mfma_f32_16x16x32_f16 v[8:11], v[138:141], v[212:215], v[8:11]
	s_waitcnt lgkmcnt(3)
	v_mfma_f32_16x16x32_f16 v[62:65], v[130:133], v[150:153], v[62:65]
	v_mfma_f32_16x16x32_f16 v[58:61], v[142:145], v[150:153], v[58:61]
	s_waitcnt lgkmcnt(2)
	v_mfma_f32_16x16x32_f16 v[46:49], v[130:133], v[200:203], v[46:49]
	v_mfma_f32_16x16x32_f16 v[42:45], v[142:145], v[200:203], v[42:45]
	s_waitcnt lgkmcnt(1)
	v_mfma_f32_16x16x32_f16 v[28:31], v[130:133], v[208:211], v[28:31]
	v_mfma_f32_16x16x32_f16 v[24:27], v[142:145], v[208:211], v[24:27]
	s_waitcnt lgkmcnt(0)
	v_mfma_f32_16x16x32_f16 v[12:15], v[130:133], v[216:219], v[12:15]
	v_mfma_f32_16x16x32_f16 v[8:11], v[142:145], v[216:219], v[8:11]
	s_setprio 0
	s_barrier
	s_add_u32 s10, s14, 0x40000
	s_addc_u32 s11, s15, 0
	s_add_i32 s38, s39, s20
	v_lshl_add_u64 v[122:123], s[10:11], 0, v[32:33]
	s_mov_b32 m0, s38
	s_nop 0
	global_load_lds_dwordx4 v[122:123], off
	v_lshl_add_u64 v[122:123], s[10:11], 0, v[154:155]
	s_add_i32 m0, s38, 0x2000
	s_nop 0
	global_load_lds_dwordx4 v[122:123], off
	s_waitcnt vmcnt(10)
	s_barrier
	s_setprio 1
	v_mfma_f32_16x16x32_f16 v[54:57], v[230:233], v[146:149], v[54:57]
	v_mfma_f32_16x16x32_f16 v[50:53], v[238:241], v[146:149], v[50:53]
	v_mfma_f32_16x16x32_f16 v[38:41], v[230:233], v[192:195], v[38:41]
	v_mfma_f32_16x16x32_f16 v[34:37], v[238:241], v[192:195], v[34:37]
	v_mfma_f32_16x16x32_f16 v[20:23], v[230:233], v[204:207], v[20:23]
	v_mfma_f32_16x16x32_f16 v[16:19], v[238:241], v[204:207], v[16:19]
	v_mfma_f32_16x16x32_f16 v[4:7], v[230:233], v[212:215], v[4:7]
	v_mfma_f32_16x16x32_f16 v[0:3], v[238:241], v[212:215], v[0:3]
	v_mfma_f32_16x16x32_f16 v[54:57], v[234:237], v[150:153], v[54:57]
	v_mfma_f32_16x16x32_f16 v[50:53], v[242:245], v[150:153], v[50:53]
	v_mfma_f32_16x16x32_f16 v[38:41], v[234:237], v[200:203], v[38:41]
	v_mfma_f32_16x16x32_f16 v[34:37], v[242:245], v[200:203], v[34:37]
	v_mfma_f32_16x16x32_f16 v[20:23], v[234:237], v[208:211], v[20:23]
	v_mfma_f32_16x16x32_f16 v[16:19], v[242:245], v[208:211], v[16:19]
	v_mfma_f32_16x16x32_f16 v[4:7], v[234:237], v[216:219], v[4:7]
	v_mfma_f32_16x16x32_f16 v[0:3], v[242:245], v[216:219], v[0:3]
	s_setprio 0
	s_add_i32 s38, 0, 0x18000
	v_add_u32_e32 v142, s38, v196
	s_barrier
	ds_read_b128 v[122:125], v142
	ds_read_b128 v[138:141], v142 offset:2048
	ds_read_b128 v[130:133], v142 offset:1024
	ds_read_b128 v[142:145], v142 offset:3072
	s_add_u32 s10, s16, 0x40000
	s_addc_u32 s11, s17, 0
	s_mov_b32 m0, s23
	v_lshl_add_u64 v[230:231], s[10:11], 0, v[32:33]
	ds_read_b128 v[146:149], v198 offset:32768
	ds_read_b128 v[192:195], v198 offset:34816
	ds_read_b128 v[204:207], v198 offset:36864
	ds_read_b128 v[212:215], v198 offset:38912
	ds_read_b128 v[150:153], v198 offset:33792
	ds_read_b128 v[200:203], v198 offset:35840
	ds_read_b128 v[208:211], v198 offset:37888
	ds_read_b128 v[216:219], v198 offset:39936
	global_load_lds_dwordx4 v[230:231], off
	v_lshl_add_u64 v[230:231], s[10:11], 0, v[154:155]
	s_mov_b32 m0, s24
	s_nop 0
	global_load_lds_dwordx4 v[230:231], off
	s_waitcnt lgkmcnt(8)
	s_waitcnt vmcnt(10)
	s_barrier
	s_waitcnt lgkmcnt(7)
	s_setprio 1
	v_mfma_f32_16x16x32_f16 v[134:137], v[122:125], v[146:149], v[134:137]
	v_mfma_f32_16x16x32_f16 v[126:129], v[138:141], v[146:149], v[126:129]
	s_waitcnt lgkmcnt(6)
	v_mfma_f32_16x16x32_f16 v[110:113], v[122:125], v[192:195], v[110:113]
	v_mfma_f32_16x16x32_f16 v[106:109], v[138:141], v[192:195], v[106:109]
	s_waitcnt lgkmcnt(5)
	v_mfma_f32_16x16x32_f16 v[94:97], v[122:125], v[204:207], v[94:97]
	v_mfma_f32_16x16x32_f16 v[90:93], v[138:141], v[204:207], v[90:93]
	s_waitcnt lgkmcnt(4)
	v_mfma_f32_16x16x32_f16 v[78:81], v[122:125], v[212:215], v[78:81]
	v_mfma_f32_16x16x32_f16 v[74:77], v[138:141], v[212:215], v[74:77]
	s_waitcnt lgkmcnt(3)
	v_mfma_f32_16x16x32_f16 v[134:137], v[130:133], v[150:153], v[134:137]
	v_mfma_f32_16x16x32_f16 v[126:129], v[142:145], v[150:153], v[126:129]
	s_waitcnt lgkmcnt(2)
	v_mfma_f32_16x16x32_f16 v[110:113], v[130:133], v[200:203], v[110:113]
	v_mfma_f32_16x16x32_f16 v[106:109], v[142:145], v[200:203], v[106:109]
	s_waitcnt lgkmcnt(1)
	v_mfma_f32_16x16x32_f16 v[94:97], v[130:133], v[208:211], v[94:97]
	v_mfma_f32_16x16x32_f16 v[90:93], v[142:145], v[208:211], v[90:93]
	s_waitcnt lgkmcnt(0)
	v_mfma_f32_16x16x32_f16 v[78:81], v[130:133], v[216:219], v[78:81]
	v_mfma_f32_16x16x32_f16 v[74:77], v[142:145], v[216:219], v[74:77]
	s_setprio 0
	s_barrier
	s_add_i32 s16, 0, 0x1c000
	s_add_i32 s10, s38, s20
	v_add_u32_e32 v199, s16, v196
	v_lshl_add_u64 v[246:247], v[246:247], 0, s[84:85]
	s_mov_b32 m0, s10
	ds_read_b128 v[230:233], v199
	ds_read_b128 v[238:241], v199 offset:2048
	ds_read_b128 v[234:237], v199 offset:1024
	ds_read_b128 v[242:245], v199 offset:3072
	global_load_lds_dwordx4 v[246:247], off
	v_lshl_add_u64 v[246:247], v[248:249], 0, s[84:85]
	s_add_i32 m0, s10, 0x2000
	s_nop 0
	global_load_lds_dwordx4 v[246:247], off
	s_waitcnt vmcnt(10)
	s_barrier
	s_waitcnt lgkmcnt(2)
	s_setprio 1
	v_mfma_f32_16x16x32_f16 v[118:121], v[230:233], v[146:149], v[118:121]
	v_mfma_f32_16x16x32_f16 v[114:117], v[238:241], v[146:149], v[114:117]
	v_mfma_f32_16x16x32_f16 v[102:105], v[230:233], v[192:195], v[102:105]
	v_mfma_f32_16x16x32_f16 v[98:101], v[238:241], v[192:195], v[98:101]
	v_mfma_f32_16x16x32_f16 v[86:89], v[230:233], v[204:207], v[86:89]
	v_mfma_f32_16x16x32_f16 v[82:85], v[238:241], v[204:207], v[82:85]
	v_mfma_f32_16x16x32_f16 v[70:73], v[230:233], v[212:215], v[70:73]
	v_mfma_f32_16x16x32_f16 v[66:69], v[238:241], v[212:215], v[66:69]
	s_waitcnt lgkmcnt(0)
	v_mfma_f32_16x16x32_f16 v[118:121], v[234:237], v[150:153], v[118:121]
	v_mfma_f32_16x16x32_f16 v[114:117], v[242:245], v[150:153], v[114:117]
	v_mfma_f32_16x16x32_f16 v[102:105], v[234:237], v[200:203], v[102:105]
	v_mfma_f32_16x16x32_f16 v[98:101], v[242:245], v[200:203], v[98:101]
	v_mfma_f32_16x16x32_f16 v[86:89], v[234:237], v[208:211], v[86:89]
	v_mfma_f32_16x16x32_f16 v[82:85], v[242:245], v[208:211], v[82:85]
	v_mfma_f32_16x16x32_f16 v[70:73], v[234:237], v[216:219], v[70:73]
	v_mfma_f32_16x16x32_f16 v[66:69], v[242:245], v[216:219], v[66:69]
	s_setprio 0
	s_mov_b32 m0, s25
	v_lshl_add_u64 v[228:229], v[228:229], 0, s[84:85]
	s_barrier
	ds_read_b128 v[146:149], v198 offset:49152
	ds_read_b128 v[192:195], v198 offset:51200
	ds_read_b128 v[204:207], v198 offset:53248
	ds_read_b128 v[212:215], v198 offset:55296
	ds_read_b128 v[150:153], v198 offset:50176
	ds_read_b128 v[200:203], v198 offset:52224
	ds_read_b128 v[208:211], v198 offset:54272
	ds_read_b128 v[216:219], v198 offset:56320
	global_load_lds_dwordx4 v[228:229], off
	v_lshl_add_u64 v[222:223], v[222:223], 0, s[84:85]
	s_mov_b32 m0, s27
	s_nop 0
	global_load_lds_dwordx4 v[222:223], off
	s_barrier
	s_waitcnt lgkmcnt(7)
	s_setprio 1
	v_mfma_f32_16x16x32_f16 v[62:65], v[122:125], v[146:149], v[62:65]
	v_mfma_f32_16x16x32_f16 v[58:61], v[138:141], v[146:149], v[58:61]
	s_waitcnt lgkmcnt(6)
	v_mfma_f32_16x16x32_f16 v[46:49], v[122:125], v[192:195], v[46:49]
	v_mfma_f32_16x16x32_f16 v[42:45], v[138:141], v[192:195], v[42:45]
	s_waitcnt lgkmcnt(5)
	v_mfma_f32_16x16x32_f16 v[28:31], v[122:125], v[204:207], v[28:31]
	v_mfma_f32_16x16x32_f16 v[24:27], v[138:141], v[204:207], v[24:27]
	s_waitcnt lgkmcnt(4)
	v_mfma_f32_16x16x32_f16 v[12:15], v[122:125], v[212:215], v[12:15]
	v_mfma_f32_16x16x32_f16 v[8:11], v[138:141], v[212:215], v[8:11]
	s_waitcnt lgkmcnt(3)
	v_mfma_f32_16x16x32_f16 v[62:65], v[130:133], v[150:153], v[62:65]
	v_mfma_f32_16x16x32_f16 v[58:61], v[142:145], v[150:153], v[58:61]
	s_waitcnt lgkmcnt(2)
	v_mfma_f32_16x16x32_f16 v[46:49], v[130:133], v[200:203], v[46:49]
	v_mfma_f32_16x16x32_f16 v[42:45], v[142:145], v[200:203], v[42:45]
	s_waitcnt lgkmcnt(1)
	v_mfma_f32_16x16x32_f16 v[28:31], v[130:133], v[208:211], v[28:31]
	v_mfma_f32_16x16x32_f16 v[24:27], v[142:145], v[208:211], v[24:27]
	s_waitcnt lgkmcnt(0)
	v_mfma_f32_16x16x32_f16 v[12:15], v[130:133], v[216:219], v[12:15]
	v_mfma_f32_16x16x32_f16 v[8:11], v[142:145], v[216:219], v[8:11]
	s_setprio 0
	s_barrier
	s_add_u32 s10, s14, 0x40080
	s_addc_u32 s11, s15, 0
	s_add_i32 s14, s16, s20
	v_lshl_add_u64 v[122:123], s[10:11], 0, v[32:33]
	s_mov_b32 m0, s14
	s_nop 0
	global_load_lds_dwordx4 v[122:123], off
	v_lshl_add_u64 v[122:123], s[10:11], 0, v[154:155]
	s_add_i32 m0, s14, 0x2000
	s_nop 0
	global_load_lds_dwordx4 v[122:123], off
	s_waitcnt vmcnt(6)
	s_barrier
	s_setprio 1
	v_mfma_f32_16x16x32_f16 v[54:57], v[230:233], v[146:149], v[54:57]
	v_mfma_f32_16x16x32_f16 v[50:53], v[238:241], v[146:149], v[50:53]
	v_mfma_f32_16x16x32_f16 v[38:41], v[230:233], v[192:195], v[38:41]
	v_mfma_f32_16x16x32_f16 v[34:37], v[238:241], v[192:195], v[34:37]
	v_mfma_f32_16x16x32_f16 v[20:23], v[230:233], v[204:207], v[20:23]
	v_mfma_f32_16x16x32_f16 v[16:19], v[238:241], v[204:207], v[16:19]
	v_mfma_f32_16x16x32_f16 v[4:7], v[230:233], v[212:215], v[4:7]
	v_mfma_f32_16x16x32_f16 v[0:3], v[238:241], v[212:215], v[0:3]
	v_mfma_f32_16x16x32_f16 v[54:57], v[234:237], v[150:153], v[54:57]
	v_mfma_f32_16x16x32_f16 v[50:53], v[242:245], v[150:153], v[50:53]
	v_mfma_f32_16x16x32_f16 v[38:41], v[234:237], v[200:203], v[38:41]
	v_mfma_f32_16x16x32_f16 v[34:37], v[242:245], v[200:203], v[34:37]
	v_mfma_f32_16x16x32_f16 v[20:23], v[234:237], v[208:211], v[20:23]
	v_mfma_f32_16x16x32_f16 v[16:19], v[242:245], v[208:211], v[16:19]
	v_mfma_f32_16x16x32_f16 v[4:7], v[234:237], v[216:219], v[4:7]
	v_mfma_f32_16x16x32_f16 v[0:3], v[242:245], v[216:219], v[0:3]
	s_setprio 0
	s_add_i32 s37, s37, 2
	s_add_u32 s35, s35, 0x100
	s_addc_u32 s36, s36, 0
	s_cmp_gt_u32 s37, 13
	s_mov_b64 s[10:11], s[12:13]
	s_barrier
	s_cbranch_scc0 .LBB0_958
	s_cmp_eq_u32 s34, 2
	s_movk_i32 s6, 0x2800
	v_lshl_or_b32 v122, s31, 8, v197
	s_cselect_b32 s6, 0x2000, s6
	s_mov_b32 s7, 0x23a3c000
	s_cselect_b32 s8, s7, 0x23abc000
	s_add_u32 s6, s70, s6
	v_ashrrev_i32_e32 v123, 31, v122
	s_addc_u32 s7, s71, 0
	v_lshlrev_b64 v[192:193], 1, v[122:123]
	v_lshl_add_u64 v[194:195], s[6:7], 0, v[192:193]
	v_lshl_add_u64 v[122:123], v[194:195], 0, v[156:157]
	v_lshl_add_u64 v[124:125], v[194:195], 0, v[158:159]
	v_lshl_add_u64 v[130:131], v[194:195], 0, v[160:161]
	v_lshl_add_u64 v[208:209], v[194:195], 0, v[162:163]
	global_load_dwordx4 v[200:203], v[122:123], off
	global_load_dwordx4 v[204:207], v[122:123], off offset:256
	global_load_dwordx4 v[150:153], v[124:125], off
	global_load_dwordx4 v[146:149], v[124:125], off offset:256
	global_load_dwordx4 v[142:145], v[130:131], off
	global_load_dwordx4 v[138:141], v[130:131], off offset:256
	s_nop 0
	global_load_dwordx4 v[130:133], v[208:209], off
	global_load_dwordx4 v[122:125], v[208:209], off offset:256
	v_readlane_b32 s36, v252, 26
	v_readlane_b32 s42, v252, 32
	v_readlane_b32 s43, v252, 33
	s_add_u32 s6, s42, s8
	s_addc_u32 s7, s43, 0
	v_readlane_b32 s37, v252, 27
	v_readlane_b32 s38, v252, 28
	v_readlane_b32 s39, v252, 29
	v_readlane_b32 s40, v252, 30
	v_readlane_b32 s41, v252, 31
	v_lshl_add_u64 v[192:193], s[6:7], 0, v[192:193]
	s_waitcnt vmcnt(0)
	v_cvt_f32_f16_e32 v199, v200
	v_cvt_f32_f16_sdwa v200, v200 dst_sel:DWORD dst_unused:UNUSED_PAD src0_sel:WORD_1
	v_cvt_f32_f16_e32 v210, v201
	v_lshl_add_u64 v[208:209], v[192:193], 0, v[164:165]
	v_max_f32_e32 v199, 0xc1f00000, v199
	v_mul_f32_e32 v199, 0xbfb8aa3b, v199
	v_exp_f32_e32 v199, v199
	v_max_f32_e32 v200, 0xc1f00000, v200
	v_max_f32_e32 v210, 0xc1f00000, v210
	v_mul_f32_e32 v200, 0xbfb8aa3b, v200
	v_add_f32_e32 v199, 1.0, v199
	v_rcp_f32_e32 v199, v199
	v_exp_f32_e32 v200, v200
	v_mul_f32_e32 v210, 0xbfb8aa3b, v210
	v_exp_f32_e32 v211, v210
	v_fma_mixlo_f16 v199, v134, v199, 0
	v_add_f32_e32 v134, 1.0, v200
	v_rcp_f32_e32 v210, v134
	v_add_f32_e32 v134, 1.0, v211
	v_cvt_f32_f16_sdwa v200, v201 dst_sel:DWORD dst_unused:UNUSED_PAD src0_sel:WORD_1
	v_rcp_f32_e32 v211, v134
	v_mov_b32_e32 v134, v135
	v_mov_b32_e32 v135, v136
	v_cvt_f32_f16_e32 v136, v202
	v_max_f32_e32 v200, 0xc1f00000, v200
	v_mul_f32_e32 v200, 0xbfb8aa3b, v200
	v_exp_f32_e32 v200, v200
	v_max_f32_e32 v136, 0xc1f00000, v136
	v_mul_f32_e32 v136, 0xbfb8aa3b, v136
	v_exp_f32_e32 v136, v136
	v_pk_mul_f32 v[134:135], v[134:135], v[210:211]
	s_nop 0
	v_cvt_pk_f16_f32 v135, v134, v135
	v_add_f32_e32 v134, 1.0, v200
	v_rcp_f32_e32 v200, v134
	v_add_f32_e32 v134, 1.0, v136
	v_rcp_f32_e32 v201, v134
	v_pk_mov_b32 v[136:137], v[136:137], v[126:127] op_sel:[1,0]
	v_cvt_f32_f16_sdwa v126, v202 dst_sel:DWORD dst_unused:UNUSED_PAD src0_sel:WORD_1
	v_pack_b32_f16 v134, v199, v135
	v_pk_mul_f32 v[136:137], v[136:137], v[200:201]
	v_cvt_f32_f16_sdwa v200, v203 dst_sel:DWORD dst_unused:UNUSED_PAD src0_sel:WORD_1
	v_cvt_pk_f16_f32 v199, v136, v137
	v_cvt_f32_f16_e32 v136, v203
	v_max_f32_e32 v126, 0xc1f00000, v126
	v_mul_f32_e32 v126, 0xbfb8aa3b, v126
	v_exp_f32_e32 v126, v126
	v_max_f32_e32 v136, 0xc1f00000, v136
	v_mul_f32_e32 v136, 0xbfb8aa3b, v136
	v_exp_f32_e32 v137, v136
	v_add_f32_e32 v126, 1.0, v126
	v_rcp_f32_e32 v136, v126
	v_alignbit_b32 v135, v199, v135, 16
	v_add_f32_e32 v126, 1.0, v137
	v_rcp_f32_e32 v137, v126
	v_mov_b32_e32 v126, v127
	v_mov_b32_e32 v127, v128
	v_cvt_f32_f16_e32 v128, v204
	v_pk_mul_f32 v[126:127], v[126:127], v[136:137]
	s_nop 0
	v_cvt_pk_f16_f32 v126, v126, v127
	v_max_f32_e32 v127, 0xc1f00000, v200
	v_mul_f32_e32 v127, 0xbfb8aa3b, v127
	v_exp_f32_e32 v127, v127
	v_alignbit_b32 v136, v126, v199, 16
	v_lshrrev_b32_e32 v137, 16, v126
	v_add_f32_e32 v126, 1.0, v127
	v_rcp_f32_e32 v126, v126
	v_max_f32_e32 v127, 0xc1f00000, v128
	v_mul_f32_e32 v127, 0xbfb8aa3b, v127
	v_exp_f32_e32 v127, v127
	v_fma_mixhi_f16 v137, v129, v126, 0
	v_cvt_f32_f16_sdwa v126, v204 dst_sel:DWORD dst_unused:UNUSED_PAD src0_sel:WORD_1
	v_cvt_f32_f16_e32 v128, v205
	v_add_f32_e32 v127, 1.0, v127
	v_rcp_f32_e32 v127, v127
	v_max_f32_e32 v126, 0xc1f00000, v126
	v_mul_f32_e32 v126, 0xbfb8aa3b, v126
	v_max_f32_e32 v128, 0xc1f00000, v128
	v_exp_f32_e32 v126, v126
	v_mul_f32_e32 v128, 0xbfb8aa3b, v128
	v_exp_f32_e32 v128, v128
	v_fma_mixlo_f16 v129, v118, v127, 0
	v_add_f32_e32 v118, 1.0, v126
	v_rcp_f32_e32 v126, v118
	v_add_f32_e32 v118, 1.0, v128
	v_rcp_f32_e32 v127, v118
	v_cvt_f32_f16_sdwa v128, v205 dst_sel:DWORD dst_unused:UNUSED_PAD src0_sel:WORD_1
	v_mov_b32_e32 v118, v119
	v_mov_b32_e32 v119, v120
	v_cvt_f32_f16_e32 v120, v206
	v_max_f32_e32 v128, 0xc1f00000, v128
	v_mul_f32_e32 v128, 0xbfb8aa3b, v128
	v_exp_f32_e32 v128, v128
	v_max_f32_e32 v120, 0xc1f00000, v120
	v_mul_f32_e32 v120, 0xbfb8aa3b, v120
	v_exp_f32_e32 v120, v120
	v_pk_mul_f32 v[118:119], v[118:119], v[126:127]
	v_add_f32_e32 v126, 1.0, v128
	v_rcp_f32_e32 v126, v126
	v_add_f32_e32 v120, 1.0, v120
	v_rcp_f32_e32 v127, v120
	v_pk_mov_b32 v[120:121], v[120:121], v[114:115] op_sel:[1,0]
	v_cvt_f32_f16_sdwa v114, v206 dst_sel:DWORD dst_unused:UNUSED_PAD src0_sel:WORD_1
	v_cvt_pk_f16_f32 v119, v118, v119
	v_pk_mul_f32 v[120:121], v[120:121], v[126:127]
	v_cvt_f32_f16_sdwa v127, v207 dst_sel:DWORD dst_unused:UNUSED_PAD src0_sel:WORD_1
	v_cvt_pk_f16_f32 v126, v120, v121
	v_cvt_f32_f16_e32 v120, v207
	v_max_f32_e32 v114, 0xc1f00000, v114
	v_mul_f32_e32 v114, 0xbfb8aa3b, v114
	v_exp_f32_e32 v114, v114
	v_max_f32_e32 v120, 0xc1f00000, v120
	v_mul_f32_e32 v120, 0xbfb8aa3b, v120
	v_exp_f32_e32 v121, v120
	v_add_f32_e32 v114, 1.0, v114
	v_rcp_f32_e32 v120, v114
	v_pack_b32_f16 v118, v129, v119
	v_add_f32_e32 v114, 1.0, v121
	v_rcp_f32_e32 v121, v114
	v_mov_b32_e32 v114, v115
	v_max_f32_e32 v115, 0xc1f00000, v127
	v_mul_f32_e32 v115, 0xbfb8aa3b, v115
	v_exp_f32_e32 v127, v115
	v_mov_b32_e32 v115, v116
	v_pk_mul_f32 v[114:115], v[114:115], v[120:121]
	v_cvt_f32_f16_e32 v116, v150
	v_cvt_pk_f16_f32 v114, v114, v115
	v_add_f32_e32 v115, 1.0, v127
	v_rcp_f32_e32 v115, v115
	v_alignbit_b32 v120, v114, v126, 16
	v_lshrrev_b32_e32 v121, 16, v114
	v_max_f32_e32 v114, 0xc1f00000, v116
	v_alignbit_b32 v119, v126, v119, 16
	v_fma_mixhi_f16 v121, v117, v115, 0
	v_mul_f32_e32 v114, 0xbfb8aa3b, v114
	v_cvt_f32_f16_sdwa v117, v150 dst_sel:DWORD dst_unused:UNUSED_PAD src0_sel:WORD_1
	v_exp_f32_e32 v116, v114
	global_store_dwordx4 v[208:209], v[118:121], off offset:256
	v_lshl_add_u64 v[114:115], v[192:193], 0, v[166:167]
	v_max_f32_e32 v117, 0xc1f00000, v117
	v_cvt_f32_f16_e32 v118, v151
	v_add_f32_e32 v116, 1.0, v116
	v_mul_f32_e32 v117, 0xbfb8aa3b, v117
	v_rcp_f32_e32 v116, v116
	v_max_f32_e32 v118, 0xc1f00000, v118
	v_exp_f32_e32 v117, v117
	v_mul_f32_e32 v118, 0xbfb8aa3b, v118
	v_exp_f32_e32 v118, v118
	v_fma_mixlo_f16 v119, v110, v116, 0
	v_add_f32_e32 v110, 1.0, v117
	v_rcp_f32_e32 v116, v110
	v_add_f32_e32 v110, 1.0, v118
	v_rcp_f32_e32 v117, v110
	v_cvt_f32_f16_sdwa v118, v151 dst_sel:DWORD dst_unused:UNUSED_PAD src0_sel:WORD_1
	v_mov_b32_e32 v110, v111
	v_mov_b32_e32 v111, v112
	v_cvt_f32_f16_e32 v112, v152
	v_pk_mul_f32 v[110:111], v[110:111], v[116:117]
	v_max_f32_e32 v116, 0xc1f00000, v118
	v_mul_f32_e32 v116, 0xbfb8aa3b, v116
	v_max_f32_e32 v112, 0xc1f00000, v112
	v_exp_f32_e32 v116, v116
	v_mul_f32_e32 v112, 0xbfb8aa3b, v112
	v_exp_f32_e32 v112, v112
	v_cvt_pk_f16_f32 v111, v110, v111
	v_add_f32_e32 v110, 1.0, v116
	v_rcp_f32_e32 v116, v110
	v_add_f32_e32 v110, 1.0, v112
	v_rcp_f32_e32 v117, v110
	v_pk_mov_b32 v[112:113], v[112:113], v[106:107] op_sel:[1,0]
	v_cvt_f32_f16_sdwa v106, v152 dst_sel:DWORD dst_unused:UNUSED_PAD src0_sel:WORD_1
	v_pack_b32_f16 v110, v119, v111
	v_pk_mul_f32 v[112:113], v[112:113], v[116:117]
	v_cvt_f32_f16_sdwa v117, v153 dst_sel:DWORD dst_unused:UNUSED_PAD src0_sel:WORD_1
	v_cvt_pk_f16_f32 v116, v112, v113
	v_cvt_f32_f16_e32 v112, v153
	v_max_f32_e32 v106, 0xc1f00000, v106
	v_mul_f32_e32 v106, 0xbfb8aa3b, v106
	v_exp_f32_e32 v106, v106
	v_max_f32_e32 v112, 0xc1f00000, v112
	v_mul_f32_e32 v112, 0xbfb8aa3b, v112
	v_exp_f32_e32 v113, v112
	v_add_f32_e32 v106, 1.0, v106
	v_rcp_f32_e32 v112, v106
	v_alignbit_b32 v111, v116, v111, 16
	v_add_f32_e32 v106, 1.0, v113
	v_rcp_f32_e32 v113, v106
	v_mov_b32_e32 v106, v107
	v_mov_b32_e32 v107, v108
	v_cvt_f32_f16_e32 v108, v146
	v_pk_mul_f32 v[106:107], v[106:107], v[112:113]
	global_store_dwordx4 v[208:209], v[134:137], off
	v_cvt_pk_f16_f32 v106, v106, v107
	v_max_f32_e32 v107, 0xc1f00000, v117
	v_mul_f32_e32 v107, 0xbfb8aa3b, v107
	v_exp_f32_e32 v107, v107
	v_alignbit_b32 v112, v106, v116, 16
	v_lshrrev_b32_e32 v113, 16, v106
	v_add_f32_e32 v106, 1.0, v107
	v_rcp_f32_e32 v106, v106
	v_max_f32_e32 v107, 0xc1f00000, v108
	v_mul_f32_e32 v107, 0xbfb8aa3b, v107
	v_exp_f32_e32 v107, v107
	v_fma_mixhi_f16 v113, v109, v106, 0
	v_cvt_f32_f16_sdwa v106, v146 dst_sel:DWORD dst_unused:UNUSED_PAD src0_sel:WORD_1
	v_cvt_f32_f16_e32 v108, v147
	v_add_f32_e32 v107, 1.0, v107
	v_rcp_f32_e32 v107, v107
	v_max_f32_e32 v106, 0xc1f00000, v106
	v_mul_f32_e32 v106, 0xbfb8aa3b, v106
	v_max_f32_e32 v108, 0xc1f00000, v108
	v_exp_f32_e32 v106, v106
	v_mul_f32_e32 v108, 0xbfb8aa3b, v108
	v_exp_f32_e32 v108, v108
	v_fma_mixlo_f16 v109, v102, v107, 0
	v_add_f32_e32 v102, 1.0, v106
	v_rcp_f32_e32 v106, v102
	v_add_f32_e32 v102, 1.0, v108
	v_rcp_f32_e32 v107, v102
	v_cvt_f32_f16_sdwa v108, v147 dst_sel:DWORD dst_unused:UNUSED_PAD src0_sel:WORD_1
	v_mov_b32_e32 v102, v103
	v_mov_b32_e32 v103, v104
	v_cvt_f32_f16_e32 v104, v148
	v_max_f32_e32 v108, 0xc1f00000, v108
	v_mul_f32_e32 v108, 0xbfb8aa3b, v108
	v_exp_f32_e32 v108, v108
	v_max_f32_e32 v104, 0xc1f00000, v104
	v_mul_f32_e32 v104, 0xbfb8aa3b, v104
	v_exp_f32_e32 v104, v104
	v_pk_mul_f32 v[102:103], v[102:103], v[106:107]
	v_add_f32_e32 v106, 1.0, v108
	v_rcp_f32_e32 v106, v106
	v_add_f32_e32 v104, 1.0, v104
	v_rcp_f32_e32 v107, v104
	v_pk_mov_b32 v[104:105], v[104:105], v[98:99] op_sel:[1,0]
	v_cvt_f32_f16_sdwa v98, v148 dst_sel:DWORD dst_unused:UNUSED_PAD src0_sel:WORD_1
	v_cvt_pk_f16_f32 v103, v102, v103
	v_pk_mul_f32 v[104:105], v[104:105], v[106:107]
	v_cvt_f32_f16_sdwa v107, v149 dst_sel:DWORD dst_unused:UNUSED_PAD src0_sel:WORD_1
	v_cvt_pk_f16_f32 v106, v104, v105
	v_cvt_f32_f16_e32 v104, v149
	v_max_f32_e32 v98, 0xc1f00000, v98
	v_mul_f32_e32 v98, 0xbfb8aa3b, v98
	v_exp_f32_e32 v98, v98
	v_max_f32_e32 v104, 0xc1f00000, v104
	v_mul_f32_e32 v104, 0xbfb8aa3b, v104
	v_exp_f32_e32 v105, v104
	v_add_f32_e32 v98, 1.0, v98
	v_rcp_f32_e32 v104, v98
	v_pack_b32_f16 v102, v109, v103
	v_add_f32_e32 v98, 1.0, v105
	v_rcp_f32_e32 v105, v98
	v_mov_b32_e32 v98, v99
	v_max_f32_e32 v99, 0xc1f00000, v107
	v_mul_f32_e32 v99, 0xbfb8aa3b, v99
	v_exp_f32_e32 v107, v99
	v_mov_b32_e32 v99, v100
	v_pk_mul_f32 v[98:99], v[98:99], v[104:105]
	v_cvt_f32_f16_e32 v100, v142
	v_cvt_pk_f16_f32 v98, v98, v99
	v_add_f32_e32 v99, 1.0, v107
	v_rcp_f32_e32 v99, v99
	v_alignbit_b32 v104, v98, v106, 16
	v_lshrrev_b32_e32 v105, 16, v98
	v_max_f32_e32 v98, 0xc1f00000, v100
	v_alignbit_b32 v103, v106, v103, 16
	v_fma_mixhi_f16 v105, v101, v99, 0
	v_mul_f32_e32 v98, 0xbfb8aa3b, v98
	v_cvt_f32_f16_sdwa v101, v142 dst_sel:DWORD dst_unused:UNUSED_PAD src0_sel:WORD_1
	v_exp_f32_e32 v100, v98
	global_store_dwordx4 v[114:115], v[102:105], off offset:256
	v_lshl_add_u64 v[98:99], v[192:193], 0, v[168:169]
	v_max_f32_e32 v101, 0xc1f00000, v101
	v_cvt_f32_f16_e32 v102, v143
	v_add_f32_e32 v100, 1.0, v100
	v_mul_f32_e32 v101, 0xbfb8aa3b, v101
	v_rcp_f32_e32 v100, v100
	v_max_f32_e32 v102, 0xc1f00000, v102
	v_exp_f32_e32 v101, v101
	v_mul_f32_e32 v102, 0xbfb8aa3b, v102
	v_exp_f32_e32 v102, v102
	v_fma_mixlo_f16 v103, v94, v100, 0
	v_add_f32_e32 v94, 1.0, v101
	v_rcp_f32_e32 v100, v94
	v_add_f32_e32 v94, 1.0, v102
	v_rcp_f32_e32 v101, v94
	v_cvt_f32_f16_sdwa v102, v143 dst_sel:DWORD dst_unused:UNUSED_PAD src0_sel:WORD_1
	v_mov_b32_e32 v94, v95
	v_mov_b32_e32 v95, v96
	v_cvt_f32_f16_e32 v96, v144
	v_pk_mul_f32 v[94:95], v[94:95], v[100:101]
	v_max_f32_e32 v100, 0xc1f00000, v102
	v_mul_f32_e32 v100, 0xbfb8aa3b, v100
	v_max_f32_e32 v96, 0xc1f00000, v96
	v_exp_f32_e32 v100, v100
	v_mul_f32_e32 v96, 0xbfb8aa3b, v96
	v_exp_f32_e32 v96, v96
	v_cvt_pk_f16_f32 v95, v94, v95
	v_add_f32_e32 v94, 1.0, v100
	v_rcp_f32_e32 v100, v94
	v_add_f32_e32 v94, 1.0, v96
	v_rcp_f32_e32 v101, v94
	v_pk_mov_b32 v[96:97], v[96:97], v[90:91] op_sel:[1,0]
	v_cvt_f32_f16_sdwa v90, v144 dst_sel:DWORD dst_unused:UNUSED_PAD src0_sel:WORD_1
	v_pack_b32_f16 v94, v103, v95
	v_pk_mul_f32 v[96:97], v[96:97], v[100:101]
	v_cvt_f32_f16_sdwa v101, v145 dst_sel:DWORD dst_unused:UNUSED_PAD src0_sel:WORD_1
	v_cvt_pk_f16_f32 v100, v96, v97
	v_cvt_f32_f16_e32 v96, v145
	v_max_f32_e32 v90, 0xc1f00000, v90
	v_mul_f32_e32 v90, 0xbfb8aa3b, v90
	v_exp_f32_e32 v90, v90
	v_max_f32_e32 v96, 0xc1f00000, v96
	v_mul_f32_e32 v96, 0xbfb8aa3b, v96
	v_exp_f32_e32 v97, v96
	v_add_f32_e32 v90, 1.0, v90
	v_rcp_f32_e32 v96, v90
	v_alignbit_b32 v95, v100, v95, 16
	v_add_f32_e32 v90, 1.0, v97
	v_rcp_f32_e32 v97, v90
	v_mov_b32_e32 v90, v91
	v_mov_b32_e32 v91, v92
	v_cvt_f32_f16_e32 v92, v138
	v_pk_mul_f32 v[90:91], v[90:91], v[96:97]
	global_store_dwordx4 v[114:115], v[110:113], off
	v_cvt_pk_f16_f32 v90, v90, v91
	v_max_f32_e32 v91, 0xc1f00000, v101
	v_mul_f32_e32 v91, 0xbfb8aa3b, v91
	v_exp_f32_e32 v91, v91
	v_alignbit_b32 v96, v90, v100, 16
	v_lshrrev_b32_e32 v97, 16, v90
	v_add_f32_e32 v90, 1.0, v91
	v_rcp_f32_e32 v90, v90
	v_max_f32_e32 v91, 0xc1f00000, v92
	v_mul_f32_e32 v91, 0xbfb8aa3b, v91
	v_exp_f32_e32 v91, v91
	v_fma_mixhi_f16 v97, v93, v90, 0
	v_cvt_f32_f16_sdwa v90, v138 dst_sel:DWORD dst_unused:UNUSED_PAD src0_sel:WORD_1
	v_cvt_f32_f16_e32 v92, v139
	v_add_f32_e32 v91, 1.0, v91
	v_rcp_f32_e32 v91, v91
	v_max_f32_e32 v90, 0xc1f00000, v90
	v_mul_f32_e32 v90, 0xbfb8aa3b, v90
	v_max_f32_e32 v92, 0xc1f00000, v92
	v_exp_f32_e32 v90, v90
	v_mul_f32_e32 v92, 0xbfb8aa3b, v92
	v_exp_f32_e32 v92, v92
	v_fma_mixlo_f16 v93, v86, v91, 0
	v_add_f32_e32 v86, 1.0, v90
	v_rcp_f32_e32 v90, v86
	v_add_f32_e32 v86, 1.0, v92
	v_rcp_f32_e32 v91, v86
	v_cvt_f32_f16_sdwa v92, v139 dst_sel:DWORD dst_unused:UNUSED_PAD src0_sel:WORD_1
	v_mov_b32_e32 v86, v87
	v_mov_b32_e32 v87, v88
	v_cvt_f32_f16_e32 v88, v140
	v_max_f32_e32 v92, 0xc1f00000, v92
	v_mul_f32_e32 v92, 0xbfb8aa3b, v92
	v_exp_f32_e32 v92, v92
	v_max_f32_e32 v88, 0xc1f00000, v88
	v_mul_f32_e32 v88, 0xbfb8aa3b, v88
	v_exp_f32_e32 v88, v88
	v_pk_mul_f32 v[86:87], v[86:87], v[90:91]
	v_add_f32_e32 v90, 1.0, v92
	v_rcp_f32_e32 v90, v90
	v_add_f32_e32 v88, 1.0, v88
	v_rcp_f32_e32 v91, v88
	v_pk_mov_b32 v[88:89], v[88:89], v[82:83] op_sel:[1,0]
	v_cvt_f32_f16_sdwa v82, v140 dst_sel:DWORD dst_unused:UNUSED_PAD src0_sel:WORD_1
	v_cvt_pk_f16_f32 v87, v86, v87
	v_pk_mul_f32 v[88:89], v[88:89], v[90:91]
	v_cvt_f32_f16_sdwa v91, v141 dst_sel:DWORD dst_unused:UNUSED_PAD src0_sel:WORD_1
	v_cvt_pk_f16_f32 v90, v88, v89
	v_cvt_f32_f16_e32 v88, v141
	v_max_f32_e32 v82, 0xc1f00000, v82
	v_mul_f32_e32 v82, 0xbfb8aa3b, v82
	v_exp_f32_e32 v82, v82
	v_max_f32_e32 v88, 0xc1f00000, v88
	v_mul_f32_e32 v88, 0xbfb8aa3b, v88
	v_exp_f32_e32 v89, v88
	v_add_f32_e32 v82, 1.0, v82
	v_rcp_f32_e32 v88, v82
	v_pack_b32_f16 v86, v93, v87
	v_add_f32_e32 v82, 1.0, v89
	v_rcp_f32_e32 v89, v82
	v_mov_b32_e32 v82, v83
	v_max_f32_e32 v83, 0xc1f00000, v91
	v_mul_f32_e32 v83, 0xbfb8aa3b, v83
	v_exp_f32_e32 v91, v83
	v_mov_b32_e32 v83, v84
	v_pk_mul_f32 v[82:83], v[82:83], v[88:89]
	v_cvt_f32_f16_e32 v84, v130
	v_cvt_pk_f16_f32 v82, v82, v83
	v_add_f32_e32 v83, 1.0, v91
	v_rcp_f32_e32 v83, v83
	v_alignbit_b32 v88, v82, v90, 16
	v_lshrrev_b32_e32 v89, 16, v82
	v_max_f32_e32 v82, 0xc1f00000, v84
	v_alignbit_b32 v87, v90, v87, 16
	v_fma_mixhi_f16 v89, v85, v83, 0
	v_mul_f32_e32 v82, 0xbfb8aa3b, v82
	v_cvt_f32_f16_sdwa v85, v130 dst_sel:DWORD dst_unused:UNUSED_PAD src0_sel:WORD_1
	v_exp_f32_e32 v84, v82
	global_store_dwordx4 v[98:99], v[86:89], off offset:256
	v_lshl_add_u64 v[82:83], v[192:193], 0, v[170:171]
	v_max_f32_e32 v85, 0xc1f00000, v85
	v_cvt_f32_f16_e32 v86, v131
	v_add_f32_e32 v84, 1.0, v84
	v_mul_f32_e32 v85, 0xbfb8aa3b, v85
	v_rcp_f32_e32 v84, v84
	v_max_f32_e32 v86, 0xc1f00000, v86
	v_exp_f32_e32 v85, v85
	v_mul_f32_e32 v86, 0xbfb8aa3b, v86
	v_exp_f32_e32 v86, v86
	v_fma_mixlo_f16 v87, v78, v84, 0
	v_add_f32_e32 v78, 1.0, v85
	v_rcp_f32_e32 v84, v78
	v_add_f32_e32 v78, 1.0, v86
	v_rcp_f32_e32 v85, v78
	v_cvt_f32_f16_sdwa v86, v131 dst_sel:DWORD dst_unused:UNUSED_PAD src0_sel:WORD_1
	v_mov_b32_e32 v78, v79
	v_mov_b32_e32 v79, v80
	v_cvt_f32_f16_e32 v80, v132
	v_pk_mul_f32 v[78:79], v[78:79], v[84:85]
	v_max_f32_e32 v84, 0xc1f00000, v86
	v_mul_f32_e32 v84, 0xbfb8aa3b, v84
	v_max_f32_e32 v80, 0xc1f00000, v80
	v_exp_f32_e32 v84, v84
	v_mul_f32_e32 v80, 0xbfb8aa3b, v80
	v_exp_f32_e32 v80, v80
	v_cvt_pk_f16_f32 v79, v78, v79
	v_add_f32_e32 v78, 1.0, v84
	v_rcp_f32_e32 v84, v78
	v_add_f32_e32 v78, 1.0, v80
	v_rcp_f32_e32 v85, v78
	v_pk_mov_b32 v[80:81], v[80:81], v[74:75] op_sel:[1,0]
	v_cvt_f32_f16_sdwa v74, v132 dst_sel:DWORD dst_unused:UNUSED_PAD src0_sel:WORD_1
	v_pack_b32_f16 v78, v87, v79
	v_pk_mul_f32 v[80:81], v[80:81], v[84:85]
	v_cvt_f32_f16_sdwa v85, v133 dst_sel:DWORD dst_unused:UNUSED_PAD src0_sel:WORD_1
	v_cvt_pk_f16_f32 v84, v80, v81
	v_cvt_f32_f16_e32 v80, v133
	v_max_f32_e32 v74, 0xc1f00000, v74
	v_mul_f32_e32 v74, 0xbfb8aa3b, v74
	v_exp_f32_e32 v74, v74
	v_max_f32_e32 v80, 0xc1f00000, v80
	v_mul_f32_e32 v80, 0xbfb8aa3b, v80
	v_exp_f32_e32 v81, v80
	v_add_f32_e32 v74, 1.0, v74
	v_rcp_f32_e32 v80, v74
	v_alignbit_b32 v79, v84, v79, 16
	v_add_f32_e32 v74, 1.0, v81
	v_rcp_f32_e32 v81, v74
	v_mov_b32_e32 v74, v75
	v_mov_b32_e32 v75, v76
	v_cvt_f32_f16_e32 v76, v122
	v_pk_mul_f32 v[74:75], v[74:75], v[80:81]
	global_store_dwordx4 v[98:99], v[94:97], off
	v_cvt_pk_f16_f32 v74, v74, v75
	v_max_f32_e32 v75, 0xc1f00000, v85
	v_mul_f32_e32 v75, 0xbfb8aa3b, v75
	v_exp_f32_e32 v75, v75
	v_alignbit_b32 v80, v74, v84, 16
	v_lshrrev_b32_e32 v81, 16, v74
	v_add_f32_e32 v74, 1.0, v75
	v_rcp_f32_e32 v74, v74
	v_max_f32_e32 v75, 0xc1f00000, v76
	v_mul_f32_e32 v75, 0xbfb8aa3b, v75
	v_exp_f32_e32 v75, v75
	v_fma_mixhi_f16 v81, v77, v74, 0
	v_cvt_f32_f16_sdwa v74, v122 dst_sel:DWORD dst_unused:UNUSED_PAD src0_sel:WORD_1
	v_cvt_f32_f16_e32 v76, v123
	v_add_f32_e32 v75, 1.0, v75
	v_rcp_f32_e32 v75, v75
	v_max_f32_e32 v74, 0xc1f00000, v74
	v_mul_f32_e32 v74, 0xbfb8aa3b, v74
	v_max_f32_e32 v76, 0xc1f00000, v76
	v_exp_f32_e32 v74, v74
	v_mul_f32_e32 v76, 0xbfb8aa3b, v76
	v_exp_f32_e32 v76, v76
	v_fma_mixlo_f16 v77, v70, v75, 0
	v_add_f32_e32 v70, 1.0, v74
	v_rcp_f32_e32 v74, v70
	v_add_f32_e32 v70, 1.0, v76
	v_rcp_f32_e32 v75, v70
	v_cvt_f32_f16_sdwa v76, v123 dst_sel:DWORD dst_unused:UNUSED_PAD src0_sel:WORD_1
	v_mov_b32_e32 v70, v71
	v_mov_b32_e32 v71, v72
	v_cvt_f32_f16_e32 v72, v124
	v_max_f32_e32 v76, 0xc1f00000, v76
	v_mul_f32_e32 v76, 0xbfb8aa3b, v76
	v_exp_f32_e32 v76, v76
	v_max_f32_e32 v72, 0xc1f00000, v72
	v_mul_f32_e32 v72, 0xbfb8aa3b, v72
	v_exp_f32_e32 v72, v72
	v_pk_mul_f32 v[70:71], v[70:71], v[74:75]
	v_add_f32_e32 v74, 1.0, v76
	v_rcp_f32_e32 v74, v74
	v_add_f32_e32 v72, 1.0, v72
	v_rcp_f32_e32 v75, v72
	v_pk_mov_b32 v[72:73], v[72:73], v[66:67] op_sel:[1,0]
	v_cvt_f32_f16_sdwa v66, v124 dst_sel:DWORD dst_unused:UNUSED_PAD src0_sel:WORD_1
	v_cvt_pk_f16_f32 v71, v70, v71
	v_pk_mul_f32 v[72:73], v[72:73], v[74:75]
	v_cvt_f32_f16_sdwa v75, v125 dst_sel:DWORD dst_unused:UNUSED_PAD src0_sel:WORD_1
	v_cvt_pk_f16_f32 v74, v72, v73
	v_cvt_f32_f16_e32 v72, v125
	v_max_f32_e32 v66, 0xc1f00000, v66
	v_mul_f32_e32 v66, 0xbfb8aa3b, v66
	v_exp_f32_e32 v66, v66
	v_max_f32_e32 v72, 0xc1f00000, v72
	v_mul_f32_e32 v72, 0xbfb8aa3b, v72
	v_exp_f32_e32 v73, v72
	v_add_f32_e32 v66, 1.0, v66
	v_rcp_f32_e32 v72, v66
	v_pack_b32_f16 v70, v77, v71
	v_add_f32_e32 v66, 1.0, v73
	v_rcp_f32_e32 v73, v66
	v_max_f32_e32 v66, 0xc1f00000, v75
	v_mul_f32_e32 v66, 0xbfb8aa3b, v66
	v_exp_f32_e32 v75, v66
	v_mov_b32_e32 v66, v67
	v_mov_b32_e32 v67, v68
	v_pk_mul_f32 v[66:67], v[66:67], v[72:73]
	v_add_f32_e32 v68, 1.0, v75
	v_rcp_f32_e32 v68, v68
	v_cvt_pk_f16_f32 v66, v66, v67
	v_lshrrev_b32_e32 v73, 16, v66
	v_alignbit_b32 v71, v74, v71, 16
	v_alignbit_b32 v72, v66, v74, 16
	v_fma_mixhi_f16 v73, v69, v68, 0
	global_store_dwordx4 v[82:83], v[78:81], off
	global_store_dwordx4 v[82:83], v[70:73], off offset:256
	v_lshl_add_u64 v[66:67], v[194:195], 0, v[172:173]
	v_lshl_add_u64 v[68:69], v[194:195], 0, v[174:175]
	v_lshl_add_u64 v[70:71], v[194:195], 0, v[176:177]
	v_lshl_add_u64 v[98:99], v[194:195], 0, v[178:179]
	global_load_dwordx4 v[90:93], v[66:67], off
	global_load_dwordx4 v[94:97], v[66:67], off offset:256
	global_load_dwordx4 v[86:89], v[68:69], off
	global_load_dwordx4 v[82:85], v[68:69], off offset:256
	global_load_dwordx4 v[78:81], v[70:71], off
	global_load_dwordx4 v[74:77], v[70:71], off offset:256
	s_nop 0
	global_load_dwordx4 v[70:73], v[98:99], off
	global_load_dwordx4 v[66:69], v[98:99], off offset:256
	s_waitcnt vmcnt(0)
	v_cvt_f32_f16_e32 v100, v90
	v_cvt_f32_f16_sdwa v90, v90 dst_sel:DWORD dst_unused:UNUSED_PAD src0_sel:WORD_1
	v_cvt_f32_f16_e32 v101, v91
	v_lshl_add_u64 v[98:99], v[192:193], 0, v[180:181]
	v_max_f32_e32 v100, 0xc1f00000, v100
	v_mul_f32_e32 v100, 0xbfb8aa3b, v100
	v_exp_f32_e32 v100, v100
	v_max_f32_e32 v90, 0xc1f00000, v90
	v_max_f32_e32 v101, 0xc1f00000, v101
	v_mul_f32_e32 v90, 0xbfb8aa3b, v90
	v_add_f32_e32 v100, 1.0, v100
	v_rcp_f32_e32 v100, v100
	v_exp_f32_e32 v90, v90
	v_mul_f32_e32 v101, 0xbfb8aa3b, v101
	v_exp_f32_e32 v101, v101
	v_fma_mixlo_f16 v102, v62, v100, 0
	v_add_f32_e32 v62, 1.0, v90
	v_rcp_f32_e32 v100, v62
	v_add_f32_e32 v62, 1.0, v101
	v_cvt_f32_f16_sdwa v90, v91 dst_sel:DWORD dst_unused:UNUSED_PAD src0_sel:WORD_1
	v_rcp_f32_e32 v101, v62
	v_mov_b32_e32 v62, v63
	v_mov_b32_e32 v63, v64
	v_cvt_f32_f16_e32 v64, v92
	v_max_f32_e32 v90, 0xc1f00000, v90
	v_mul_f32_e32 v90, 0xbfb8aa3b, v90
	v_exp_f32_e32 v90, v90
	v_max_f32_e32 v64, 0xc1f00000, v64
	v_mul_f32_e32 v64, 0xbfb8aa3b, v64
	v_exp_f32_e32 v64, v64
	v_pk_mul_f32 v[62:63], v[62:63], v[100:101]
	s_nop 0
	v_cvt_pk_f16_f32 v63, v62, v63
	v_add_f32_e32 v62, 1.0, v90
	v_rcp_f32_e32 v90, v62
	v_add_f32_e32 v62, 1.0, v64
	v_rcp_f32_e32 v91, v62
	v_pk_mov_b32 v[64:65], v[64:65], v[58:59] op_sel:[1,0]
	v_cvt_f32_f16_sdwa v58, v92 dst_sel:DWORD dst_unused:UNUSED_PAD src0_sel:WORD_1
	v_pack_b32_f16 v62, v102, v63
	v_pk_mul_f32 v[64:65], v[64:65], v[90:91]
	v_cvt_f32_f16_sdwa v91, v93 dst_sel:DWORD dst_unused:UNUSED_PAD src0_sel:WORD_1
	v_cvt_pk_f16_f32 v90, v64, v65
	v_cvt_f32_f16_e32 v64, v93
	v_max_f32_e32 v58, 0xc1f00000, v58
	v_mul_f32_e32 v58, 0xbfb8aa3b, v58
	v_exp_f32_e32 v58, v58
	v_max_f32_e32 v64, 0xc1f00000, v64
	v_mul_f32_e32 v64, 0xbfb8aa3b, v64
	v_exp_f32_e32 v65, v64
	v_add_f32_e32 v58, 1.0, v58
	v_rcp_f32_e32 v64, v58
	v_alignbit_b32 v63, v90, v63, 16
	v_add_f32_e32 v58, 1.0, v65
	v_rcp_f32_e32 v65, v58
	v_mov_b32_e32 v58, v59
	v_mov_b32_e32 v59, v60
	v_cvt_f32_f16_e32 v60, v94
	v_pk_mul_f32 v[58:59], v[58:59], v[64:65]
	s_nop 0
	v_cvt_pk_f16_f32 v58, v58, v59
	v_max_f32_e32 v59, 0xc1f00000, v91
	v_mul_f32_e32 v59, 0xbfb8aa3b, v59
	v_exp_f32_e32 v59, v59
	v_alignbit_b32 v64, v58, v90, 16
	v_lshrrev_b32_e32 v65, 16, v58
	v_add_f32_e32 v58, 1.0, v59
	v_rcp_f32_e32 v58, v58
	v_max_f32_e32 v59, 0xc1f00000, v60
	v_mul_f32_e32 v59, 0xbfb8aa3b, v59
	v_exp_f32_e32 v59, v59
	v_fma_mixhi_f16 v65, v61, v58, 0
	v_cvt_f32_f16_sdwa v58, v94 dst_sel:DWORD dst_unused:UNUSED_PAD src0_sel:WORD_1
	v_cvt_f32_f16_e32 v60, v95
	v_add_f32_e32 v59, 1.0, v59
	v_rcp_f32_e32 v59, v59
	v_max_f32_e32 v58, 0xc1f00000, v58
	v_mul_f32_e32 v58, 0xbfb8aa3b, v58
	v_max_f32_e32 v60, 0xc1f00000, v60
	v_exp_f32_e32 v58, v58
	v_mul_f32_e32 v60, 0xbfb8aa3b, v60
	v_exp_f32_e32 v60, v60
	v_fma_mixlo_f16 v61, v54, v59, 0
	v_add_f32_e32 v54, 1.0, v58
	v_rcp_f32_e32 v58, v54
	v_add_f32_e32 v54, 1.0, v60
	v_rcp_f32_e32 v59, v54
	v_cvt_f32_f16_sdwa v60, v95 dst_sel:DWORD dst_unused:UNUSED_PAD src0_sel:WORD_1
	v_mov_b32_e32 v54, v55
	v_mov_b32_e32 v55, v56
	v_cvt_f32_f16_e32 v56, v96
	v_max_f32_e32 v60, 0xc1f00000, v60
	v_mul_f32_e32 v60, 0xbfb8aa3b, v60
	v_exp_f32_e32 v60, v60
	v_max_f32_e32 v56, 0xc1f00000, v56
	v_mul_f32_e32 v56, 0xbfb8aa3b, v56
	v_exp_f32_e32 v56, v56
	v_pk_mul_f32 v[54:55], v[54:55], v[58:59]
	v_add_f32_e32 v58, 1.0, v60
	v_rcp_f32_e32 v58, v58
	v_add_f32_e32 v56, 1.0, v56
	v_rcp_f32_e32 v59, v56
	v_pk_mov_b32 v[56:57], v[56:57], v[50:51] op_sel:[1,0]
	v_cvt_f32_f16_sdwa v50, v96 dst_sel:DWORD dst_unused:UNUSED_PAD src0_sel:WORD_1
	v_cvt_pk_f16_f32 v55, v54, v55
	v_pk_mul_f32 v[56:57], v[56:57], v[58:59]
	v_cvt_f32_f16_sdwa v59, v97 dst_sel:DWORD dst_unused:UNUSED_PAD src0_sel:WORD_1
	v_cvt_pk_f16_f32 v58, v56, v57
	v_cvt_f32_f16_e32 v56, v97
	v_max_f32_e32 v50, 0xc1f00000, v50
	v_mul_f32_e32 v50, 0xbfb8aa3b, v50
	v_exp_f32_e32 v50, v50
	v_max_f32_e32 v56, 0xc1f00000, v56
	v_mul_f32_e32 v56, 0xbfb8aa3b, v56
	v_exp_f32_e32 v57, v56
	v_add_f32_e32 v50, 1.0, v50
	v_rcp_f32_e32 v56, v50
	v_pack_b32_f16 v54, v61, v55
	v_add_f32_e32 v50, 1.0, v57
	v_rcp_f32_e32 v57, v50
	v_mov_b32_e32 v50, v51
	v_max_f32_e32 v51, 0xc1f00000, v59
	v_mul_f32_e32 v51, 0xbfb8aa3b, v51
	v_exp_f32_e32 v59, v51
	v_mov_b32_e32 v51, v52
	v_pk_mul_f32 v[50:51], v[50:51], v[56:57]
	v_cvt_f32_f16_e32 v52, v86
	v_cvt_pk_f16_f32 v50, v50, v51
	v_add_f32_e32 v51, 1.0, v59
	v_rcp_f32_e32 v51, v51
	v_alignbit_b32 v56, v50, v58, 16
	v_lshrrev_b32_e32 v57, 16, v50
	v_max_f32_e32 v50, 0xc1f00000, v52
	v_alignbit_b32 v55, v58, v55, 16
	v_fma_mixhi_f16 v57, v53, v51, 0
	v_mul_f32_e32 v50, 0xbfb8aa3b, v50
	v_cvt_f32_f16_sdwa v53, v86 dst_sel:DWORD dst_unused:UNUSED_PAD src0_sel:WORD_1
	v_exp_f32_e32 v52, v50
	global_store_dwordx4 v[98:99], v[54:57], off offset:256
	v_lshl_add_u64 v[50:51], v[192:193], 0, v[182:183]
	v_max_f32_e32 v53, 0xc1f00000, v53
	v_cvt_f32_f16_e32 v54, v87
	v_add_f32_e32 v52, 1.0, v52
	v_mul_f32_e32 v53, 0xbfb8aa3b, v53
	v_rcp_f32_e32 v52, v52
	v_max_f32_e32 v54, 0xc1f00000, v54
	v_exp_f32_e32 v53, v53
	v_mul_f32_e32 v54, 0xbfb8aa3b, v54
	v_exp_f32_e32 v54, v54
	v_fma_mixlo_f16 v55, v46, v52, 0
	v_add_f32_e32 v46, 1.0, v53
	v_rcp_f32_e32 v52, v46
	v_add_f32_e32 v46, 1.0, v54
	v_rcp_f32_e32 v53, v46
	v_cvt_f32_f16_sdwa v54, v87 dst_sel:DWORD dst_unused:UNUSED_PAD src0_sel:WORD_1
	v_mov_b32_e32 v46, v47
	v_mov_b32_e32 v47, v48
	v_cvt_f32_f16_e32 v48, v88
	v_pk_mul_f32 v[46:47], v[46:47], v[52:53]
	v_max_f32_e32 v52, 0xc1f00000, v54
	v_mul_f32_e32 v52, 0xbfb8aa3b, v52
	v_max_f32_e32 v48, 0xc1f00000, v48
	v_exp_f32_e32 v52, v52
	v_mul_f32_e32 v48, 0xbfb8aa3b, v48
	v_exp_f32_e32 v48, v48
	v_cvt_pk_f16_f32 v47, v46, v47
	v_add_f32_e32 v46, 1.0, v52
	v_rcp_f32_e32 v52, v46
	v_add_f32_e32 v46, 1.0, v48
	v_rcp_f32_e32 v53, v46
	v_pk_mov_b32 v[48:49], v[48:49], v[42:43] op_sel:[1,0]
	v_cvt_f32_f16_sdwa v42, v88 dst_sel:DWORD dst_unused:UNUSED_PAD src0_sel:WORD_1
	v_pack_b32_f16 v46, v55, v47
	v_pk_mul_f32 v[48:49], v[48:49], v[52:53]
	v_cvt_f32_f16_sdwa v53, v89 dst_sel:DWORD dst_unused:UNUSED_PAD src0_sel:WORD_1
	v_cvt_pk_f16_f32 v52, v48, v49
	v_cvt_f32_f16_e32 v48, v89
	v_max_f32_e32 v42, 0xc1f00000, v42
	v_mul_f32_e32 v42, 0xbfb8aa3b, v42
	v_exp_f32_e32 v42, v42
	v_max_f32_e32 v48, 0xc1f00000, v48
	v_mul_f32_e32 v48, 0xbfb8aa3b, v48
	v_exp_f32_e32 v49, v48
	v_add_f32_e32 v42, 1.0, v42
	v_rcp_f32_e32 v48, v42
	v_alignbit_b32 v47, v52, v47, 16
	v_add_f32_e32 v42, 1.0, v49
	v_rcp_f32_e32 v49, v42
	v_mov_b32_e32 v42, v43
	v_mov_b32_e32 v43, v44
	v_cvt_f32_f16_e32 v44, v82
	v_pk_mul_f32 v[42:43], v[42:43], v[48:49]
	global_store_dwordx4 v[98:99], v[62:65], off
	v_cvt_pk_f16_f32 v42, v42, v43
	v_max_f32_e32 v43, 0xc1f00000, v53
	v_mul_f32_e32 v43, 0xbfb8aa3b, v43
	v_exp_f32_e32 v43, v43
	v_alignbit_b32 v48, v42, v52, 16
	v_lshrrev_b32_e32 v49, 16, v42
	v_add_f32_e32 v42, 1.0, v43
	v_rcp_f32_e32 v42, v42
	v_max_f32_e32 v43, 0xc1f00000, v44
	v_mul_f32_e32 v43, 0xbfb8aa3b, v43
	v_exp_f32_e32 v43, v43
	v_fma_mixhi_f16 v49, v45, v42, 0
	v_cvt_f32_f16_sdwa v42, v82 dst_sel:DWORD dst_unused:UNUSED_PAD src0_sel:WORD_1
	v_cvt_f32_f16_e32 v44, v83
	v_add_f32_e32 v43, 1.0, v43
	v_rcp_f32_e32 v43, v43
	v_max_f32_e32 v42, 0xc1f00000, v42
	v_mul_f32_e32 v42, 0xbfb8aa3b, v42
	v_max_f32_e32 v44, 0xc1f00000, v44
	v_exp_f32_e32 v42, v42
	v_mul_f32_e32 v44, 0xbfb8aa3b, v44
	v_exp_f32_e32 v44, v44
	v_fma_mixlo_f16 v45, v38, v43, 0
	v_add_f32_e32 v38, 1.0, v42
	v_rcp_f32_e32 v42, v38
	v_add_f32_e32 v38, 1.0, v44
	v_rcp_f32_e32 v43, v38
	v_cvt_f32_f16_sdwa v44, v83 dst_sel:DWORD dst_unused:UNUSED_PAD src0_sel:WORD_1
	v_mov_b32_e32 v38, v39
	v_mov_b32_e32 v39, v40
	v_cvt_f32_f16_e32 v40, v84
	v_max_f32_e32 v44, 0xc1f00000, v44
	v_mul_f32_e32 v44, 0xbfb8aa3b, v44
	v_exp_f32_e32 v44, v44
	v_max_f32_e32 v40, 0xc1f00000, v40
	v_mul_f32_e32 v40, 0xbfb8aa3b, v40
	v_exp_f32_e32 v40, v40
	v_pk_mul_f32 v[38:39], v[38:39], v[42:43]
	v_add_f32_e32 v42, 1.0, v44
	v_rcp_f32_e32 v42, v42
	v_add_f32_e32 v40, 1.0, v40
	v_rcp_f32_e32 v43, v40
	v_pk_mov_b32 v[40:41], v[40:41], v[34:35] op_sel:[1,0]
	v_cvt_f32_f16_sdwa v34, v84 dst_sel:DWORD dst_unused:UNUSED_PAD src0_sel:WORD_1
	v_cvt_pk_f16_f32 v39, v38, v39
	v_pk_mul_f32 v[40:41], v[40:41], v[42:43]
	v_cvt_f32_f16_sdwa v43, v85 dst_sel:DWORD dst_unused:UNUSED_PAD src0_sel:WORD_1
	v_cvt_pk_f16_f32 v42, v40, v41
	v_cvt_f32_f16_e32 v40, v85
	v_max_f32_e32 v34, 0xc1f00000, v34
	v_mul_f32_e32 v34, 0xbfb8aa3b, v34
	v_exp_f32_e32 v34, v34
	v_max_f32_e32 v40, 0xc1f00000, v40
	v_mul_f32_e32 v40, 0xbfb8aa3b, v40
	v_exp_f32_e32 v41, v40
	v_add_f32_e32 v34, 1.0, v34
	v_rcp_f32_e32 v40, v34
	v_pack_b32_f16 v38, v45, v39
	v_add_f32_e32 v34, 1.0, v41
	v_rcp_f32_e32 v41, v34
	v_mov_b32_e32 v34, v35
	v_max_f32_e32 v35, 0xc1f00000, v43
	v_mul_f32_e32 v35, 0xbfb8aa3b, v35
	v_exp_f32_e32 v43, v35
	v_mov_b32_e32 v35, v36
	v_pk_mul_f32 v[34:35], v[34:35], v[40:41]
	v_cvt_f32_f16_e32 v36, v78
	v_cvt_pk_f16_f32 v34, v34, v35
	v_add_f32_e32 v35, 1.0, v43
	v_rcp_f32_e32 v35, v35
	v_alignbit_b32 v40, v34, v42, 16
	v_lshrrev_b32_e32 v41, 16, v34
	v_max_f32_e32 v34, 0xc1f00000, v36
	v_alignbit_b32 v39, v42, v39, 16
	v_fma_mixhi_f16 v41, v37, v35, 0
	v_mul_f32_e32 v34, 0xbfb8aa3b, v34
	v_cvt_f32_f16_sdwa v37, v78 dst_sel:DWORD dst_unused:UNUSED_PAD src0_sel:WORD_1
	v_exp_f32_e32 v36, v34
	global_store_dwordx4 v[50:51], v[38:41], off offset:256
	v_lshl_add_u64 v[34:35], v[192:193], 0, v[184:185]
	v_max_f32_e32 v37, 0xc1f00000, v37
	v_cvt_f32_f16_e32 v38, v79
	v_add_f32_e32 v36, 1.0, v36
	v_mul_f32_e32 v37, 0xbfb8aa3b, v37
	v_rcp_f32_e32 v36, v36
	v_max_f32_e32 v38, 0xc1f00000, v38
	v_exp_f32_e32 v37, v37
	v_mul_f32_e32 v38, 0xbfb8aa3b, v38
	v_exp_f32_e32 v38, v38
	v_fma_mixlo_f16 v39, v28, v36, 0
	v_add_f32_e32 v28, 1.0, v37
	v_rcp_f32_e32 v36, v28
	v_add_f32_e32 v28, 1.0, v38
	v_rcp_f32_e32 v37, v28
	v_cvt_f32_f16_sdwa v38, v79 dst_sel:DWORD dst_unused:UNUSED_PAD src0_sel:WORD_1
	v_mov_b32_e32 v28, v29
	v_mov_b32_e32 v29, v30
	v_cvt_f32_f16_e32 v30, v80
	v_pk_mul_f32 v[28:29], v[28:29], v[36:37]
	v_max_f32_e32 v36, 0xc1f00000, v38
	v_mul_f32_e32 v36, 0xbfb8aa3b, v36
	v_max_f32_e32 v30, 0xc1f00000, v30
	v_exp_f32_e32 v36, v36
	v_mul_f32_e32 v30, 0xbfb8aa3b, v30
	v_exp_f32_e32 v30, v30
	v_cvt_pk_f16_f32 v29, v28, v29
	v_add_f32_e32 v28, 1.0, v36
	v_rcp_f32_e32 v36, v28
	v_add_f32_e32 v28, 1.0, v30
	v_rcp_f32_e32 v37, v28
	v_pk_mov_b32 v[30:31], v[30:31], v[24:25] op_sel:[1,0]
	v_cvt_f32_f16_sdwa v24, v80 dst_sel:DWORD dst_unused:UNUSED_PAD src0_sel:WORD_1
	v_pack_b32_f16 v28, v39, v29
	v_pk_mul_f32 v[30:31], v[30:31], v[36:37]
	v_cvt_f32_f16_sdwa v37, v81 dst_sel:DWORD dst_unused:UNUSED_PAD src0_sel:WORD_1
	v_cvt_pk_f16_f32 v36, v30, v31
	v_cvt_f32_f16_e32 v30, v81
	v_max_f32_e32 v24, 0xc1f00000, v24
	v_mul_f32_e32 v24, 0xbfb8aa3b, v24
	v_exp_f32_e32 v24, v24
	v_max_f32_e32 v30, 0xc1f00000, v30
	v_mul_f32_e32 v30, 0xbfb8aa3b, v30
	v_exp_f32_e32 v31, v30
	v_add_f32_e32 v24, 1.0, v24
	v_rcp_f32_e32 v30, v24
	v_alignbit_b32 v29, v36, v29, 16
	v_add_f32_e32 v24, 1.0, v31
	v_rcp_f32_e32 v31, v24
	v_mov_b32_e32 v24, v25
	v_mov_b32_e32 v25, v26
	v_cvt_f32_f16_e32 v26, v74
	v_pk_mul_f32 v[24:25], v[24:25], v[30:31]
	global_store_dwordx4 v[50:51], v[46:49], off
	v_cvt_pk_f16_f32 v24, v24, v25
	v_max_f32_e32 v25, 0xc1f00000, v37
	v_mul_f32_e32 v25, 0xbfb8aa3b, v25
	v_exp_f32_e32 v25, v25
	v_alignbit_b32 v30, v24, v36, 16
	v_lshrrev_b32_e32 v31, 16, v24
	v_add_f32_e32 v24, 1.0, v25
	v_rcp_f32_e32 v24, v24
	v_max_f32_e32 v25, 0xc1f00000, v26
	v_mul_f32_e32 v25, 0xbfb8aa3b, v25
	v_exp_f32_e32 v25, v25
	v_fma_mixhi_f16 v31, v27, v24, 0
	v_cvt_f32_f16_sdwa v24, v74 dst_sel:DWORD dst_unused:UNUSED_PAD src0_sel:WORD_1
	v_cvt_f32_f16_e32 v26, v75
	v_add_f32_e32 v25, 1.0, v25
	v_rcp_f32_e32 v25, v25
	v_max_f32_e32 v24, 0xc1f00000, v24
	v_mul_f32_e32 v24, 0xbfb8aa3b, v24
	v_max_f32_e32 v26, 0xc1f00000, v26
	v_exp_f32_e32 v24, v24
	v_mul_f32_e32 v26, 0xbfb8aa3b, v26
	v_exp_f32_e32 v26, v26
	v_fma_mixlo_f16 v27, v20, v25, 0
	v_add_f32_e32 v20, 1.0, v24
	v_rcp_f32_e32 v24, v20
	v_add_f32_e32 v20, 1.0, v26
	v_rcp_f32_e32 v25, v20
	v_cvt_f32_f16_sdwa v26, v75 dst_sel:DWORD dst_unused:UNUSED_PAD src0_sel:WORD_1
	v_mov_b32_e32 v20, v21
	v_mov_b32_e32 v21, v22
	v_cvt_f32_f16_e32 v22, v76
	v_max_f32_e32 v26, 0xc1f00000, v26
	v_mul_f32_e32 v26, 0xbfb8aa3b, v26
	v_exp_f32_e32 v26, v26
	v_max_f32_e32 v22, 0xc1f00000, v22
	v_mul_f32_e32 v22, 0xbfb8aa3b, v22
	v_exp_f32_e32 v22, v22
	v_pk_mul_f32 v[20:21], v[20:21], v[24:25]
	v_add_f32_e32 v24, 1.0, v26
	v_rcp_f32_e32 v24, v24
	v_add_f32_e32 v22, 1.0, v22
	v_rcp_f32_e32 v25, v22
	v_pk_mov_b32 v[22:23], v[22:23], v[16:17] op_sel:[1,0]
	v_cvt_f32_f16_sdwa v16, v76 dst_sel:DWORD dst_unused:UNUSED_PAD src0_sel:WORD_1
	v_cvt_pk_f16_f32 v21, v20, v21
	v_pk_mul_f32 v[22:23], v[22:23], v[24:25]
	v_cvt_f32_f16_sdwa v25, v77 dst_sel:DWORD dst_unused:UNUSED_PAD src0_sel:WORD_1
	v_cvt_pk_f16_f32 v24, v22, v23
	v_cvt_f32_f16_e32 v22, v77
	v_max_f32_e32 v16, 0xc1f00000, v16
	v_mul_f32_e32 v16, 0xbfb8aa3b, v16
	v_exp_f32_e32 v16, v16
	v_max_f32_e32 v22, 0xc1f00000, v22
	v_mul_f32_e32 v22, 0xbfb8aa3b, v22
	v_exp_f32_e32 v23, v22
	v_add_f32_e32 v16, 1.0, v16
	v_rcp_f32_e32 v22, v16
	v_pack_b32_f16 v20, v27, v21
	v_add_f32_e32 v16, 1.0, v23
	v_rcp_f32_e32 v23, v16
	v_mov_b32_e32 v16, v17
	v_max_f32_e32 v17, 0xc1f00000, v25
	v_mul_f32_e32 v17, 0xbfb8aa3b, v17
	v_exp_f32_e32 v25, v17
	v_mov_b32_e32 v17, v18
	v_pk_mul_f32 v[16:17], v[16:17], v[22:23]
	v_cvt_f32_f16_e32 v18, v70
	v_cvt_pk_f16_f32 v16, v16, v17
	v_add_f32_e32 v17, 1.0, v25
	v_rcp_f32_e32 v17, v17
	v_alignbit_b32 v22, v16, v24, 16
	v_lshrrev_b32_e32 v23, 16, v16
	v_max_f32_e32 v16, 0xc1f00000, v18
	v_alignbit_b32 v21, v24, v21, 16
	v_fma_mixhi_f16 v23, v19, v17, 0
	v_mul_f32_e32 v16, 0xbfb8aa3b, v16
	v_cvt_f32_f16_sdwa v19, v70 dst_sel:DWORD dst_unused:UNUSED_PAD src0_sel:WORD_1
	v_exp_f32_e32 v18, v16
	global_store_dwordx4 v[34:35], v[20:23], off offset:256
	v_lshl_add_u64 v[16:17], v[192:193], 0, v[186:187]
	v_max_f32_e32 v19, 0xc1f00000, v19
	v_cvt_f32_f16_e32 v20, v71
	v_add_f32_e32 v18, 1.0, v18
	v_mul_f32_e32 v19, 0xbfb8aa3b, v19
	v_rcp_f32_e32 v18, v18
	v_max_f32_e32 v20, 0xc1f00000, v20
	v_exp_f32_e32 v19, v19
	v_mul_f32_e32 v20, 0xbfb8aa3b, v20
	v_exp_f32_e32 v20, v20
	v_fma_mixlo_f16 v21, v12, v18, 0
	v_add_f32_e32 v12, 1.0, v19
	v_rcp_f32_e32 v18, v12
	v_add_f32_e32 v12, 1.0, v20
	v_rcp_f32_e32 v19, v12
	v_cvt_f32_f16_sdwa v20, v71 dst_sel:DWORD dst_unused:UNUSED_PAD src0_sel:WORD_1
	v_mov_b32_e32 v12, v13
	v_mov_b32_e32 v13, v14
	v_cvt_f32_f16_e32 v14, v72
	v_pk_mul_f32 v[12:13], v[12:13], v[18:19]
	v_max_f32_e32 v18, 0xc1f00000, v20
	v_mul_f32_e32 v18, 0xbfb8aa3b, v18
	v_max_f32_e32 v14, 0xc1f00000, v14
	v_exp_f32_e32 v18, v18
	v_mul_f32_e32 v14, 0xbfb8aa3b, v14
	v_exp_f32_e32 v14, v14
	v_cvt_pk_f16_f32 v13, v12, v13
	v_add_f32_e32 v12, 1.0, v18
	v_rcp_f32_e32 v18, v12
	v_add_f32_e32 v12, 1.0, v14
	v_rcp_f32_e32 v19, v12
	v_pk_mov_b32 v[14:15], v[14:15], v[8:9] op_sel:[1,0]
	v_cvt_f32_f16_sdwa v8, v72 dst_sel:DWORD dst_unused:UNUSED_PAD src0_sel:WORD_1
	v_pack_b32_f16 v12, v21, v13
	v_pk_mul_f32 v[14:15], v[14:15], v[18:19]
	v_cvt_f32_f16_sdwa v19, v73 dst_sel:DWORD dst_unused:UNUSED_PAD src0_sel:WORD_1
	v_cvt_pk_f16_f32 v18, v14, v15
	v_cvt_f32_f16_e32 v14, v73
	v_max_f32_e32 v8, 0xc1f00000, v8
	v_mul_f32_e32 v8, 0xbfb8aa3b, v8
	v_exp_f32_e32 v8, v8
	v_max_f32_e32 v14, 0xc1f00000, v14
	v_mul_f32_e32 v14, 0xbfb8aa3b, v14
	v_exp_f32_e32 v15, v14
	v_add_f32_e32 v8, 1.0, v8
	v_rcp_f32_e32 v14, v8
	v_alignbit_b32 v13, v18, v13, 16
	v_add_f32_e32 v8, 1.0, v15
	v_rcp_f32_e32 v15, v8
	v_mov_b32_e32 v8, v9
	v_mov_b32_e32 v9, v10
	v_cvt_f32_f16_e32 v10, v66
	v_pk_mul_f32 v[8:9], v[8:9], v[14:15]
	global_store_dwordx4 v[34:35], v[28:31], off
	v_cvt_pk_f16_f32 v8, v8, v9
	v_max_f32_e32 v9, 0xc1f00000, v19
	v_mul_f32_e32 v9, 0xbfb8aa3b, v9
	v_exp_f32_e32 v9, v9
	v_alignbit_b32 v14, v8, v18, 16
	v_lshrrev_b32_e32 v15, 16, v8
	v_add_f32_e32 v8, 1.0, v9
	v_rcp_f32_e32 v8, v8
	v_max_f32_e32 v9, 0xc1f00000, v10
	v_mul_f32_e32 v9, 0xbfb8aa3b, v9
	v_exp_f32_e32 v9, v9
	v_fma_mixhi_f16 v15, v11, v8, 0
	v_cvt_f32_f16_sdwa v8, v66 dst_sel:DWORD dst_unused:UNUSED_PAD src0_sel:WORD_1
	v_cvt_f32_f16_e32 v10, v67
	v_add_f32_e32 v9, 1.0, v9
	v_rcp_f32_e32 v9, v9
	v_max_f32_e32 v8, 0xc1f00000, v8
	v_mul_f32_e32 v8, 0xbfb8aa3b, v8
	v_max_f32_e32 v10, 0xc1f00000, v10
	v_exp_f32_e32 v8, v8
	v_mul_f32_e32 v10, 0xbfb8aa3b, v10
	v_exp_f32_e32 v10, v10
	v_fma_mixlo_f16 v11, v4, v9, 0
	v_add_f32_e32 v4, 1.0, v8
	v_rcp_f32_e32 v8, v4
	v_add_f32_e32 v4, 1.0, v10
	v_rcp_f32_e32 v9, v4
	v_cvt_f32_f16_sdwa v10, v67 dst_sel:DWORD dst_unused:UNUSED_PAD src0_sel:WORD_1
	v_mov_b32_e32 v4, v5
	v_mov_b32_e32 v5, v6
	v_cvt_f32_f16_e32 v6, v68
	v_max_f32_e32 v10, 0xc1f00000, v10
	v_mul_f32_e32 v10, 0xbfb8aa3b, v10
	v_exp_f32_e32 v10, v10
	v_max_f32_e32 v6, 0xc1f00000, v6
	v_mul_f32_e32 v6, 0xbfb8aa3b, v6
	v_exp_f32_e32 v6, v6
	v_pk_mul_f32 v[4:5], v[4:5], v[8:9]
	v_add_f32_e32 v8, 1.0, v10
	v_rcp_f32_e32 v8, v8
	v_add_f32_e32 v6, 1.0, v6
	v_rcp_f32_e32 v9, v6
	v_pk_mov_b32 v[6:7], v[6:7], v[0:1] op_sel:[1,0]
	v_cvt_f32_f16_sdwa v0, v68 dst_sel:DWORD dst_unused:UNUSED_PAD src0_sel:WORD_1
	v_cvt_pk_f16_f32 v5, v4, v5
	v_pk_mul_f32 v[6:7], v[6:7], v[8:9]
	v_cvt_f32_f16_sdwa v9, v69 dst_sel:DWORD dst_unused:UNUSED_PAD src0_sel:WORD_1
	v_cvt_pk_f16_f32 v8, v6, v7
	v_cvt_f32_f16_e32 v6, v69
	v_max_f32_e32 v0, 0xc1f00000, v0
	v_mul_f32_e32 v0, 0xbfb8aa3b, v0
	v_exp_f32_e32 v0, v0
	v_max_f32_e32 v6, 0xc1f00000, v6
	v_mul_f32_e32 v6, 0xbfb8aa3b, v6
	v_exp_f32_e32 v7, v6
	v_add_f32_e32 v0, 1.0, v0
	v_rcp_f32_e32 v6, v0
	v_pack_b32_f16 v4, v11, v5
	v_add_f32_e32 v0, 1.0, v7
	v_rcp_f32_e32 v7, v0
	v_max_f32_e32 v0, 0xc1f00000, v9
	v_mul_f32_e32 v0, 0xbfb8aa3b, v0
	v_exp_f32_e32 v9, v0
	v_mov_b32_e32 v0, v1
	v_mov_b32_e32 v1, v2
	v_pk_mul_f32 v[0:1], v[0:1], v[6:7]
	v_add_f32_e32 v2, 1.0, v9
	v_rcp_f32_e32 v2, v2
	v_cvt_pk_f16_f32 v0, v0, v1
	v_lshrrev_b32_e32 v7, 16, v0
	v_alignbit_b32 v5, v8, v5, 16
	v_alignbit_b32 v6, v0, v8, 16
	v_fma_mixhi_f16 v7, v3, v2, 0
	global_store_dwordx4 v[16:17], v[12:15], off
	global_store_dwordx4 v[16:17], v[4:7], off offset:256
	s_and_b64 vcc, exec, s[4:5]
	s_mov_b32 s31, s30
	s_mov_b32 s34, s29
	s_mov_b64 s[12:13], s[0:1]
	s_mov_b64 s[10:11], s[2:3]
	s_cbranch_vccz .LBB0_955
	s_waitcnt vmcnt(0)
	s_cmpk_gt_u32 s19, 0xff
	s_cbranch_scc1 .LBB0_962
	s_barrier

.LBB0_1117:
	s_add_i32 s41, s22, 2
	s_add_u32 s20, s14, 0x100
	s_addc_u32 s21, s15, 0
	s_add_i32 s42, 0, 0x10000
	s_waitcnt vmcnt(0)
	v_add_u32_e32 v102, s42, v230
	ds_read_b128 v[78:81], v102
	ds_read_b128 v[94:97], v102 offset:2048
	ds_read_b128 v[86:89], v102 offset:1024
	ds_read_b128 v[102:105], v102 offset:3072
	s_cmp_eq_u32 s38, s22
	s_cselect_b32 s22, s18, s39
	s_cselect_b32 s25, s17, s21
	s_cselect_b32 s24, s16, s20
	s_cselect_b32 s23, s19, s40
	v_lshl_add_u64 v[178:179], s[14:15], 0, v[200:201]
	s_add_i32 m0, s28, 0xc000
	ds_read_b128 v[122:125], v232
	ds_read_b128 v[130:133], v232 offset:2048
	ds_read_b128 v[154:157], v232 offset:4096
	ds_read_b128 v[170:173], v232 offset:6144
	ds_read_b128 v[126:129], v232 offset:1024
	ds_read_b128 v[134:137], v232 offset:3072
	ds_read_b128 v[158:161], v232 offset:5120
	ds_read_b128 v[174:177], v232 offset:7168
	global_load_lds_dwordx4 v[178:179], off
	v_lshl_add_u64 v[178:179], s[14:15], 0, v[202:203]
	s_add_i32 m0, s28, 0xe000
	s_nop 0
	global_load_lds_dwordx4 v[178:179], off
	s_waitcnt lgkmcnt(8)
	s_barrier
	s_waitcnt lgkmcnt(7)
	s_setprio 1
	v_mfma_f32_16x16x32_f16 v[166:169], v[78:81], v[122:125], v[166:169]
	v_mfma_f32_16x16x32_f16 v[162:165], v[94:97], v[122:125], v[162:165]
	s_waitcnt lgkmcnt(6)
	v_mfma_f32_16x16x32_f16 v[150:153], v[78:81], v[130:133], v[150:153]
	v_mfma_f32_16x16x32_f16 v[142:145], v[94:97], v[130:133], v[142:145]
	s_waitcnt lgkmcnt(5)
	v_mfma_f32_16x16x32_f16 v[110:113], v[78:81], v[154:157], v[110:113]
	v_mfma_f32_16x16x32_f16 v[106:109], v[94:97], v[154:157], v[106:109]
	s_waitcnt lgkmcnt(4)
	v_mfma_f32_16x16x32_f16 v[82:85], v[78:81], v[170:173], v[82:85]
	v_mfma_f32_16x16x32_f16 v[74:77], v[94:97], v[170:173], v[74:77]
	s_waitcnt lgkmcnt(3)
	v_mfma_f32_16x16x32_f16 v[166:169], v[86:89], v[126:129], v[166:169]
	v_mfma_f32_16x16x32_f16 v[162:165], v[102:105], v[126:129], v[162:165]
	s_waitcnt lgkmcnt(2)
	v_mfma_f32_16x16x32_f16 v[150:153], v[86:89], v[134:137], v[150:153]
	v_mfma_f32_16x16x32_f16 v[142:145], v[102:105], v[134:137], v[142:145]
	s_waitcnt lgkmcnt(1)
	v_mfma_f32_16x16x32_f16 v[110:113], v[86:89], v[158:161], v[110:113]
	v_mfma_f32_16x16x32_f16 v[106:109], v[102:105], v[158:161], v[106:109]
	s_waitcnt lgkmcnt(0)
	v_mfma_f32_16x16x32_f16 v[82:85], v[86:89], v[174:177], v[82:85]
	v_mfma_f32_16x16x32_f16 v[74:77], v[102:105], v[174:177], v[74:77]
	s_setprio 0
	s_barrier
	s_add_i32 s43, 0, 0x14000
	s_add_i32 s14, s42, s13
	v_add_u32_e32 v190, s43, v230
	v_lshl_add_u64 v[204:205], s[22:23], 0, v[32:33]
	s_mov_b32 m0, s14
	ds_read_b128 v[178:181], v190
	ds_read_b128 v[186:189], v190 offset:2048
	ds_read_b128 v[182:185], v190 offset:1024
	ds_read_b128 v[190:193], v190 offset:3072
	global_load_lds_dwordx4 v[204:205], off
	v_lshl_add_u64 v[206:207], s[22:23], 0, v[198:199]
	s_add_i32 m0, s14, 0x2000
	s_nop 0
	global_load_lds_dwordx4 v[206:207], off
	s_barrier
	s_waitcnt lgkmcnt(3)
	s_setprio 1
	v_mfma_f32_16x16x32_f16 v[146:149], v[178:181], v[122:125], v[146:149]
	v_mfma_f32_16x16x32_f16 v[118:121], v[178:181], v[130:133], v[118:121]
	s_waitcnt lgkmcnt(2)
	v_mfma_f32_16x16x32_f16 v[114:117], v[186:189], v[130:133], v[114:117]
	v_mfma_f32_16x16x32_f16 v[98:101], v[178:181], v[154:157], v[98:101]
	v_mfma_f32_16x16x32_f16 v[90:93], v[186:189], v[154:157], v[90:93]
	v_mfma_f32_16x16x32_f16 v[70:73], v[178:181], v[170:173], v[70:73]
	s_waitcnt lgkmcnt(1)
	v_mfma_f32_16x16x32_f16 v[66:69], v[186:189], v[170:173], v[66:69]
	v_mfma_f32_16x16x32_f16 v[146:149], v[182:185], v[126:129], v[146:149]
	v_mfma_f32_16x16x32_f16 v[122:125], v[186:189], v[122:125], v[138:141]
	v_mfma_f32_16x16x32_f16 v[118:121], v[182:185], v[134:137], v[118:121]
	s_waitcnt lgkmcnt(0)
	v_mfma_f32_16x16x32_f16 v[114:117], v[190:193], v[134:137], v[114:117]
	v_mfma_f32_16x16x32_f16 v[98:101], v[182:185], v[158:161], v[98:101]
	v_mfma_f32_16x16x32_f16 v[90:93], v[190:193], v[158:161], v[90:93]
	v_mfma_f32_16x16x32_f16 v[70:73], v[182:185], v[174:177], v[70:73]
	v_mfma_f32_16x16x32_f16 v[66:69], v[190:193], v[174:177], v[66:69]
	v_mfma_f32_16x16x32_f16 v[122:125], v[190:193], v[126:129], v[122:125]
	s_setprio 0
	s_mov_b32 m0, s28
	v_lshl_add_u64 v[208:209], s[24:25], 0, v[32:33]
	s_barrier
	ds_read_b128 v[126:129], v232 offset:16384
	ds_read_b128 v[134:137], v232 offset:18432
	ds_read_b128 v[154:157], v232 offset:20480
	ds_read_b128 v[170:173], v232 offset:22528
	ds_read_b128 v[130:133], v232 offset:17408
	ds_read_b128 v[138:141], v232 offset:19456
	ds_read_b128 v[158:161], v232 offset:21504
	ds_read_b128 v[174:177], v232 offset:23552
	global_load_lds_dwordx4 v[208:209], off
	v_lshl_add_u64 v[210:211], s[24:25], 0, v[198:199]
	s_mov_b32 m0, s29
	s_nop 0
	global_load_lds_dwordx4 v[210:211], off
	s_barrier
	s_waitcnt lgkmcnt(7)
	s_setprio 1
	v_mfma_f32_16x16x32_f16 v[62:65], v[78:81], v[126:129], v[62:65]
	v_mfma_f32_16x16x32_f16 v[58:61], v[94:97], v[126:129], v[58:61]
	s_waitcnt lgkmcnt(6)
	v_mfma_f32_16x16x32_f16 v[46:49], v[78:81], v[134:137], v[46:49]
	v_mfma_f32_16x16x32_f16 v[42:45], v[94:97], v[134:137], v[42:45]
	s_waitcnt lgkmcnt(5)
	v_mfma_f32_16x16x32_f16 v[28:31], v[78:81], v[154:157], v[28:31]
	v_mfma_f32_16x16x32_f16 v[24:27], v[94:97], v[154:157], v[24:27]
	s_waitcnt lgkmcnt(4)
	v_mfma_f32_16x16x32_f16 v[12:15], v[78:81], v[170:173], v[12:15]
	v_mfma_f32_16x16x32_f16 v[8:11], v[94:97], v[170:173], v[8:11]
	s_waitcnt lgkmcnt(3)
	v_mfma_f32_16x16x32_f16 v[62:65], v[86:89], v[130:133], v[62:65]
	v_mfma_f32_16x16x32_f16 v[58:61], v[102:105], v[130:133], v[58:61]
	s_waitcnt lgkmcnt(2)
	v_mfma_f32_16x16x32_f16 v[46:49], v[86:89], v[138:141], v[46:49]
	v_mfma_f32_16x16x32_f16 v[42:45], v[102:105], v[138:141], v[42:45]
	s_waitcnt lgkmcnt(1)
	v_mfma_f32_16x16x32_f16 v[28:31], v[86:89], v[158:161], v[28:31]
	v_mfma_f32_16x16x32_f16 v[24:27], v[102:105], v[158:161], v[24:27]
	s_waitcnt lgkmcnt(0)
	v_mfma_f32_16x16x32_f16 v[12:15], v[86:89], v[174:177], v[12:15]
	v_mfma_f32_16x16x32_f16 v[8:11], v[102:105], v[174:177], v[8:11]
	s_setprio 0
	s_barrier
	s_add_u32 s14, s22, 0x40000
	s_addc_u32 s15, s23, 0
	s_add_i32 s42, s43, s13
	v_lshl_add_u64 v[78:79], s[14:15], 0, v[32:33]
	s_mov_b32 m0, s42
	s_nop 0
	global_load_lds_dwordx4 v[78:79], off
	v_lshl_add_u64 v[78:79], s[14:15], 0, v[198:199]
	s_add_i32 m0, s42, 0x2000
	s_nop 0
	global_load_lds_dwordx4 v[78:79], off
	s_waitcnt vmcnt(10)
	s_barrier
	s_setprio 1
	v_mfma_f32_16x16x32_f16 v[54:57], v[178:181], v[126:129], v[54:57]
	v_mfma_f32_16x16x32_f16 v[50:53], v[186:189], v[126:129], v[50:53]
	v_mfma_f32_16x16x32_f16 v[38:41], v[178:181], v[134:137], v[38:41]
	v_mfma_f32_16x16x32_f16 v[34:37], v[186:189], v[134:137], v[34:37]
	v_mfma_f32_16x16x32_f16 v[20:23], v[178:181], v[154:157], v[20:23]
	v_mfma_f32_16x16x32_f16 v[16:19], v[186:189], v[154:157], v[16:19]
	v_mfma_f32_16x16x32_f16 v[4:7], v[178:181], v[170:173], v[4:7]
	v_mfma_f32_16x16x32_f16 v[0:3], v[186:189], v[170:173], v[0:3]
	v_mfma_f32_16x16x32_f16 v[54:57], v[182:185], v[130:133], v[54:57]
	v_mfma_f32_16x16x32_f16 v[50:53], v[190:193], v[130:133], v[50:53]
	v_mfma_f32_16x16x32_f16 v[38:41], v[182:185], v[138:141], v[38:41]
	v_mfma_f32_16x16x32_f16 v[34:37], v[190:193], v[138:141], v[34:37]
	v_mfma_f32_16x16x32_f16 v[20:23], v[182:185], v[158:161], v[20:23]
	v_mfma_f32_16x16x32_f16 v[16:19], v[190:193], v[158:161], v[16:19]
	v_mfma_f32_16x16x32_f16 v[4:7], v[182:185], v[174:177], v[4:7]
	v_mfma_f32_16x16x32_f16 v[0:3], v[190:193], v[174:177], v[0:3]
	s_setprio 0
	s_add_i32 s42, 0, 0x18000
	v_add_u32_e32 v102, s42, v230
	s_barrier
	ds_read_b128 v[78:81], v102
	ds_read_b128 v[86:89], v102 offset:1024
	ds_read_b128 v[94:97], v102 offset:2048
	ds_read_b128 v[102:105], v102 offset:3072
	s_add_u32 s14, s24, 0x40000
	s_addc_u32 s15, s25, 0
	s_mov_b32 m0, s30
	v_lshl_add_u64 v[138:139], s[14:15], 0, v[32:33]
	ds_read_b128 v[126:129], v232 offset:32768
	ds_read_b128 v[130:133], v232 offset:33792
	ds_read_b128 v[134:137], v232 offset:34816
	ds_read_b128 v[154:157], v232 offset:35840
	ds_read_b128 v[158:161], v232 offset:36864
	ds_read_b128 v[174:177], v232 offset:38912
	ds_read_b128 v[170:173], v232 offset:37888
	ds_read_b128 v[178:181], v232 offset:39936
	global_load_lds_dwordx4 v[138:139], off
	v_lshl_add_u64 v[138:139], s[14:15], 0, v[198:199]
	s_mov_b32 m0, s31
	s_nop 0
	global_load_lds_dwordx4 v[138:139], off
	s_waitcnt lgkmcnt(8)
	s_waitcnt vmcnt(10)
	s_barrier
	s_waitcnt lgkmcnt(6)
	s_setprio 1
	v_mfma_f32_16x16x32_f16 v[138:141], v[78:81], v[126:129], v[166:169]
	v_mfma_f32_16x16x32_f16 v[166:169], v[86:89], v[130:133], v[138:141]
	v_mfma_f32_16x16x32_f16 v[138:141], v[94:97], v[126:129], v[162:165]
	v_mfma_f32_16x16x32_f16 v[162:165], v[102:105], v[130:133], v[138:141]
	s_waitcnt lgkmcnt(4)
	v_mfma_f32_16x16x32_f16 v[138:141], v[78:81], v[134:137], v[150:153]
	v_mfma_f32_16x16x32_f16 v[150:153], v[86:89], v[154:157], v[138:141]
	s_waitcnt lgkmcnt(3)
	v_mfma_f32_16x16x32_f16 v[138:141], v[94:97], v[134:137], v[142:145]
	v_mfma_f32_16x16x32_f16 v[110:113], v[78:81], v[158:161], v[110:113]
	s_waitcnt lgkmcnt(2)
	v_mfma_f32_16x16x32_f16 v[106:109], v[94:97], v[158:161], v[106:109]
	v_mfma_f32_16x16x32_f16 v[82:85], v[78:81], v[174:177], v[82:85]
	v_mfma_f32_16x16x32_f16 v[74:77], v[94:97], v[174:177], v[74:77]
	v_mfma_f32_16x16x32_f16 v[142:145], v[102:105], v[154:157], v[138:141]
	s_waitcnt lgkmcnt(1)
	v_mfma_f32_16x16x32_f16 v[110:113], v[86:89], v[170:173], v[110:113]
	v_mfma_f32_16x16x32_f16 v[106:109], v[102:105], v[170:173], v[106:109]
	s_waitcnt lgkmcnt(0)
	v_mfma_f32_16x16x32_f16 v[82:85], v[86:89], v[178:181], v[82:85]
	v_mfma_f32_16x16x32_f16 v[74:77], v[102:105], v[178:181], v[74:77]
	s_setprio 0
	s_barrier
	s_add_i32 s24, 0, 0x1c000
	v_add_u32_e32 v138, s24, v230
	s_add_i32 s14, s42, s13
	ds_read_b128 v[182:185], v138
	ds_read_b128 v[190:193], v138 offset:2048
	ds_read_b128 v[186:189], v138 offset:1024
	ds_read_b128 v[194:197], v138 offset:3072
	v_lshl_add_u64 v[138:139], v[204:205], 0, s[84:85]
	s_mov_b32 m0, s14
	s_nop 0
	global_load_lds_dwordx4 v[138:139], off
	v_lshl_add_u64 v[138:139], v[206:207], 0, s[84:85]
	s_add_i32 m0, s14, 0x2000
	s_nop 0
	global_load_lds_dwordx4 v[138:139], off
	s_waitcnt vmcnt(10)
	s_barrier
	s_waitcnt lgkmcnt(2)
	s_setprio 1
	v_mfma_f32_16x16x32_f16 v[138:141], v[182:185], v[126:129], v[146:149]
	v_mfma_f32_16x16x32_f16 v[122:125], v[190:193], v[126:129], v[122:125]
	v_mfma_f32_16x16x32_f16 v[118:121], v[182:185], v[134:137], v[118:121]
	v_mfma_f32_16x16x32_f16 v[114:117], v[190:193], v[134:137], v[114:117]
	v_mfma_f32_16x16x32_f16 v[98:101], v[182:185], v[158:161], v[98:101]
	v_mfma_f32_16x16x32_f16 v[90:93], v[190:193], v[158:161], v[90:93]
	v_mfma_f32_16x16x32_f16 v[70:73], v[182:185], v[174:177], v[70:73]
	v_mfma_f32_16x16x32_f16 v[66:69], v[190:193], v[174:177], v[66:69]
	s_waitcnt lgkmcnt(0)
	v_mfma_f32_16x16x32_f16 v[146:149], v[186:189], v[130:133], v[138:141]
	v_mfma_f32_16x16x32_f16 v[138:141], v[194:197], v[130:133], v[122:125]
	v_mfma_f32_16x16x32_f16 v[118:121], v[186:189], v[154:157], v[118:121]
	v_mfma_f32_16x16x32_f16 v[114:117], v[194:197], v[154:157], v[114:117]
	v_mfma_f32_16x16x32_f16 v[98:101], v[186:189], v[170:173], v[98:101]
	v_mfma_f32_16x16x32_f16 v[90:93], v[194:197], v[170:173], v[90:93]
	v_mfma_f32_16x16x32_f16 v[70:73], v[186:189], v[178:181], v[70:73]
	v_mfma_f32_16x16x32_f16 v[66:69], v[194:197], v[178:181], v[66:69]
	s_setprio 0
	s_mov_b32 m0, s34
	v_lshl_add_u64 v[178:179], v[208:209], 0, s[84:85]
	s_barrier
	ds_read_b128 v[122:125], v232 offset:49152
	ds_read_b128 v[130:133], v232 offset:51200
	ds_read_b128 v[154:157], v232 offset:53248
	ds_read_b128 v[170:173], v232 offset:55296
	ds_read_b128 v[126:129], v232 offset:50176
	ds_read_b128 v[134:137], v232 offset:52224
	ds_read_b128 v[158:161], v232 offset:54272
	ds_read_b128 v[174:177], v232 offset:56320
	global_load_lds_dwordx4 v[178:179], off
	v_lshl_add_u64 v[178:179], v[210:211], 0, s[84:85]
	s_mov_b32 m0, s35
	s_nop 0
	global_load_lds_dwordx4 v[178:179], off
	s_barrier
	s_waitcnt lgkmcnt(7)
	s_setprio 1
	v_mfma_f32_16x16x32_f16 v[62:65], v[78:81], v[122:125], v[62:65]
	v_mfma_f32_16x16x32_f16 v[58:61], v[94:97], v[122:125], v[58:61]
	s_waitcnt lgkmcnt(6)
	v_mfma_f32_16x16x32_f16 v[46:49], v[78:81], v[130:133], v[46:49]
	v_mfma_f32_16x16x32_f16 v[42:45], v[94:97], v[130:133], v[42:45]
	s_waitcnt lgkmcnt(5)
	v_mfma_f32_16x16x32_f16 v[28:31], v[78:81], v[154:157], v[28:31]
	v_mfma_f32_16x16x32_f16 v[24:27], v[94:97], v[154:157], v[24:27]
	s_waitcnt lgkmcnt(4)
	v_mfma_f32_16x16x32_f16 v[12:15], v[78:81], v[170:173], v[12:15]
	v_mfma_f32_16x16x32_f16 v[8:11], v[94:97], v[170:173], v[8:11]
	s_waitcnt lgkmcnt(3)
	v_mfma_f32_16x16x32_f16 v[62:65], v[86:89], v[126:129], v[62:65]
	v_mfma_f32_16x16x32_f16 v[58:61], v[102:105], v[126:129], v[58:61]
	s_waitcnt lgkmcnt(2)
	v_mfma_f32_16x16x32_f16 v[46:49], v[86:89], v[134:137], v[46:49]
	v_mfma_f32_16x16x32_f16 v[42:45], v[102:105], v[134:137], v[42:45]
	s_waitcnt lgkmcnt(1)
	v_mfma_f32_16x16x32_f16 v[28:31], v[86:89], v[158:161], v[28:31]
	v_mfma_f32_16x16x32_f16 v[24:27], v[102:105], v[158:161], v[24:27]
	s_waitcnt lgkmcnt(0)
	v_mfma_f32_16x16x32_f16 v[12:15], v[86:89], v[174:177], v[12:15]
	v_mfma_f32_16x16x32_f16 v[8:11], v[102:105], v[174:177], v[8:11]
	s_setprio 0
	s_barrier
	s_add_u32 s14, s22, 0x40080
	s_addc_u32 s15, s23, 0
	s_add_i32 s22, s24, s13
	v_lshl_add_u64 v[78:79], s[14:15], 0, v[32:33]
	s_mov_b32 m0, s22
	s_nop 0
	global_load_lds_dwordx4 v[78:79], off
	v_lshl_add_u64 v[78:79], s[14:15], 0, v[198:199]
	s_add_i32 m0, s22, 0x2000
	s_nop 0
	global_load_lds_dwordx4 v[78:79], off
	s_waitcnt vmcnt(6)
	s_barrier
	s_setprio 1
	v_mfma_f32_16x16x32_f16 v[54:57], v[182:185], v[122:125], v[54:57]
	v_mfma_f32_16x16x32_f16 v[50:53], v[190:193], v[122:125], v[50:53]
	v_mfma_f32_16x16x32_f16 v[38:41], v[182:185], v[130:133], v[38:41]
	v_mfma_f32_16x16x32_f16 v[34:37], v[190:193], v[130:133], v[34:37]
	v_mfma_f32_16x16x32_f16 v[20:23], v[182:185], v[154:157], v[20:23]
	v_mfma_f32_16x16x32_f16 v[16:19], v[190:193], v[154:157], v[16:19]
	v_mfma_f32_16x16x32_f16 v[4:7], v[182:185], v[170:173], v[4:7]
	v_mfma_f32_16x16x32_f16 v[0:3], v[190:193], v[170:173], v[0:3]
	v_mfma_f32_16x16x32_f16 v[54:57], v[186:189], v[126:129], v[54:57]
	v_mfma_f32_16x16x32_f16 v[50:53], v[194:197], v[126:129], v[50:53]
	v_mfma_f32_16x16x32_f16 v[38:41], v[186:189], v[134:137], v[38:41]
	v_mfma_f32_16x16x32_f16 v[34:37], v[194:197], v[134:137], v[34:37]
	v_mfma_f32_16x16x32_f16 v[20:23], v[186:189], v[158:161], v[20:23]
	v_mfma_f32_16x16x32_f16 v[16:19], v[194:197], v[158:161], v[16:19]
	v_mfma_f32_16x16x32_f16 v[4:7], v[186:189], v[174:177], v[4:7]
	v_mfma_f32_16x16x32_f16 v[0:3], v[194:197], v[174:177], v[0:3]
	s_setprio 0
	s_add_u32 s39, s39, 0x100
	s_addc_u32 s40, s40, 0
	s_cmp_ge_u32 s41, s37
	s_mov_b64 s[14:15], s[20:21]
	s_mov_b32 s22, s41
	s_barrier
	s_cbranch_scc0 .LBB0_1117
	v_lshl_or_b32 v124, s12, 8, v231
	s_cmp_eq_u32 s10, 0
	s_movk_i32 s12, 0x5000
	s_cselect_b32 s12, 0xe000, s12
	v_readlane_b32 s14, v252, 51
	s_add_u32 s14, s14, s12
	v_readlane_b32 s12, v252, 52
	s_addc_u32 s15, s12, 0
	v_ashrrev_i32_e32 v125, 31, v124
	v_lshl_add_u64 v[86:87], v[124:125], 2, s[14:15]
	global_load_dwordx4 v[94:97], v[86:87], off offset:16
	global_load_dwordx4 v[102:105], v[86:87], off
	global_load_dwordx4 v[78:81], v[86:87], off offset:528
	s_nop 0
	global_load_dwordx4 v[86:89], v[86:87], off offset:512
	v_lshl_add_u32 v130, s10, 8, v229
	v_or_b32_e32 v128, 16, v130
	v_or_b32_e32 v126, 32, v130
	v_or_b32_e32 v122, 48, v130
	s_cmp_eq_u32 s11, 0
	v_ashrrev_i32_e32 v131, 31, v130
	v_ashrrev_i32_e32 v129, 31, v128
	v_ashrrev_i32_e32 v127, 31, v126
	v_ashrrev_i32_e32 v123, 31, v122
	s_cbranch_scc1 .LBB0_1120
	s_add_i32 s96, s11, -1
	s_lshl_b64 s[10:11], s[96:97], 20
	v_readlane_b32 s14, v252, 11
	v_readlane_b32 s15, v252, 12
	s_add_u32 s10, s14, s10
	s_addc_u32 s11, s15, s11
	v_lshlrev_b64 v[132:133], 2, v[124:125]
	v_lshrrev_b32_e32 v134, 5, v220
	v_mul_u32_u24_e32 v134, 48, v134
	s_nop 0
	v_sub_co_u32_e32 v132, vcc, v132, v134
	s_nop 1
	v_subbrev_co_u32_e32 v133, vcc, 0, v133, vcc
	v_lshl_add_u64 v[132:133], s[10:11], 0, v[132:133]
	s_mov_b64 s[10:11], 0x80000
	v_lshlrev_b64 v[204:205], 12, v[130:131]
	v_lshl_add_u64 v[204:205], v[204:205], 0, v[132:133]
	v_lshl_add_u64 v[212:213], v[204:205], 0, s[10:11]
	v_lshlrev_b64 v[206:207], 12, v[128:129]
	v_lshl_add_u64 v[206:207], v[206:207], 0, v[132:133]
	v_lshl_add_u64 v[214:215], v[206:207], 0, s[10:11]
	v_lshlrev_b64 v[208:209], 12, v[126:127]
	v_lshl_add_u64 v[208:209], v[208:209], 0, v[132:133]
	v_lshl_add_u64 v[216:217], v[208:209], 0, s[10:11]
	v_lshlrev_b64 v[210:211], 12, v[122:123]
	v_lshl_add_u64 v[210:211], v[210:211], 0, v[132:133]
	v_lshl_add_u64 v[218:219], v[210:211], 0, s[10:11]
	s_waitcnt vmcnt(0)
	v_pk_mul_f32 v[172:173], v[166:167], v[102:103]
	v_pk_mul_f32 v[174:175], v[168:169], v[104:105]
	v_pk_mul_f32 v[176:177], v[162:163], v[94:95]
	v_pk_mul_f32 v[178:179], v[164:165], v[96:97]
	s_nop 1
	v_permlane32_swap_b32_e32 v172, v176
	v_permlane32_swap_b32_e32 v173, v177
	v_permlane32_swap_b32_e32 v174, v178
	v_permlane32_swap_b32_e32 v175, v179
	s_nop 0
	global_store_dwordx4 v[204:205], v[172:175], off
	global_store_dwordx4 v[204:205], v[176:179], off offset:64
	v_pk_mul_f32 v[180:181], v[146:147], v[86:87]
	v_pk_mul_f32 v[182:183], v[148:149], v[88:89]
	v_pk_mul_f32 v[184:185], v[138:139], v[78:79]
	v_pk_mul_f32 v[186:187], v[140:141], v[80:81]
	s_nop 1
	v_permlane32_swap_b32_e32 v180, v184
	v_permlane32_swap_b32_e32 v181, v185
	v_permlane32_swap_b32_e32 v182, v186
	v_permlane32_swap_b32_e32 v183, v187
	s_nop 0
	global_store_dwordx4 v[204:205], v[180:183], off offset:512
	global_store_dwordx4 v[204:205], v[184:187], off offset:576
	v_pk_mul_f32 v[188:189], v[150:151], v[102:103]
	v_pk_mul_f32 v[190:191], v[152:153], v[104:105]
	v_pk_mul_f32 v[192:193], v[142:143], v[94:95]
	v_pk_mul_f32 v[194:195], v[144:145], v[96:97]
	s_nop 1
	v_permlane32_swap_b32_e32 v188, v192
	v_permlane32_swap_b32_e32 v189, v193
	v_permlane32_swap_b32_e32 v190, v194
	v_permlane32_swap_b32_e32 v191, v195
	s_nop 0
	global_store_dwordx4 v[206:207], v[188:191], off
	global_store_dwordx4 v[206:207], v[192:195], off offset:64
	v_pk_mul_f32 v[154:155], v[118:119], v[86:87]
	v_pk_mul_f32 v[156:157], v[120:121], v[88:89]
	v_pk_mul_f32 v[158:159], v[114:115], v[78:79]
	v_pk_mul_f32 v[160:161], v[116:117], v[80:81]
	s_nop 1
	v_permlane32_swap_b32_e32 v154, v158
	v_permlane32_swap_b32_e32 v155, v159
	v_permlane32_swap_b32_e32 v156, v160
	v_permlane32_swap_b32_e32 v157, v161
	s_nop 0
	global_store_dwordx4 v[206:207], v[154:157], off offset:512
	global_store_dwordx4 v[206:207], v[158:161], off offset:576
	v_pk_mul_f32 v[172:173], v[110:111], v[102:103]
	v_pk_mul_f32 v[174:175], v[112:113], v[104:105]
	v_pk_mul_f32 v[176:177], v[106:107], v[94:95]
	v_pk_mul_f32 v[178:179], v[108:109], v[96:97]
	s_nop 1
	v_permlane32_swap_b32_e32 v172, v176
	v_permlane32_swap_b32_e32 v173, v177
	v_permlane32_swap_b32_e32 v174, v178
	v_permlane32_swap_b32_e32 v175, v179
	s_nop 0
	global_store_dwordx4 v[208:209], v[172:175], off
	global_store_dwordx4 v[208:209], v[176:179], off offset:64
	v_pk_mul_f32 v[180:181], v[98:99], v[86:87]
	v_pk_mul_f32 v[182:183], v[100:101], v[88:89]
	v_pk_mul_f32 v[184:185], v[90:91], v[78:79]
	v_pk_mul_f32 v[186:187], v[92:93], v[80:81]
	s_nop 1
	v_permlane32_swap_b32_e32 v180, v184
	v_permlane32_swap_b32_e32 v181, v185
	v_permlane32_swap_b32_e32 v182, v186
	v_permlane32_swap_b32_e32 v183, v187
	s_nop 0
	global_store_dwordx4 v[208:209], v[180:183], off offset:512
	global_store_dwordx4 v[208:209], v[184:187], off offset:576
	v_pk_mul_f32 v[188:189], v[82:83], v[102:103]
	v_pk_mul_f32 v[190:191], v[84:85], v[104:105]
	v_pk_mul_f32 v[192:193], v[74:75], v[94:95]
	v_pk_mul_f32 v[194:195], v[76:77], v[96:97]
	s_nop 1
	v_permlane32_swap_b32_e32 v188, v192
	v_permlane32_swap_b32_e32 v189, v193
	v_permlane32_swap_b32_e32 v190, v194
	v_permlane32_swap_b32_e32 v191, v195
	s_nop 0
	global_store_dwordx4 v[210:211], v[188:191], off
	global_store_dwordx4 v[210:211], v[192:195], off offset:64
	v_pk_mul_f32 v[154:155], v[70:71], v[86:87]
	v_pk_mul_f32 v[156:157], v[72:73], v[88:89]
	v_pk_mul_f32 v[158:159], v[66:67], v[78:79]
	v_pk_mul_f32 v[160:161], v[68:69], v[80:81]
	s_nop 1
	v_permlane32_swap_b32_e32 v154, v158
	v_permlane32_swap_b32_e32 v155, v159
	v_permlane32_swap_b32_e32 v156, v160
	v_permlane32_swap_b32_e32 v157, v161
	s_nop 0
	global_store_dwordx4 v[210:211], v[154:157], off offset:512
	global_store_dwordx4 v[210:211], v[158:161], off offset:576
	v_pk_mul_f32 v[172:173], v[62:63], v[102:103]
	v_pk_mul_f32 v[174:175], v[64:65], v[104:105]
	v_pk_mul_f32 v[176:177], v[58:59], v[94:95]
	v_pk_mul_f32 v[178:179], v[60:61], v[96:97]
	s_nop 1
	v_permlane32_swap_b32_e32 v172, v176
	v_permlane32_swap_b32_e32 v173, v177
	v_permlane32_swap_b32_e32 v174, v178
	v_permlane32_swap_b32_e32 v175, v179
	s_nop 0
	global_store_dwordx4 v[212:213], v[172:175], off
	global_store_dwordx4 v[212:213], v[176:179], off offset:64
	v_pk_mul_f32 v[180:181], v[54:55], v[86:87]
	v_pk_mul_f32 v[182:183], v[56:57], v[88:89]
	v_pk_mul_f32 v[184:185], v[50:51], v[78:79]
	v_pk_mul_f32 v[186:187], v[52:53], v[80:81]
	s_nop 1
	v_permlane32_swap_b32_e32 v180, v184
	v_permlane32_swap_b32_e32 v181, v185
	v_permlane32_swap_b32_e32 v182, v186
	v_permlane32_swap_b32_e32 v183, v187
	s_nop 0
	global_store_dwordx4 v[212:213], v[180:183], off offset:512
	global_store_dwordx4 v[212:213], v[184:187], off offset:576
	v_pk_mul_f32 v[188:189], v[46:47], v[102:103]
	v_pk_mul_f32 v[190:191], v[48:49], v[104:105]
	v_pk_mul_f32 v[192:193], v[42:43], v[94:95]
	v_pk_mul_f32 v[194:195], v[44:45], v[96:97]
	s_nop 1
	v_permlane32_swap_b32_e32 v188, v192
	v_permlane32_swap_b32_e32 v189, v193
	v_permlane32_swap_b32_e32 v190, v194
	v_permlane32_swap_b32_e32 v191, v195
	s_nop 0
	global_store_dwordx4 v[214:215], v[188:191], off
	global_store_dwordx4 v[214:215], v[192:195], off offset:64
	v_pk_mul_f32 v[154:155], v[38:39], v[86:87]
	v_pk_mul_f32 v[156:157], v[40:41], v[88:89]
	v_pk_mul_f32 v[158:159], v[34:35], v[78:79]
	v_pk_mul_f32 v[160:161], v[36:37], v[80:81]
	s_nop 1
	v_permlane32_swap_b32_e32 v154, v158
	v_permlane32_swap_b32_e32 v155, v159
	v_permlane32_swap_b32_e32 v156, v160
	v_permlane32_swap_b32_e32 v157, v161
	s_nop 0
	global_store_dwordx4 v[214:215], v[154:157], off offset:512
	global_store_dwordx4 v[214:215], v[158:161], off offset:576
	v_pk_mul_f32 v[172:173], v[28:29], v[102:103]
	v_pk_mul_f32 v[174:175], v[30:31], v[104:105]
	v_pk_mul_f32 v[176:177], v[24:25], v[94:95]
	v_pk_mul_f32 v[178:179], v[26:27], v[96:97]
	s_nop 1
	v_permlane32_swap_b32_e32 v172, v176
	v_permlane32_swap_b32_e32 v173, v177
	v_permlane32_swap_b32_e32 v174, v178
	v_permlane32_swap_b32_e32 v175, v179
	s_nop 0
	global_store_dwordx4 v[216:217], v[172:175], off
	global_store_dwordx4 v[216:217], v[176:179], off offset:64
	v_pk_mul_f32 v[180:181], v[20:21], v[86:87]
	v_pk_mul_f32 v[182:183], v[22:23], v[88:89]
	v_pk_mul_f32 v[184:185], v[16:17], v[78:79]
	v_pk_mul_f32 v[186:187], v[18:19], v[80:81]
	s_nop 1
	v_permlane32_swap_b32_e32 v180, v184
	v_permlane32_swap_b32_e32 v181, v185
	v_permlane32_swap_b32_e32 v182, v186
	v_permlane32_swap_b32_e32 v183, v187
	s_nop 0
	global_store_dwordx4 v[216:217], v[180:183], off offset:512
	global_store_dwordx4 v[216:217], v[184:187], off offset:576
	v_pk_mul_f32 v[188:189], v[12:13], v[102:103]
	v_pk_mul_f32 v[190:191], v[14:15], v[104:105]
	v_pk_mul_f32 v[192:193], v[8:9], v[94:95]
	v_pk_mul_f32 v[194:195], v[10:11], v[96:97]
	s_nop 1
	v_permlane32_swap_b32_e32 v188, v192
	v_permlane32_swap_b32_e32 v189, v193
	v_permlane32_swap_b32_e32 v190, v194
	v_permlane32_swap_b32_e32 v191, v195
	s_nop 0
	global_store_dwordx4 v[218:219], v[188:191], off
	global_store_dwordx4 v[218:219], v[192:195], off offset:64
	v_pk_mul_f32 v[154:155], v[4:5], v[86:87]
	v_pk_mul_f32 v[156:157], v[6:7], v[88:89]
	v_pk_mul_f32 v[158:159], v[0:1], v[78:79]
	v_pk_mul_f32 v[160:161], v[2:3], v[80:81]
	s_nop 1
	v_permlane32_swap_b32_e32 v154, v158
	v_permlane32_swap_b32_e32 v155, v159
	v_permlane32_swap_b32_e32 v156, v160
	v_permlane32_swap_b32_e32 v157, v161
	s_nop 0
	global_store_dwordx4 v[218:219], v[154:157], off offset:512
	global_store_dwordx4 v[218:219], v[158:161], off offset:576
	s_cbranch_execnz .LBB0_1104
	s_branch .LBB0_1103

.LBB0_1276:
	s_add_u32 s16, s14, 0x100
	s_addc_u32 s17, s15, 0
	s_add_i32 s39, 0, 0x10000
	v_add_u32_e32 v152, s39, v137
	ds_read_b128 v[140:143], v152
	ds_read_b128 v[148:151], v152 offset:2048
	ds_read_b128 v[144:147], v152 offset:1024
	ds_read_b128 v[152:155], v152 offset:3072
	s_cmp_eq_u32 s38, 12
	s_cselect_b32 s21, s11, s17
	s_cselect_b32 s20, s10, s16
	s_cselect_b32 s19, s13, s37
	s_cselect_b32 s18, s12, s3
	v_lshl_add_u64 v[188:189], s[14:15], 0, v[132:133]
	s_add_i32 m0, s9, 0xc000
	ds_read_b128 v[156:159], v139
	ds_read_b128 v[164:167], v139 offset:2048
	ds_read_b128 v[172:175], v139 offset:4096
	ds_read_b128 v[180:183], v139 offset:6144
	ds_read_b128 v[160:163], v139 offset:1024
	ds_read_b128 v[168:171], v139 offset:3072
	ds_read_b128 v[176:179], v139 offset:5120
	ds_read_b128 v[184:187], v139 offset:7168
	global_load_lds_dwordx4 v[188:189], off
	v_lshl_add_u64 v[188:189], s[14:15], 0, v[134:135]
	s_add_i32 m0, s9, 0xe000
	s_nop 0
	global_load_lds_dwordx4 v[188:189], off
	s_waitcnt lgkmcnt(8)
	s_barrier
	s_waitcnt lgkmcnt(7)
	s_setprio 1
	v_mfma_f32_16x16x32_f16 v[126:129], v[140:143], v[156:159], v[126:129]
	v_mfma_f32_16x16x32_f16 v[122:125], v[148:151], v[156:159], v[122:125]
	s_waitcnt lgkmcnt(6)
	v_mfma_f32_16x16x32_f16 v[110:113], v[140:143], v[164:167], v[110:113]
	v_mfma_f32_16x16x32_f16 v[106:109], v[148:151], v[164:167], v[106:109]
	s_waitcnt lgkmcnt(5)
	v_mfma_f32_16x16x32_f16 v[94:97], v[140:143], v[172:175], v[94:97]
	v_mfma_f32_16x16x32_f16 v[90:93], v[148:151], v[172:175], v[90:93]
	s_waitcnt lgkmcnt(4)
	v_mfma_f32_16x16x32_f16 v[78:81], v[140:143], v[180:183], v[78:81]
	v_mfma_f32_16x16x32_f16 v[74:77], v[148:151], v[180:183], v[74:77]
	s_waitcnt lgkmcnt(3)
	v_mfma_f32_16x16x32_f16 v[126:129], v[144:147], v[160:163], v[126:129]
	v_mfma_f32_16x16x32_f16 v[122:125], v[152:155], v[160:163], v[122:125]
	s_waitcnt lgkmcnt(2)
	v_mfma_f32_16x16x32_f16 v[110:113], v[144:147], v[168:171], v[110:113]
	v_mfma_f32_16x16x32_f16 v[106:109], v[152:155], v[168:171], v[106:109]
	s_waitcnt lgkmcnt(1)
	v_mfma_f32_16x16x32_f16 v[94:97], v[144:147], v[176:179], v[94:97]
	v_mfma_f32_16x16x32_f16 v[90:93], v[152:155], v[176:179], v[90:93]
	s_waitcnt lgkmcnt(0)
	v_mfma_f32_16x16x32_f16 v[78:81], v[144:147], v[184:187], v[78:81]
	v_mfma_f32_16x16x32_f16 v[74:77], v[152:155], v[184:187], v[74:77]
	s_setprio 0
	s_barrier
	s_add_i32 s40, 0, 0x14000
	s_add_i32 s14, s39, s26
	v_add_u32_e32 v200, s40, v137
	v_lshl_add_u64 v[204:205], s[18:19], 0, v[32:33]
	s_mov_b32 m0, s14
	ds_read_b128 v[188:191], v200
	ds_read_b128 v[196:199], v200 offset:2048
	ds_read_b128 v[192:195], v200 offset:1024
	ds_read_b128 v[200:203], v200 offset:3072
	global_load_lds_dwordx4 v[204:205], off
	v_lshl_add_u64 v[206:207], s[18:19], 0, v[130:131]
	s_add_i32 m0, s14, 0x2000
	s_nop 0
	global_load_lds_dwordx4 v[206:207], off
	s_barrier
	s_waitcnt lgkmcnt(2)
	s_setprio 1
	v_mfma_f32_16x16x32_f16 v[118:121], v[188:191], v[156:159], v[118:121]
	v_mfma_f32_16x16x32_f16 v[114:117], v[196:199], v[156:159], v[114:117]
	v_mfma_f32_16x16x32_f16 v[102:105], v[188:191], v[164:167], v[102:105]
	v_mfma_f32_16x16x32_f16 v[98:101], v[196:199], v[164:167], v[98:101]
	v_mfma_f32_16x16x32_f16 v[86:89], v[188:191], v[172:175], v[86:89]
	v_mfma_f32_16x16x32_f16 v[82:85], v[196:199], v[172:175], v[82:85]
	v_mfma_f32_16x16x32_f16 v[70:73], v[188:191], v[180:183], v[70:73]
	v_mfma_f32_16x16x32_f16 v[66:69], v[196:199], v[180:183], v[66:69]
	s_waitcnt lgkmcnt(0)
	v_mfma_f32_16x16x32_f16 v[118:121], v[192:195], v[160:163], v[118:121]
	v_mfma_f32_16x16x32_f16 v[114:117], v[200:203], v[160:163], v[114:117]
	v_mfma_f32_16x16x32_f16 v[102:105], v[192:195], v[168:171], v[102:105]
	v_mfma_f32_16x16x32_f16 v[98:101], v[200:203], v[168:171], v[98:101]
	v_mfma_f32_16x16x32_f16 v[86:89], v[192:195], v[176:179], v[86:89]
	v_mfma_f32_16x16x32_f16 v[82:85], v[200:203], v[176:179], v[82:85]
	v_mfma_f32_16x16x32_f16 v[70:73], v[192:195], v[184:187], v[70:73]
	v_mfma_f32_16x16x32_f16 v[66:69], v[200:203], v[184:187], v[66:69]
	s_setprio 0
	s_mov_b32 m0, s9
	v_lshl_add_u64 v[208:209], s[20:21], 0, v[32:33]
	s_barrier
	ds_read_b128 v[156:159], v139 offset:16384
	ds_read_b128 v[164:167], v139 offset:18432
	ds_read_b128 v[172:175], v139 offset:20480
	ds_read_b128 v[180:183], v139 offset:22528
	ds_read_b128 v[160:163], v139 offset:17408
	ds_read_b128 v[168:171], v139 offset:19456
	ds_read_b128 v[176:179], v139 offset:21504
	ds_read_b128 v[184:187], v139 offset:23552
	global_load_lds_dwordx4 v[208:209], off
	v_lshl_add_u64 v[210:211], s[20:21], 0, v[130:131]
	s_mov_b32 m0, s27
	s_nop 0
	global_load_lds_dwordx4 v[210:211], off
	s_barrier
	s_waitcnt lgkmcnt(7)
	s_setprio 1
	v_mfma_f32_16x16x32_f16 v[62:65], v[140:143], v[156:159], v[62:65]
	v_mfma_f32_16x16x32_f16 v[58:61], v[148:151], v[156:159], v[58:61]
	s_waitcnt lgkmcnt(6)
	v_mfma_f32_16x16x32_f16 v[46:49], v[140:143], v[164:167], v[46:49]
	v_mfma_f32_16x16x32_f16 v[42:45], v[148:151], v[164:167], v[42:45]
	s_waitcnt lgkmcnt(5)
	v_mfma_f32_16x16x32_f16 v[28:31], v[140:143], v[172:175], v[28:31]
	v_mfma_f32_16x16x32_f16 v[24:27], v[148:151], v[172:175], v[24:27]
	s_waitcnt lgkmcnt(4)
	v_mfma_f32_16x16x32_f16 v[12:15], v[140:143], v[180:183], v[12:15]
	v_mfma_f32_16x16x32_f16 v[8:11], v[148:151], v[180:183], v[8:11]
	s_waitcnt lgkmcnt(3)
	v_mfma_f32_16x16x32_f16 v[62:65], v[144:147], v[160:163], v[62:65]
	v_mfma_f32_16x16x32_f16 v[58:61], v[152:155], v[160:163], v[58:61]
	s_waitcnt lgkmcnt(2)
	v_mfma_f32_16x16x32_f16 v[46:49], v[144:147], v[168:171], v[46:49]
	v_mfma_f32_16x16x32_f16 v[42:45], v[152:155], v[168:171], v[42:45]
	s_waitcnt lgkmcnt(1)
	v_mfma_f32_16x16x32_f16 v[28:31], v[144:147], v[176:179], v[28:31]
	v_mfma_f32_16x16x32_f16 v[24:27], v[152:155], v[176:179], v[24:27]
	s_waitcnt lgkmcnt(0)
	v_mfma_f32_16x16x32_f16 v[12:15], v[144:147], v[184:187], v[12:15]
	v_mfma_f32_16x16x32_f16 v[8:11], v[152:155], v[184:187], v[8:11]
	s_setprio 0
	s_barrier
	s_add_u32 s14, s18, 0x40000
	s_addc_u32 s15, s19, 0
	s_add_i32 s39, s40, s26
	v_lshl_add_u64 v[140:141], s[14:15], 0, v[32:33]
	s_mov_b32 m0, s39
	s_nop 0
	global_load_lds_dwordx4 v[140:141], off
	v_lshl_add_u64 v[140:141], s[14:15], 0, v[130:131]
	s_add_i32 m0, s39, 0x2000
	s_nop 0
	global_load_lds_dwordx4 v[140:141], off
	s_waitcnt vmcnt(10)
	s_barrier
	s_setprio 1
	v_mfma_f32_16x16x32_f16 v[54:57], v[188:191], v[156:159], v[54:57]
	v_mfma_f32_16x16x32_f16 v[50:53], v[196:199], v[156:159], v[50:53]
	v_mfma_f32_16x16x32_f16 v[38:41], v[188:191], v[164:167], v[38:41]
	v_mfma_f32_16x16x32_f16 v[34:37], v[196:199], v[164:167], v[34:37]
	v_mfma_f32_16x16x32_f16 v[20:23], v[188:191], v[172:175], v[20:23]
	v_mfma_f32_16x16x32_f16 v[16:19], v[196:199], v[172:175], v[16:19]
	v_mfma_f32_16x16x32_f16 v[4:7], v[188:191], v[180:183], v[4:7]
	v_mfma_f32_16x16x32_f16 v[0:3], v[196:199], v[180:183], v[0:3]
	v_mfma_f32_16x16x32_f16 v[54:57], v[192:195], v[160:163], v[54:57]
	v_mfma_f32_16x16x32_f16 v[50:53], v[200:203], v[160:163], v[50:53]
	v_mfma_f32_16x16x32_f16 v[38:41], v[192:195], v[168:171], v[38:41]
	v_mfma_f32_16x16x32_f16 v[34:37], v[200:203], v[168:171], v[34:37]
	v_mfma_f32_16x16x32_f16 v[20:23], v[192:195], v[176:179], v[20:23]
	v_mfma_f32_16x16x32_f16 v[16:19], v[200:203], v[176:179], v[16:19]
	v_mfma_f32_16x16x32_f16 v[4:7], v[192:195], v[184:187], v[4:7]
	v_mfma_f32_16x16x32_f16 v[0:3], v[200:203], v[184:187], v[0:3]
	s_setprio 0
	s_add_i32 s39, 0, 0x18000
	v_add_u32_e32 v152, s39, v137
	s_barrier
	ds_read_b128 v[140:143], v152
	ds_read_b128 v[148:151], v152 offset:2048
	ds_read_b128 v[144:147], v152 offset:1024
	ds_read_b128 v[152:155], v152 offset:3072
	s_add_u32 s14, s20, 0x40000
	s_addc_u32 s15, s21, 0
	s_mov_b32 m0, s28
	v_lshl_add_u64 v[188:189], s[14:15], 0, v[32:33]
	ds_read_b128 v[156:159], v139 offset:32768
	ds_read_b128 v[164:167], v139 offset:34816
	ds_read_b128 v[172:175], v139 offset:36864
	ds_read_b128 v[180:183], v139 offset:38912
	ds_read_b128 v[160:163], v139 offset:33792
	ds_read_b128 v[168:171], v139 offset:35840
	ds_read_b128 v[176:179], v139 offset:37888
	ds_read_b128 v[184:187], v139 offset:39936
	global_load_lds_dwordx4 v[188:189], off
	v_lshl_add_u64 v[188:189], s[14:15], 0, v[130:131]
	s_mov_b32 m0, s29
	s_nop 0
	global_load_lds_dwordx4 v[188:189], off
	s_waitcnt lgkmcnt(8)
	s_waitcnt vmcnt(10)
	s_barrier
	s_waitcnt lgkmcnt(7)
	s_setprio 1
	v_mfma_f32_16x16x32_f16 v[126:129], v[140:143], v[156:159], v[126:129]
	v_mfma_f32_16x16x32_f16 v[122:125], v[148:151], v[156:159], v[122:125]
	s_waitcnt lgkmcnt(6)
	v_mfma_f32_16x16x32_f16 v[110:113], v[140:143], v[164:167], v[110:113]
	v_mfma_f32_16x16x32_f16 v[106:109], v[148:151], v[164:167], v[106:109]
	s_waitcnt lgkmcnt(5)
	v_mfma_f32_16x16x32_f16 v[94:97], v[140:143], v[172:175], v[94:97]
	v_mfma_f32_16x16x32_f16 v[90:93], v[148:151], v[172:175], v[90:93]
	s_waitcnt lgkmcnt(4)
	v_mfma_f32_16x16x32_f16 v[78:81], v[140:143], v[180:183], v[78:81]
	v_mfma_f32_16x16x32_f16 v[74:77], v[148:151], v[180:183], v[74:77]
	s_waitcnt lgkmcnt(3)
	v_mfma_f32_16x16x32_f16 v[126:129], v[144:147], v[160:163], v[126:129]
	v_mfma_f32_16x16x32_f16 v[122:125], v[152:155], v[160:163], v[122:125]
	s_waitcnt lgkmcnt(2)
	v_mfma_f32_16x16x32_f16 v[110:113], v[144:147], v[168:171], v[110:113]
	v_mfma_f32_16x16x32_f16 v[106:109], v[152:155], v[168:171], v[106:109]
	s_waitcnt lgkmcnt(1)
	v_mfma_f32_16x16x32_f16 v[94:97], v[144:147], v[176:179], v[94:97]
	v_mfma_f32_16x16x32_f16 v[90:93], v[152:155], v[176:179], v[90:93]
	s_waitcnt lgkmcnt(0)
	v_mfma_f32_16x16x32_f16 v[78:81], v[144:147], v[184:187], v[78:81]
	v_mfma_f32_16x16x32_f16 v[74:77], v[152:155], v[184:187], v[74:77]
	s_setprio 0
	s_barrier
	s_add_i32 s20, 0, 0x1c000
	s_add_i32 s14, s39, s26
	v_add_u32_e32 v200, s20, v137
	v_lshl_add_u64 v[204:205], v[204:205], 0, s[84:85]
	s_mov_b32 m0, s14
	ds_read_b128 v[188:191], v200
	ds_read_b128 v[196:199], v200 offset:2048
	ds_read_b128 v[192:195], v200 offset:1024
	ds_read_b128 v[200:203], v200 offset:3072
	global_load_lds_dwordx4 v[204:205], off
	v_lshl_add_u64 v[204:205], v[206:207], 0, s[84:85]
	s_add_i32 m0, s14, 0x2000
	s_nop 0
	global_load_lds_dwordx4 v[204:205], off
	s_waitcnt vmcnt(10)
	s_barrier
	s_waitcnt lgkmcnt(2)
	s_setprio 1
	v_mfma_f32_16x16x32_f16 v[118:121], v[188:191], v[156:159], v[118:121]
	v_mfma_f32_16x16x32_f16 v[114:117], v[196:199], v[156:159], v[114:117]
	v_mfma_f32_16x16x32_f16 v[102:105], v[188:191], v[164:167], v[102:105]
	v_mfma_f32_16x16x32_f16 v[98:101], v[196:199], v[164:167], v[98:101]
	v_mfma_f32_16x16x32_f16 v[86:89], v[188:191], v[172:175], v[86:89]
	v_mfma_f32_16x16x32_f16 v[82:85], v[196:199], v[172:175], v[82:85]
	v_mfma_f32_16x16x32_f16 v[70:73], v[188:191], v[180:183], v[70:73]
	v_mfma_f32_16x16x32_f16 v[66:69], v[196:199], v[180:183], v[66:69]
	s_waitcnt lgkmcnt(0)
	v_mfma_f32_16x16x32_f16 v[118:121], v[192:195], v[160:163], v[118:121]
	v_mfma_f32_16x16x32_f16 v[114:117], v[200:203], v[160:163], v[114:117]
	v_mfma_f32_16x16x32_f16 v[102:105], v[192:195], v[168:171], v[102:105]
	v_mfma_f32_16x16x32_f16 v[98:101], v[200:203], v[168:171], v[98:101]
	v_mfma_f32_16x16x32_f16 v[86:89], v[192:195], v[176:179], v[86:89]
	v_mfma_f32_16x16x32_f16 v[82:85], v[200:203], v[176:179], v[82:85]
	v_mfma_f32_16x16x32_f16 v[70:73], v[192:195], v[184:187], v[70:73]
	v_mfma_f32_16x16x32_f16 v[66:69], v[200:203], v[184:187], v[66:69]
	s_setprio 0
	s_mov_b32 m0, s30
	v_lshl_add_u64 v[204:205], v[208:209], 0, s[84:85]
	s_barrier
	ds_read_b128 v[156:159], v139 offset:49152
	ds_read_b128 v[164:167], v139 offset:51200
	ds_read_b128 v[172:175], v139 offset:53248
	ds_read_b128 v[180:183], v139 offset:55296
	ds_read_b128 v[160:163], v139 offset:50176
	ds_read_b128 v[168:171], v139 offset:52224
	ds_read_b128 v[176:179], v139 offset:54272
	ds_read_b128 v[184:187], v139 offset:56320
	global_load_lds_dwordx4 v[204:205], off
	v_lshl_add_u64 v[204:205], v[210:211], 0, s[84:85]
	s_mov_b32 m0, s31
	s_nop 0
	global_load_lds_dwordx4 v[204:205], off
	s_barrier
	s_waitcnt lgkmcnt(7)
	s_setprio 1
	v_mfma_f32_16x16x32_f16 v[62:65], v[140:143], v[156:159], v[62:65]
	v_mfma_f32_16x16x32_f16 v[58:61], v[148:151], v[156:159], v[58:61]
	s_waitcnt lgkmcnt(6)
	v_mfma_f32_16x16x32_f16 v[46:49], v[140:143], v[164:167], v[46:49]
	v_mfma_f32_16x16x32_f16 v[42:45], v[148:151], v[164:167], v[42:45]
	s_waitcnt lgkmcnt(5)
	v_mfma_f32_16x16x32_f16 v[28:31], v[140:143], v[172:175], v[28:31]
	v_mfma_f32_16x16x32_f16 v[24:27], v[148:151], v[172:175], v[24:27]
	s_waitcnt lgkmcnt(4)
	v_mfma_f32_16x16x32_f16 v[12:15], v[140:143], v[180:183], v[12:15]
	v_mfma_f32_16x16x32_f16 v[8:11], v[148:151], v[180:183], v[8:11]
	s_waitcnt lgkmcnt(3)
	v_mfma_f32_16x16x32_f16 v[62:65], v[144:147], v[160:163], v[62:65]
	v_mfma_f32_16x16x32_f16 v[58:61], v[152:155], v[160:163], v[58:61]
	s_waitcnt lgkmcnt(2)
	v_mfma_f32_16x16x32_f16 v[46:49], v[144:147], v[168:171], v[46:49]
	v_mfma_f32_16x16x32_f16 v[42:45], v[152:155], v[168:171], v[42:45]
	s_waitcnt lgkmcnt(1)
	v_mfma_f32_16x16x32_f16 v[28:31], v[144:147], v[176:179], v[28:31]
	v_mfma_f32_16x16x32_f16 v[24:27], v[152:155], v[176:179], v[24:27]
	s_waitcnt lgkmcnt(0)
	v_mfma_f32_16x16x32_f16 v[12:15], v[144:147], v[184:187], v[12:15]
	v_mfma_f32_16x16x32_f16 v[8:11], v[152:155], v[184:187], v[8:11]
	s_setprio 0
	s_barrier
	s_add_u32 s14, s18, 0x40080
	s_addc_u32 s15, s19, 0
	s_add_i32 s18, s20, s26
	v_lshl_add_u64 v[140:141], s[14:15], 0, v[32:33]
	s_mov_b32 m0, s18
	s_nop 0
	global_load_lds_dwordx4 v[140:141], off
	v_lshl_add_u64 v[140:141], s[14:15], 0, v[130:131]
	s_add_i32 m0, s18, 0x2000
	s_nop 0
	global_load_lds_dwordx4 v[140:141], off
	s_waitcnt vmcnt(6)
	s_barrier
	s_setprio 1
	v_mfma_f32_16x16x32_f16 v[54:57], v[188:191], v[156:159], v[54:57]
	v_mfma_f32_16x16x32_f16 v[50:53], v[196:199], v[156:159], v[50:53]
	v_mfma_f32_16x16x32_f16 v[38:41], v[188:191], v[164:167], v[38:41]
	v_mfma_f32_16x16x32_f16 v[34:37], v[196:199], v[164:167], v[34:37]
	v_mfma_f32_16x16x32_f16 v[20:23], v[188:191], v[172:175], v[20:23]
	v_mfma_f32_16x16x32_f16 v[16:19], v[196:199], v[172:175], v[16:19]
	v_mfma_f32_16x16x32_f16 v[4:7], v[188:191], v[180:183], v[4:7]
	v_mfma_f32_16x16x32_f16 v[0:3], v[196:199], v[180:183], v[0:3]
	v_mfma_f32_16x16x32_f16 v[54:57], v[192:195], v[160:163], v[54:57]
	v_mfma_f32_16x16x32_f16 v[50:53], v[200:203], v[160:163], v[50:53]
	v_mfma_f32_16x16x32_f16 v[38:41], v[192:195], v[168:171], v[38:41]
	v_mfma_f32_16x16x32_f16 v[34:37], v[200:203], v[168:171], v[34:37]
	v_mfma_f32_16x16x32_f16 v[20:23], v[192:195], v[176:179], v[20:23]
	v_mfma_f32_16x16x32_f16 v[16:19], v[200:203], v[176:179], v[16:19]
	v_mfma_f32_16x16x32_f16 v[4:7], v[192:195], v[184:187], v[4:7]
	v_mfma_f32_16x16x32_f16 v[0:3], v[200:203], v[184:187], v[0:3]
	s_setprio 0
	s_add_i32 s38, s38, 2
	s_add_u32 s3, s3, 0x100
	s_addc_u32 s37, s37, 0
	s_cmp_gt_u32 s38, 13
	s_mov_b64 s[14:15], s[16:17]
	s_barrier
	s_cbranch_scc0 .LBB0_1276
	v_mul_f32_e32 v144, 0xbfb8aa3b, v127
	v_mul_f32_e32 v141, 0xbfb8aa3b, v126
	v_exp_f32_e32 v145, v144
	v_mul_f32_e32 v144, 0xbfb8aa3b, v128
	v_exp_f32_e32 v141, v141
	v_exp_f32_e32 v146, v144
	v_mul_f32_e32 v144, 0xbfb8aa3b, v129
	v_exp_f32_e32 v147, v144
	v_mul_f32_e32 v144, 0xbfb8aa3b, v122
	v_exp_f32_e32 v148, v144
	v_mul_f32_e32 v144, 0xbfb8aa3b, v123
	v_exp_f32_e32 v149, v144
	v_mul_f32_e32 v144, 0xbfb8aa3b, v124
	v_exp_f32_e32 v150, v144
	v_mul_f32_e32 v144, 0xbfb8aa3b, v125
	v_add_f32_e32 v141, 1.0, v141
	v_exp_f32_e32 v151, v144
	v_rcp_f32_e32 v144, v141
	v_add_f32_e32 v141, 1.0, v145
	v_rcp_f32_e32 v145, v141
	v_add_f32_e32 v141, 1.0, v146
	v_rcp_f32_e32 v146, v141
	v_add_f32_e32 v141, 1.0, v147
	v_rcp_f32_e32 v147, v141
	v_add_f32_e32 v141, 1.0, v148
	v_rcp_f32_e32 v148, v141
	v_add_f32_e32 v141, 1.0, v149
	v_rcp_f32_e32 v149, v141
	v_add_f32_e32 v141, 1.0, v150
	v_rcp_f32_e32 v150, v141
	v_add_f32_e32 v141, 1.0, v151
	v_pk_mul_f32 v[126:127], v[126:127], v[144:145]
	v_rcp_f32_e32 v151, v141
	v_pk_mul_f32 v[118:119], v[126:127], v[118:119]
	v_pk_mul_f32 v[126:127], v[128:129], v[146:147]
	v_cvt_pk_f16_f32 v118, v118, v119
	v_pk_mul_f32 v[120:121], v[126:127], v[120:121]
	v_lshl_or_b32 v142, s36, 7, v138
	v_cvt_pk_f16_f32 v119, v120, v121
	v_pk_mul_f32 v[120:121], v[122:123], v[148:149]
	v_lshl_add_u32 v140, s8, 8, v136
	v_pk_mul_f32 v[114:115], v[120:121], v[114:115]
	v_ashrrev_i32_e32 v143, 31, v142
	v_cvt_pk_f16_f32 v120, v114, v115
	v_pk_mul_f32 v[114:115], v[124:125], v[150:151]
	s_movk_i32 s3, 0x1600
	v_pk_mul_f32 v[114:115], v[114:115], v[116:117]
	v_lshlrev_b64 v[116:117], 1, v[142:143]
	v_cvt_pk_f16_f32 v121, v114, v115
	v_mov_b64_e32 v[114:115], s[92:93]
	v_mad_i64_i32 v[122:123], s[10:11], v140, s3, v[114:115]
	v_lshl_add_u64 v[122:123], v[122:123], 0, v[116:117]
	global_store_dwordx4 v[122:123], v[118:121], off
	v_mul_f32_e32 v122, 0xbfb8aa3b, v106
	v_mul_f32_e32 v123, 0xbfb8aa3b, v107
	v_mul_f32_e32 v118, 0xbfb8aa3b, v110
	v_mul_f32_e32 v119, 0xbfb8aa3b, v111
	v_exp_f32_e32 v118, v118
	v_exp_f32_e32 v119, v119
	v_mul_f32_e32 v120, 0xbfb8aa3b, v112
	v_mul_f32_e32 v121, 0xbfb8aa3b, v113
	v_exp_f32_e32 v120, v120
	v_exp_f32_e32 v121, v121
	v_exp_f32_e32 v122, v122
	v_exp_f32_e32 v123, v123
	v_mul_f32_e32 v124, 0xbfb8aa3b, v108
	v_mul_f32_e32 v125, 0xbfb8aa3b, v109
	v_add_f32_e32 v118, 1.0, v118
	v_add_f32_e32 v119, 1.0, v119
	v_exp_f32_e32 v124, v124
	v_exp_f32_e32 v125, v125
	v_rcp_f32_e32 v118, v118
	v_rcp_f32_e32 v119, v119
	v_add_f32_e32 v120, 1.0, v120
	v_add_f32_e32 v121, 1.0, v121
	v_rcp_f32_e32 v120, v120
	v_rcp_f32_e32 v121, v121
	v_add_f32_e32 v122, 1.0, v122
	v_add_f32_e32 v123, 1.0, v123
	v_rcp_f32_e32 v122, v122
	v_rcp_f32_e32 v123, v123
	v_add_f32_e32 v124, 1.0, v124
	v_add_f32_e32 v125, 1.0, v125
	v_pk_mul_f32 v[110:111], v[110:111], v[118:119]
	v_rcp_f32_e32 v124, v124
	v_rcp_f32_e32 v125, v125
	v_pk_mul_f32 v[102:103], v[110:111], v[102:103]
	v_pk_mul_f32 v[110:111], v[112:113], v[120:121]
	v_cvt_pk_f16_f32 v102, v102, v103
	v_pk_mul_f32 v[104:105], v[110:111], v[104:105]
	s_and_b64 vcc, exec, s[0:1]
	v_cvt_pk_f16_f32 v103, v104, v105
	v_pk_mul_f32 v[104:105], v[106:107], v[122:123]
	s_mov_b32 s36, s35
	v_pk_mul_f32 v[98:99], v[104:105], v[98:99]
	s_mov_b32 s8, s2
	v_cvt_pk_f16_f32 v104, v98, v99
	v_pk_mul_f32 v[98:99], v[108:109], v[124:125]
	s_mov_b64 s[16:17], s[6:7]
	v_pk_mul_f32 v[98:99], v[98:99], v[100:101]
	v_mul_f32_e32 v100, 0xbfb8aa3b, v96
	v_cvt_pk_f16_f32 v105, v98, v99
	v_or_b32_e32 v98, 16, v140
	v_mad_i64_i32 v[98:99], s[10:11], v98, s3, v[114:115]
	v_lshl_add_u64 v[98:99], v[98:99], 0, v[116:117]
	global_store_dwordx4 v[98:99], v[102:105], off
	v_mul_f32_e32 v98, 0xbfb8aa3b, v94
	v_mul_f32_e32 v99, 0xbfb8aa3b, v95
	v_exp_f32_e32 v98, v98
	v_exp_f32_e32 v99, v99
	v_mul_f32_e32 v101, 0xbfb8aa3b, v97
	v_exp_f32_e32 v100, v100
	v_exp_f32_e32 v101, v101
	v_mul_f32_e32 v102, 0xbfb8aa3b, v90
	v_mul_f32_e32 v103, 0xbfb8aa3b, v91
	v_exp_f32_e32 v102, v102
	v_exp_f32_e32 v103, v103
	v_mul_f32_e32 v104, 0xbfb8aa3b, v92
	v_mul_f32_e32 v105, 0xbfb8aa3b, v93
	v_add_f32_e32 v98, 1.0, v98
	v_add_f32_e32 v99, 1.0, v99
	v_exp_f32_e32 v104, v104
	v_exp_f32_e32 v105, v105
	v_rcp_f32_e32 v98, v98
	v_rcp_f32_e32 v99, v99
	v_add_f32_e32 v100, 1.0, v100
	v_add_f32_e32 v101, 1.0, v101
	v_rcp_f32_e32 v100, v100
	v_rcp_f32_e32 v101, v101
	v_add_f32_e32 v102, 1.0, v102
	v_add_f32_e32 v103, 1.0, v103
	v_rcp_f32_e32 v102, v102
	v_rcp_f32_e32 v103, v103
	v_add_f32_e32 v104, 1.0, v104
	v_add_f32_e32 v105, 1.0, v105
	v_pk_mul_f32 v[94:95], v[94:95], v[98:99]
	v_rcp_f32_e32 v104, v104
	v_rcp_f32_e32 v105, v105
	v_pk_mul_f32 v[86:87], v[94:95], v[86:87]
	v_pk_mul_f32 v[94:95], v[96:97], v[100:101]
	v_cvt_pk_f16_f32 v86, v86, v87
	v_pk_mul_f32 v[88:89], v[94:95], v[88:89]
	s_mov_b64 s[14:15], s[4:5]
	v_cvt_pk_f16_f32 v87, v88, v89
	v_pk_mul_f32 v[88:89], v[90:91], v[102:103]
	s_nop 0
	v_pk_mul_f32 v[82:83], v[88:89], v[82:83]
	s_nop 0
	v_cvt_pk_f16_f32 v88, v82, v83
	v_pk_mul_f32 v[82:83], v[92:93], v[104:105]
	s_nop 0
	v_pk_mul_f32 v[82:83], v[82:83], v[84:85]
	v_mul_f32_e32 v84, 0xbfb8aa3b, v80
	v_cvt_pk_f16_f32 v89, v82, v83
	v_or_b32_e32 v82, 32, v140
	v_mad_i64_i32 v[82:83], s[10:11], v82, s3, v[114:115]
	v_lshl_add_u64 v[82:83], v[82:83], 0, v[116:117]
	global_store_dwordx4 v[82:83], v[86:89], off
	v_mul_f32_e32 v82, 0xbfb8aa3b, v78
	v_mul_f32_e32 v83, 0xbfb8aa3b, v79
	v_exp_f32_e32 v82, v82
	v_exp_f32_e32 v83, v83
	v_mul_f32_e32 v85, 0xbfb8aa3b, v81
	v_exp_f32_e32 v84, v84
	v_exp_f32_e32 v85, v85
	v_mul_f32_e32 v86, 0xbfb8aa3b, v74
	v_mul_f32_e32 v87, 0xbfb8aa3b, v75
	v_exp_f32_e32 v86, v86
	v_exp_f32_e32 v87, v87
	v_mul_f32_e32 v88, 0xbfb8aa3b, v76
	v_mul_f32_e32 v89, 0xbfb8aa3b, v77
	v_add_f32_e32 v82, 1.0, v82
	v_add_f32_e32 v83, 1.0, v83
	v_exp_f32_e32 v88, v88
	v_exp_f32_e32 v89, v89
	v_rcp_f32_e32 v82, v82
	v_rcp_f32_e32 v83, v83
	v_add_f32_e32 v84, 1.0, v84
	v_add_f32_e32 v85, 1.0, v85
	v_rcp_f32_e32 v84, v84
	v_rcp_f32_e32 v85, v85
	v_add_f32_e32 v86, 1.0, v86
	v_add_f32_e32 v87, 1.0, v87
	v_rcp_f32_e32 v86, v86
	v_rcp_f32_e32 v87, v87
	v_add_f32_e32 v88, 1.0, v88
	v_add_f32_e32 v89, 1.0, v89
	v_pk_mul_f32 v[78:79], v[78:79], v[82:83]
	v_rcp_f32_e32 v88, v88
	v_rcp_f32_e32 v89, v89
	v_pk_mul_f32 v[70:71], v[78:79], v[70:71]
	v_pk_mul_f32 v[78:79], v[80:81], v[84:85]
	v_cvt_pk_f16_f32 v70, v70, v71
	v_pk_mul_f32 v[72:73], v[78:79], v[72:73]
	s_nop 0
	v_cvt_pk_f16_f32 v71, v72, v73
	v_pk_mul_f32 v[72:73], v[74:75], v[86:87]
	v_add_u32_e32 v74, 0x80, v140
	v_pk_mul_f32 v[66:67], v[72:73], v[66:67]
	s_nop 0
	v_cvt_pk_f16_f32 v72, v66, v67
	v_pk_mul_f32 v[66:67], v[76:77], v[88:89]
	s_nop 0
	v_pk_mul_f32 v[66:67], v[66:67], v[68:69]
	v_mul_f32_e32 v68, 0xbfb8aa3b, v64
	v_cvt_pk_f16_f32 v73, v66, v67
	v_or_b32_e32 v66, 48, v140
	v_mad_i64_i32 v[66:67], s[10:11], v66, s3, v[114:115]
	v_lshl_add_u64 v[66:67], v[66:67], 0, v[116:117]
	global_store_dwordx4 v[66:67], v[70:73], off
	v_mul_f32_e32 v66, 0xbfb8aa3b, v62
	v_mul_f32_e32 v67, 0xbfb8aa3b, v63
	v_exp_f32_e32 v66, v66
	v_exp_f32_e32 v67, v67
	v_mul_f32_e32 v69, 0xbfb8aa3b, v65
	v_exp_f32_e32 v68, v68
	v_exp_f32_e32 v69, v69
	v_mul_f32_e32 v70, 0xbfb8aa3b, v58
	v_mul_f32_e32 v71, 0xbfb8aa3b, v59
	v_exp_f32_e32 v70, v70
	v_exp_f32_e32 v71, v71
	v_mul_f32_e32 v72, 0xbfb8aa3b, v60
	v_mul_f32_e32 v73, 0xbfb8aa3b, v61
	v_add_f32_e32 v66, 1.0, v66
	v_add_f32_e32 v67, 1.0, v67
	v_exp_f32_e32 v72, v72
	v_exp_f32_e32 v73, v73
	v_rcp_f32_e32 v66, v66
	v_rcp_f32_e32 v67, v67
	v_add_f32_e32 v68, 1.0, v68
	v_add_f32_e32 v69, 1.0, v69
	v_rcp_f32_e32 v68, v68
	v_rcp_f32_e32 v69, v69
	v_add_f32_e32 v70, 1.0, v70
	v_add_f32_e32 v71, 1.0, v71
	v_rcp_f32_e32 v70, v70
	v_rcp_f32_e32 v71, v71
	v_add_f32_e32 v72, 1.0, v72
	v_add_f32_e32 v73, 1.0, v73
	v_pk_mul_f32 v[62:63], v[62:63], v[66:67]
	v_rcp_f32_e32 v72, v72
	v_rcp_f32_e32 v73, v73
	v_pk_mul_f32 v[54:55], v[62:63], v[54:55]
	v_pk_mul_f32 v[62:63], v[64:65], v[68:69]
	v_cvt_pk_f16_f32 v54, v54, v55
	v_pk_mul_f32 v[56:57], v[62:63], v[56:57]
	s_nop 0
	v_cvt_pk_f16_f32 v55, v56, v57
	v_pk_mul_f32 v[56:57], v[58:59], v[70:71]
	s_nop 0
	v_pk_mul_f32 v[50:51], v[56:57], v[50:51]
	s_nop 0
	v_cvt_pk_f16_f32 v56, v50, v51
	v_pk_mul_f32 v[50:51], v[60:61], v[72:73]
	s_nop 0
	v_pk_mul_f32 v[50:51], v[50:51], v[52:53]
	v_mul_f32_e32 v52, 0xbfb8aa3b, v48
	v_cvt_pk_f16_f32 v57, v50, v51
	v_mad_i64_i32 v[50:51], s[10:11], v74, s3, v[114:115]
	v_lshl_add_u64 v[50:51], v[50:51], 0, v[116:117]
	global_store_dwordx4 v[50:51], v[54:57], off
	v_mul_f32_e32 v50, 0xbfb8aa3b, v46
	v_mul_f32_e32 v51, 0xbfb8aa3b, v47
	v_exp_f32_e32 v50, v50
	v_exp_f32_e32 v51, v51
	v_mul_f32_e32 v53, 0xbfb8aa3b, v49
	v_exp_f32_e32 v52, v52
	v_exp_f32_e32 v53, v53
	v_mul_f32_e32 v54, 0xbfb8aa3b, v42
	v_mul_f32_e32 v55, 0xbfb8aa3b, v43
	v_exp_f32_e32 v54, v54
	v_exp_f32_e32 v55, v55
	v_mul_f32_e32 v56, 0xbfb8aa3b, v44
	v_mul_f32_e32 v57, 0xbfb8aa3b, v45
	v_add_f32_e32 v50, 1.0, v50
	v_add_f32_e32 v51, 1.0, v51
	v_exp_f32_e32 v56, v56
	v_exp_f32_e32 v57, v57
	v_rcp_f32_e32 v50, v50
	v_rcp_f32_e32 v51, v51
	v_add_f32_e32 v52, 1.0, v52
	v_add_f32_e32 v53, 1.0, v53
	v_rcp_f32_e32 v52, v52
	v_rcp_f32_e32 v53, v53
	v_add_f32_e32 v54, 1.0, v54
	v_add_f32_e32 v55, 1.0, v55
	v_rcp_f32_e32 v54, v54
	v_rcp_f32_e32 v55, v55
	v_add_f32_e32 v56, 1.0, v56
	v_add_f32_e32 v57, 1.0, v57
	v_pk_mul_f32 v[46:47], v[46:47], v[50:51]
	v_rcp_f32_e32 v56, v56
	v_rcp_f32_e32 v57, v57
	v_pk_mul_f32 v[38:39], v[46:47], v[38:39]
	v_pk_mul_f32 v[46:47], v[48:49], v[52:53]
	v_cvt_pk_f16_f32 v38, v38, v39
	v_pk_mul_f32 v[40:41], v[46:47], v[40:41]
	s_nop 0
	v_cvt_pk_f16_f32 v39, v40, v41
	v_pk_mul_f32 v[40:41], v[42:43], v[54:55]
	s_nop 0
	v_pk_mul_f32 v[34:35], v[40:41], v[34:35]
	s_nop 0
	v_cvt_pk_f16_f32 v40, v34, v35
	v_pk_mul_f32 v[34:35], v[44:45], v[56:57]
	s_nop 0
	v_pk_mul_f32 v[34:35], v[34:35], v[36:37]
	v_mul_f32_e32 v36, 0xbfb8aa3b, v30
	v_cvt_pk_f16_f32 v41, v34, v35
	v_add_u32_e32 v34, 0x90, v140
	v_mad_i64_i32 v[34:35], s[10:11], v34, s3, v[114:115]
	v_lshl_add_u64 v[34:35], v[34:35], 0, v[116:117]
	global_store_dwordx4 v[34:35], v[38:41], off
	v_mul_f32_e32 v34, 0xbfb8aa3b, v28
	v_mul_f32_e32 v35, 0xbfb8aa3b, v29
	v_exp_f32_e32 v34, v34
	v_exp_f32_e32 v35, v35
	v_mul_f32_e32 v37, 0xbfb8aa3b, v31
	v_exp_f32_e32 v36, v36
	v_exp_f32_e32 v37, v37
	v_mul_f32_e32 v38, 0xbfb8aa3b, v24
	v_mul_f32_e32 v39, 0xbfb8aa3b, v25
	v_exp_f32_e32 v38, v38
	v_exp_f32_e32 v39, v39
	v_mul_f32_e32 v40, 0xbfb8aa3b, v26
	v_mul_f32_e32 v41, 0xbfb8aa3b, v27
	v_add_f32_e32 v34, 1.0, v34
	v_add_f32_e32 v35, 1.0, v35
	v_exp_f32_e32 v40, v40
	v_exp_f32_e32 v41, v41
	v_rcp_f32_e32 v34, v34
	v_rcp_f32_e32 v35, v35
	v_add_f32_e32 v36, 1.0, v36
	v_add_f32_e32 v37, 1.0, v37
	v_rcp_f32_e32 v36, v36
	v_rcp_f32_e32 v37, v37
	v_add_f32_e32 v38, 1.0, v38
	v_add_f32_e32 v39, 1.0, v39
	v_rcp_f32_e32 v38, v38
	v_rcp_f32_e32 v39, v39
	v_add_f32_e32 v40, 1.0, v40
	v_add_f32_e32 v41, 1.0, v41
	v_pk_mul_f32 v[28:29], v[28:29], v[34:35]
	v_rcp_f32_e32 v40, v40
	v_rcp_f32_e32 v41, v41
	v_pk_mul_f32 v[20:21], v[28:29], v[20:21]
	v_pk_mul_f32 v[28:29], v[30:31], v[36:37]
	v_cvt_pk_f16_f32 v20, v20, v21
	v_pk_mul_f32 v[22:23], v[28:29], v[22:23]
	s_nop 0
	v_cvt_pk_f16_f32 v21, v22, v23
	v_pk_mul_f32 v[22:23], v[24:25], v[38:39]
	s_nop 0
	v_pk_mul_f32 v[16:17], v[22:23], v[16:17]
	s_nop 0
	v_cvt_pk_f16_f32 v22, v16, v17
	v_pk_mul_f32 v[16:17], v[26:27], v[40:41]
	s_nop 0
	v_pk_mul_f32 v[16:17], v[16:17], v[18:19]
	v_mul_f32_e32 v18, 0xbfb8aa3b, v14
	v_cvt_pk_f16_f32 v23, v16, v17
	v_add_u32_e32 v16, 0xa0, v140
	v_mad_i64_i32 v[16:17], s[10:11], v16, s3, v[114:115]
	v_lshl_add_u64 v[16:17], v[16:17], 0, v[116:117]
	global_store_dwordx4 v[16:17], v[20:23], off
	v_mul_f32_e32 v16, 0xbfb8aa3b, v12
	v_mul_f32_e32 v17, 0xbfb8aa3b, v13
	v_exp_f32_e32 v16, v16
	v_exp_f32_e32 v17, v17
	v_mul_f32_e32 v19, 0xbfb8aa3b, v15
	v_exp_f32_e32 v18, v18
	v_exp_f32_e32 v19, v19
	v_mul_f32_e32 v20, 0xbfb8aa3b, v8
	v_mul_f32_e32 v21, 0xbfb8aa3b, v9
	v_exp_f32_e32 v20, v20
	v_exp_f32_e32 v21, v21
	v_mul_f32_e32 v22, 0xbfb8aa3b, v10
	v_mul_f32_e32 v23, 0xbfb8aa3b, v11
	v_add_f32_e32 v16, 1.0, v16
	v_add_f32_e32 v17, 1.0, v17
	v_exp_f32_e32 v22, v22
	v_exp_f32_e32 v23, v23
	v_rcp_f32_e32 v16, v16
	v_rcp_f32_e32 v17, v17
	v_add_f32_e32 v18, 1.0, v18
	v_add_f32_e32 v19, 1.0, v19
	v_rcp_f32_e32 v18, v18
	v_rcp_f32_e32 v19, v19
	v_add_f32_e32 v20, 1.0, v20
	v_add_f32_e32 v21, 1.0, v21
	v_rcp_f32_e32 v20, v20
	v_rcp_f32_e32 v21, v21
	v_add_f32_e32 v22, 1.0, v22
	v_add_f32_e32 v23, 1.0, v23
	v_pk_mul_f32 v[12:13], v[12:13], v[16:17]
	v_rcp_f32_e32 v22, v22
	v_rcp_f32_e32 v23, v23
	v_pk_mul_f32 v[4:5], v[12:13], v[4:5]
	v_pk_mul_f32 v[12:13], v[14:15], v[18:19]
	v_cvt_pk_f16_f32 v4, v4, v5
	v_pk_mul_f32 v[6:7], v[12:13], v[6:7]
	s_nop 0
	v_cvt_pk_f16_f32 v5, v6, v7
	v_pk_mul_f32 v[6:7], v[8:9], v[20:21]
	s_nop 0
	v_pk_mul_f32 v[0:1], v[6:7], v[0:1]
	s_nop 0
	v_cvt_pk_f16_f32 v6, v0, v1
	v_pk_mul_f32 v[0:1], v[10:11], v[22:23]
	s_nop 0
	v_pk_mul_f32 v[0:1], v[0:1], v[2:3]
	s_nop 0
	v_cvt_pk_f16_f32 v7, v0, v1
	v_add_u32_e32 v0, 0xb0, v140
	v_mad_i64_i32 v[0:1], s[10:11], v0, s3, v[114:115]
	v_lshl_add_u64 v[0:1], v[0:1], 0, v[116:117]
	global_store_dwordx4 v[0:1], v[4:7], off
	s_cmp_lg_u32 s34, 1
	s_cbranch_scc1 .Lups_skip
	s_and_b32 s0, s91, 63
	s_cmp_gt_u32 s0, 5
	s_cbranch_scc1 .Lups_skip
	s_cmp_gt_u32 s91, 196
	s_cbranch_scc1 .Lups_skip
	s_waitcnt vmcnt(0)
	s_barrier
	v_readlane_b32 s0, v251, 36
	s_cmp_lg_u32 s0, 0
	s_cbranch_scc1 .Lups_skip
	buffer_wbl2 sc1
	s_waitcnt vmcnt(0)
	v_readlane_b32 s2, v255, 45
	v_readlane_b32 s3, v254, 25
	s_lshl_b32 s2, s2, 1
	s_cmp_eq_u32 s3, 0
	s_cselect_b32 s3, 1, 0
	s_add_i32 s2, s2, s3
	s_lshl_b32 s2, s2, 2
	s_add_i32 s2, s2, 14016
	v_readlane_b32 s0, v251, 32
	v_readlane_b32 s1, v251, 33
	s_add_u32 s0, s0, s2
	s_addc_u32 s1, s1, 0
	s_mov_b64 s[2:3], exec
	s_mov_b64 exec, 1
	global_atomic_add v33, v248, s[0:1]
	s_mov_b64 exec, s[2:3]

.LBB0_1365:
	s_add_i32 s46, s14, 2
	s_add_u32 s12, s10, 0x100
	s_addc_u32 s13, s11, 0
	s_add_i32 s47, 0, 0x10000
	v_add_u32_e32 v134, s47, v230
	ds_read_b128 v[106:109], v134
	ds_read_b128 v[114:117], v134 offset:2048
	ds_read_b128 v[110:113], v134 offset:1024
	ds_read_b128 v[134:137], v134 offset:3072
	s_cmp_eq_u32 s43, s14
	s_cselect_b32 s14, s8, s44
	s_cselect_b32 s17, s7, s13
	s_cselect_b32 s16, s6, s12
	s_cselect_b32 s15, s9, s45
	v_lshl_add_u64 v[178:179], s[10:11], 0, v[184:185]
	s_add_i32 m0, s24, 0xc000
	ds_read_b128 v[138:141], v232
	ds_read_b128 v[154:157], v232 offset:2048
	ds_read_b128 v[162:165], v232 offset:4096
	ds_read_b128 v[170:173], v232 offset:6144
	ds_read_b128 v[150:153], v232 offset:1024
	ds_read_b128 v[158:161], v232 offset:3072
	ds_read_b128 v[166:169], v232 offset:5120
	ds_read_b128 v[174:177], v232 offset:7168
	global_load_lds_dwordx4 v[178:179], off
	v_lshl_add_u64 v[178:179], s[10:11], 0, v[186:187]
	s_add_i32 m0, s24, 0xe000
	s_nop 0
	global_load_lds_dwordx4 v[178:179], off
	s_waitcnt lgkmcnt(8)
	s_barrier
	s_waitcnt lgkmcnt(7)
	s_setprio 1
	v_mfma_f32_16x16x32_f16 v[146:149], v[106:109], v[138:141], v[146:149]
	v_mfma_f32_16x16x32_f16 v[142:145], v[114:117], v[138:141], v[142:145]
	s_waitcnt lgkmcnt(6)
	v_mfma_f32_16x16x32_f16 v[130:133], v[106:109], v[154:157], v[130:133]
	v_mfma_f32_16x16x32_f16 v[122:125], v[114:117], v[154:157], v[122:125]
	s_waitcnt lgkmcnt(5)
	v_mfma_f32_16x16x32_f16 v[94:97], v[106:109], v[162:165], v[94:97]
	v_mfma_f32_16x16x32_f16 v[90:93], v[114:117], v[162:165], v[90:93]
	s_waitcnt lgkmcnt(4)
	v_mfma_f32_16x16x32_f16 v[78:81], v[106:109], v[170:173], v[78:81]
	v_mfma_f32_16x16x32_f16 v[74:77], v[114:117], v[170:173], v[74:77]
	s_waitcnt lgkmcnt(3)
	v_mfma_f32_16x16x32_f16 v[146:149], v[110:113], v[150:153], v[146:149]
	v_mfma_f32_16x16x32_f16 v[142:145], v[134:137], v[150:153], v[142:145]
	s_waitcnt lgkmcnt(2)
	v_mfma_f32_16x16x32_f16 v[130:133], v[110:113], v[158:161], v[130:133]
	v_mfma_f32_16x16x32_f16 v[122:125], v[134:137], v[158:161], v[122:125]
	s_waitcnt lgkmcnt(1)
	v_mfma_f32_16x16x32_f16 v[94:97], v[110:113], v[166:169], v[94:97]
	v_mfma_f32_16x16x32_f16 v[90:93], v[134:137], v[166:169], v[90:93]
	s_waitcnt lgkmcnt(0)
	v_mfma_f32_16x16x32_f16 v[78:81], v[110:113], v[174:177], v[78:81]
	v_mfma_f32_16x16x32_f16 v[74:77], v[134:137], v[174:177], v[74:77]
	s_setprio 0
	s_barrier
	s_add_i32 s48, 0, 0x14000
	s_add_i32 s10, s47, s23
	v_add_u32_e32 v196, s48, v230
	v_lshl_add_u64 v[200:201], s[14:15], 0, v[32:33]
	s_mov_b32 m0, s10
	ds_read_b128 v[178:181], v196
	ds_read_b128 v[192:195], v196 offset:2048
	ds_read_b128 v[188:191], v196 offset:1024
	ds_read_b128 v[196:199], v196 offset:3072
	global_load_lds_dwordx4 v[200:201], off
	v_lshl_add_u64 v[202:203], s[14:15], 0, v[182:183]
	s_add_i32 m0, s10, 0x2000
	s_nop 0
	global_load_lds_dwordx4 v[202:203], off
	s_barrier
	s_waitcnt lgkmcnt(2)
	s_setprio 1
	v_mfma_f32_16x16x32_f16 v[126:129], v[178:181], v[138:141], v[126:129]
	v_mfma_f32_16x16x32_f16 v[118:121], v[192:195], v[138:141], v[118:121]
	v_mfma_f32_16x16x32_f16 v[102:105], v[178:181], v[154:157], v[102:105]
	v_mfma_f32_16x16x32_f16 v[98:101], v[192:195], v[154:157], v[98:101]
	v_mfma_f32_16x16x32_f16 v[86:89], v[178:181], v[162:165], v[86:89]
	v_mfma_f32_16x16x32_f16 v[82:85], v[192:195], v[162:165], v[82:85]
	v_mfma_f32_16x16x32_f16 v[70:73], v[178:181], v[170:173], v[70:73]
	v_mfma_f32_16x16x32_f16 v[66:69], v[192:195], v[170:173], v[66:69]
	s_waitcnt lgkmcnt(0)
	v_mfma_f32_16x16x32_f16 v[126:129], v[188:191], v[150:153], v[126:129]
	v_mfma_f32_16x16x32_f16 v[118:121], v[196:199], v[150:153], v[118:121]
	v_mfma_f32_16x16x32_f16 v[102:105], v[188:191], v[158:161], v[102:105]
	v_mfma_f32_16x16x32_f16 v[98:101], v[196:199], v[158:161], v[98:101]
	v_mfma_f32_16x16x32_f16 v[86:89], v[188:191], v[166:169], v[86:89]
	v_mfma_f32_16x16x32_f16 v[82:85], v[196:199], v[166:169], v[82:85]
	v_mfma_f32_16x16x32_f16 v[70:73], v[188:191], v[174:177], v[70:73]
	v_mfma_f32_16x16x32_f16 v[66:69], v[196:199], v[174:177], v[66:69]
	s_setprio 0
	s_mov_b32 m0, s24
	v_lshl_add_u64 v[204:205], s[16:17], 0, v[32:33]
	s_barrier
	ds_read_b128 v[138:141], v232 offset:16384
	ds_read_b128 v[154:157], v232 offset:18432
	ds_read_b128 v[162:165], v232 offset:20480
	ds_read_b128 v[170:173], v232 offset:22528
	ds_read_b128 v[150:153], v232 offset:17408
	ds_read_b128 v[158:161], v232 offset:19456
	ds_read_b128 v[166:169], v232 offset:21504
	ds_read_b128 v[174:177], v232 offset:23552
	global_load_lds_dwordx4 v[204:205], off
	v_lshl_add_u64 v[206:207], s[16:17], 0, v[182:183]
	s_mov_b32 m0, s25
	s_nop 0
	global_load_lds_dwordx4 v[206:207], off
	s_barrier
	s_waitcnt lgkmcnt(7)
	s_setprio 1
	v_mfma_f32_16x16x32_f16 v[62:65], v[106:109], v[138:141], v[62:65]
	v_mfma_f32_16x16x32_f16 v[58:61], v[114:117], v[138:141], v[58:61]
	s_waitcnt lgkmcnt(6)
	v_mfma_f32_16x16x32_f16 v[46:49], v[106:109], v[154:157], v[46:49]
	v_mfma_f32_16x16x32_f16 v[42:45], v[114:117], v[154:157], v[42:45]
	s_waitcnt lgkmcnt(5)
	v_mfma_f32_16x16x32_f16 v[28:31], v[106:109], v[162:165], v[28:31]
	v_mfma_f32_16x16x32_f16 v[24:27], v[114:117], v[162:165], v[24:27]
	s_waitcnt lgkmcnt(4)
	v_mfma_f32_16x16x32_f16 v[12:15], v[106:109], v[170:173], v[12:15]
	v_mfma_f32_16x16x32_f16 v[8:11], v[114:117], v[170:173], v[8:11]
	s_waitcnt lgkmcnt(3)
	v_mfma_f32_16x16x32_f16 v[62:65], v[110:113], v[150:153], v[62:65]
	v_mfma_f32_16x16x32_f16 v[58:61], v[134:137], v[150:153], v[58:61]
	s_waitcnt lgkmcnt(2)
	v_mfma_f32_16x16x32_f16 v[46:49], v[110:113], v[158:161], v[46:49]
	v_mfma_f32_16x16x32_f16 v[42:45], v[134:137], v[158:161], v[42:45]
	s_waitcnt lgkmcnt(1)
	v_mfma_f32_16x16x32_f16 v[28:31], v[110:113], v[166:169], v[28:31]
	v_mfma_f32_16x16x32_f16 v[24:27], v[134:137], v[166:169], v[24:27]
	s_waitcnt lgkmcnt(0)
	v_mfma_f32_16x16x32_f16 v[12:15], v[110:113], v[174:177], v[12:15]
	v_mfma_f32_16x16x32_f16 v[8:11], v[134:137], v[174:177], v[8:11]
	s_setprio 0
	s_barrier
	s_add_u32 s10, s14, 0xb0000
	s_addc_u32 s11, s15, 0
	s_add_i32 s47, s48, s23
	v_lshl_add_u64 v[106:107], s[10:11], 0, v[32:33]
	s_mov_b32 m0, s47
	s_nop 0
	global_load_lds_dwordx4 v[106:107], off
	v_lshl_add_u64 v[106:107], s[10:11], 0, v[182:183]
	s_add_i32 m0, s47, 0x2000
	s_nop 0
	global_load_lds_dwordx4 v[106:107], off
	s_waitcnt vmcnt(10)
	s_barrier
	s_setprio 1
	v_mfma_f32_16x16x32_f16 v[54:57], v[178:181], v[138:141], v[54:57]
	v_mfma_f32_16x16x32_f16 v[50:53], v[192:195], v[138:141], v[50:53]
	v_mfma_f32_16x16x32_f16 v[38:41], v[178:181], v[154:157], v[38:41]
	v_mfma_f32_16x16x32_f16 v[34:37], v[192:195], v[154:157], v[34:37]
	v_mfma_f32_16x16x32_f16 v[20:23], v[178:181], v[162:165], v[20:23]
	v_mfma_f32_16x16x32_f16 v[16:19], v[192:195], v[162:165], v[16:19]
	v_mfma_f32_16x16x32_f16 v[4:7], v[178:181], v[170:173], v[4:7]
	v_mfma_f32_16x16x32_f16 v[0:3], v[192:195], v[170:173], v[0:3]
	v_mfma_f32_16x16x32_f16 v[54:57], v[188:191], v[150:153], v[54:57]
	v_mfma_f32_16x16x32_f16 v[50:53], v[196:199], v[150:153], v[50:53]
	v_mfma_f32_16x16x32_f16 v[38:41], v[188:191], v[158:161], v[38:41]
	v_mfma_f32_16x16x32_f16 v[34:37], v[196:199], v[158:161], v[34:37]
	v_mfma_f32_16x16x32_f16 v[20:23], v[188:191], v[166:169], v[20:23]
	v_mfma_f32_16x16x32_f16 v[16:19], v[196:199], v[166:169], v[16:19]
	v_mfma_f32_16x16x32_f16 v[4:7], v[188:191], v[174:177], v[4:7]
	v_mfma_f32_16x16x32_f16 v[0:3], v[196:199], v[174:177], v[0:3]
	s_setprio 0
	s_add_i32 s47, 0, 0x18000
	v_add_u32_e32 v134, s47, v230
	s_barrier
	ds_read_b128 v[106:109], v134
	ds_read_b128 v[114:117], v134 offset:2048
	ds_read_b128 v[110:113], v134 offset:1024
	ds_read_b128 v[134:137], v134 offset:3072
	s_add_u32 s10, s16, 0xb0000
	s_addc_u32 s11, s17, 0
	s_mov_b32 m0, s26
	v_lshl_add_u64 v[178:179], s[10:11], 0, v[32:33]
	ds_read_b128 v[138:141], v232 offset:32768
	ds_read_b128 v[154:157], v232 offset:34816
	ds_read_b128 v[162:165], v232 offset:36864
	ds_read_b128 v[170:173], v232 offset:38912
	ds_read_b128 v[150:153], v232 offset:33792
	ds_read_b128 v[158:161], v232 offset:35840
	ds_read_b128 v[166:169], v232 offset:37888
	ds_read_b128 v[174:177], v232 offset:39936
	global_load_lds_dwordx4 v[178:179], off
	v_lshl_add_u64 v[178:179], s[10:11], 0, v[182:183]
	s_mov_b32 m0, s27
	s_nop 0
	global_load_lds_dwordx4 v[178:179], off
	s_waitcnt lgkmcnt(8)
	s_waitcnt vmcnt(10)
	s_barrier
	s_waitcnt lgkmcnt(7)
	s_setprio 1
	v_mfma_f32_16x16x32_f16 v[146:149], v[106:109], v[138:141], v[146:149]
	v_mfma_f32_16x16x32_f16 v[142:145], v[114:117], v[138:141], v[142:145]
	s_waitcnt lgkmcnt(6)
	v_mfma_f32_16x16x32_f16 v[130:133], v[106:109], v[154:157], v[130:133]
	v_mfma_f32_16x16x32_f16 v[122:125], v[114:117], v[154:157], v[122:125]
	s_waitcnt lgkmcnt(5)
	v_mfma_f32_16x16x32_f16 v[94:97], v[106:109], v[162:165], v[94:97]
	v_mfma_f32_16x16x32_f16 v[90:93], v[114:117], v[162:165], v[90:93]
	s_waitcnt lgkmcnt(4)
	v_mfma_f32_16x16x32_f16 v[78:81], v[106:109], v[170:173], v[78:81]
	v_mfma_f32_16x16x32_f16 v[74:77], v[114:117], v[170:173], v[74:77]
	s_waitcnt lgkmcnt(3)
	v_mfma_f32_16x16x32_f16 v[146:149], v[110:113], v[150:153], v[146:149]
	v_mfma_f32_16x16x32_f16 v[142:145], v[134:137], v[150:153], v[142:145]
	s_waitcnt lgkmcnt(2)
	v_mfma_f32_16x16x32_f16 v[130:133], v[110:113], v[158:161], v[130:133]
	v_mfma_f32_16x16x32_f16 v[122:125], v[134:137], v[158:161], v[122:125]
	s_waitcnt lgkmcnt(1)
	v_mfma_f32_16x16x32_f16 v[94:97], v[110:113], v[166:169], v[94:97]
	v_mfma_f32_16x16x32_f16 v[90:93], v[134:137], v[166:169], v[90:93]
	s_waitcnt lgkmcnt(0)
	v_mfma_f32_16x16x32_f16 v[78:81], v[110:113], v[174:177], v[78:81]
	v_mfma_f32_16x16x32_f16 v[74:77], v[134:137], v[174:177], v[74:77]
	s_setprio 0
	s_barrier
	s_add_i32 s16, 0, 0x1c000
	s_add_i32 s10, s47, s23
	v_add_u32_e32 v196, s16, v230
	v_lshl_add_u64 v[200:201], v[200:201], 0, s[84:85]
	s_mov_b32 m0, s10
	ds_read_b128 v[178:181], v196
	ds_read_b128 v[192:195], v196 offset:2048
	ds_read_b128 v[188:191], v196 offset:1024
	ds_read_b128 v[196:199], v196 offset:3072
	global_load_lds_dwordx4 v[200:201], off
	v_lshl_add_u64 v[200:201], v[202:203], 0, s[84:85]
	s_add_i32 m0, s10, 0x2000
	s_nop 0
	global_load_lds_dwordx4 v[200:201], off
	s_waitcnt vmcnt(10)
	s_barrier
	s_waitcnt lgkmcnt(2)
	s_setprio 1
	v_mfma_f32_16x16x32_f16 v[126:129], v[178:181], v[138:141], v[126:129]
	v_mfma_f32_16x16x32_f16 v[118:121], v[192:195], v[138:141], v[118:121]
	v_mfma_f32_16x16x32_f16 v[102:105], v[178:181], v[154:157], v[102:105]
	v_mfma_f32_16x16x32_f16 v[98:101], v[192:195], v[154:157], v[98:101]
	v_mfma_f32_16x16x32_f16 v[86:89], v[178:181], v[162:165], v[86:89]
	v_mfma_f32_16x16x32_f16 v[82:85], v[192:195], v[162:165], v[82:85]
	v_mfma_f32_16x16x32_f16 v[70:73], v[178:181], v[170:173], v[70:73]
	v_mfma_f32_16x16x32_f16 v[66:69], v[192:195], v[170:173], v[66:69]
	s_waitcnt lgkmcnt(0)
	v_mfma_f32_16x16x32_f16 v[126:129], v[188:191], v[150:153], v[126:129]
	v_mfma_f32_16x16x32_f16 v[118:121], v[196:199], v[150:153], v[118:121]
	v_mfma_f32_16x16x32_f16 v[102:105], v[188:191], v[158:161], v[102:105]
	v_mfma_f32_16x16x32_f16 v[98:101], v[196:199], v[158:161], v[98:101]
	v_mfma_f32_16x16x32_f16 v[86:89], v[188:191], v[166:169], v[86:89]
	v_mfma_f32_16x16x32_f16 v[82:85], v[196:199], v[166:169], v[82:85]
	v_mfma_f32_16x16x32_f16 v[70:73], v[188:191], v[174:177], v[70:73]
	v_mfma_f32_16x16x32_f16 v[66:69], v[196:199], v[174:177], v[66:69]
	s_setprio 0
	s_mov_b32 m0, s29
	v_lshl_add_u64 v[200:201], v[204:205], 0, s[84:85]
	s_barrier
	ds_read_b128 v[138:141], v232 offset:49152
	ds_read_b128 v[154:157], v232 offset:51200
	ds_read_b128 v[162:165], v232 offset:53248
	ds_read_b128 v[170:173], v232 offset:55296
	ds_read_b128 v[150:153], v232 offset:50176
	ds_read_b128 v[158:161], v232 offset:52224
	ds_read_b128 v[166:169], v232 offset:54272
	ds_read_b128 v[174:177], v232 offset:56320
	global_load_lds_dwordx4 v[200:201], off
	v_lshl_add_u64 v[200:201], v[206:207], 0, s[84:85]
	s_mov_b32 m0, s30
	s_nop 0
	global_load_lds_dwordx4 v[200:201], off
	s_barrier
	s_waitcnt lgkmcnt(7)
	s_setprio 1
	v_mfma_f32_16x16x32_f16 v[62:65], v[106:109], v[138:141], v[62:65]
	v_mfma_f32_16x16x32_f16 v[58:61], v[114:117], v[138:141], v[58:61]
	s_waitcnt lgkmcnt(6)
	v_mfma_f32_16x16x32_f16 v[46:49], v[106:109], v[154:157], v[46:49]
	v_mfma_f32_16x16x32_f16 v[42:45], v[114:117], v[154:157], v[42:45]
	s_waitcnt lgkmcnt(5)
	v_mfma_f32_16x16x32_f16 v[28:31], v[106:109], v[162:165], v[28:31]
	v_mfma_f32_16x16x32_f16 v[24:27], v[114:117], v[162:165], v[24:27]
	s_waitcnt lgkmcnt(4)
	v_mfma_f32_16x16x32_f16 v[12:15], v[106:109], v[170:173], v[12:15]
	v_mfma_f32_16x16x32_f16 v[8:11], v[114:117], v[170:173], v[8:11]
	s_waitcnt lgkmcnt(3)
	v_mfma_f32_16x16x32_f16 v[62:65], v[110:113], v[150:153], v[62:65]
	v_mfma_f32_16x16x32_f16 v[58:61], v[134:137], v[150:153], v[58:61]
	s_waitcnt lgkmcnt(2)
	v_mfma_f32_16x16x32_f16 v[46:49], v[110:113], v[158:161], v[46:49]
	v_mfma_f32_16x16x32_f16 v[42:45], v[134:137], v[158:161], v[42:45]
	s_waitcnt lgkmcnt(1)
	v_mfma_f32_16x16x32_f16 v[28:31], v[110:113], v[166:169], v[28:31]
	v_mfma_f32_16x16x32_f16 v[24:27], v[134:137], v[166:169], v[24:27]
	s_waitcnt lgkmcnt(0)
	v_mfma_f32_16x16x32_f16 v[12:15], v[110:113], v[174:177], v[12:15]
	v_mfma_f32_16x16x32_f16 v[8:11], v[134:137], v[174:177], v[8:11]
	s_setprio 0
	s_barrier
	s_add_u32 s10, s14, 0xb0080
	s_addc_u32 s11, s15, 0
	s_add_i32 s14, s16, s23
	v_lshl_add_u64 v[106:107], s[10:11], 0, v[32:33]
	s_mov_b32 m0, s14
	s_nop 0
	global_load_lds_dwordx4 v[106:107], off
	v_lshl_add_u64 v[106:107], s[10:11], 0, v[182:183]
	s_add_i32 m0, s14, 0x2000
	s_nop 0
	global_load_lds_dwordx4 v[106:107], off
	s_waitcnt vmcnt(6)
	s_barrier
	s_setprio 1
	v_mfma_f32_16x16x32_f16 v[54:57], v[178:181], v[138:141], v[54:57]
	v_mfma_f32_16x16x32_f16 v[50:53], v[192:195], v[138:141], v[50:53]
	v_mfma_f32_16x16x32_f16 v[38:41], v[178:181], v[154:157], v[38:41]
	v_mfma_f32_16x16x32_f16 v[34:37], v[192:195], v[154:157], v[34:37]
	v_mfma_f32_16x16x32_f16 v[20:23], v[178:181], v[162:165], v[20:23]
	v_mfma_f32_16x16x32_f16 v[16:19], v[192:195], v[162:165], v[16:19]
	v_mfma_f32_16x16x32_f16 v[4:7], v[178:181], v[170:173], v[4:7]
	v_mfma_f32_16x16x32_f16 v[0:3], v[192:195], v[170:173], v[0:3]
	v_mfma_f32_16x16x32_f16 v[54:57], v[188:191], v[150:153], v[54:57]
	v_mfma_f32_16x16x32_f16 v[50:53], v[196:199], v[150:153], v[50:53]
	v_mfma_f32_16x16x32_f16 v[38:41], v[188:191], v[158:161], v[38:41]
	v_mfma_f32_16x16x32_f16 v[34:37], v[196:199], v[158:161], v[34:37]
	v_mfma_f32_16x16x32_f16 v[20:23], v[188:191], v[166:169], v[20:23]
	v_mfma_f32_16x16x32_f16 v[16:19], v[196:199], v[166:169], v[16:19]
	v_mfma_f32_16x16x32_f16 v[4:7], v[188:191], v[174:177], v[4:7]
	v_mfma_f32_16x16x32_f16 v[0:3], v[196:199], v[174:177], v[0:3]
	s_setprio 0
	s_add_u32 s44, s44, 0x100
	s_addc_u32 s45, s45, 0
	s_cmp_ge_u32 s46, s42
	s_mov_b64 s[10:11], s[12:13]
	s_mov_b32 s14, s46
	s_barrier
	s_cbranch_scc0 .LBB0_1365
	s_cmp_eq_u32 s40, 0
	s_cselect_b32 s6, 0x9000, 0
	v_lshl_or_b32 v106, s41, 8, v231
	s_add_u32 s6, s31, s6
	s_addc_u32 s7, s34, 0
	v_ashrrev_i32_e32 v107, 31, v106
	v_lshl_add_u64 v[116:117], v[106:107], 2, s[6:7]
	global_load_dwordx4 v[108:111], v[116:117], off offset:16
	global_load_dwordx4 v[112:115], v[116:117], off
	s_cmp_eq_u32 s39, 0
	s_waitcnt vmcnt(0)
	v_pk_mul_f32 v[194:195], v[110:111], 0.5 op_sel_hi:[1,0]
	v_pk_mul_f32 v[198:199], v[114:115], 0.5 op_sel_hi:[1,0]
	v_pk_mul_f32 v[202:203], v[112:113], 0.5 op_sel_hi:[1,0]
	v_pk_mul_f32 v[200:201], v[108:109], 0.5 op_sel_hi:[1,0]
	global_load_dwordx4 v[108:111], v[116:117], off offset:528
	global_load_dwordx4 v[112:115], v[116:117], off offset:512
	s_waitcnt vmcnt(0)
	v_pk_mul_f32 v[188:189], v[110:111], 0.5 op_sel_hi:[1,0]
	v_pk_mul_f32 v[196:197], v[112:113], 0.5 op_sel_hi:[1,0]
	v_lshl_add_u32 v112, s40, 8, v229
	v_pk_mul_f32 v[190:191], v[114:115], 0.5 op_sel_hi:[1,0]
	v_pk_mul_f32 v[192:193], v[108:109], 0.5 op_sel_hi:[1,0]
	v_or_b32_e32 v114, 16, v112
	v_or_b32_e32 v110, 32, v112
	v_or_b32_e32 v108, 48, v112
	v_ashrrev_i32_e32 v113, 31, v112
	v_ashrrev_i32_e32 v115, 31, v114
	v_ashrrev_i32_e32 v111, 31, v110
	v_ashrrev_i32_e32 v109, 31, v108
	s_cbranch_scc1 .LBB0_1368
	s_add_i32 s96, s39, -1
	s_lshl_b64 s[6:7], s[96:97], 20
	v_readlane_b32 s8, v252, 11
	v_readlane_b32 s9, v252, 12
	s_add_u32 s6, s8, s6
	s_addc_u32 s7, s9, s7
	v_lshlrev_b64 v[138:139], 2, v[106:107]
	v_lshrrev_b32_e32 v150, 5, v220
	v_mul_u32_u24_e32 v150, 48, v150
	s_nop 0
	v_sub_co_u32_e32 v138, vcc, v138, v150
	s_nop 1
	v_subbrev_co_u32_e32 v139, vcc, 0, v139, vcc
	v_lshl_add_u64 v[138:139], s[6:7], 0, v[138:139]
	s_mov_b64 s[6:7], 0x80000
	v_lshlrev_b64 v[204:205], 12, v[112:113]
	v_lshl_add_u64 v[204:205], v[204:205], 0, v[138:139]
	v_lshl_add_u64 v[212:213], v[204:205], 0, s[6:7]
	v_lshlrev_b64 v[206:207], 12, v[114:115]
	v_lshl_add_u64 v[206:207], v[206:207], 0, v[138:139]
	v_lshl_add_u64 v[214:215], v[206:207], 0, s[6:7]
	v_lshlrev_b64 v[208:209], 12, v[110:111]
	v_lshl_add_u64 v[208:209], v[208:209], 0, v[138:139]
	v_lshl_add_u64 v[216:217], v[208:209], 0, s[6:7]
	v_lshlrev_b64 v[210:211], 12, v[108:109]
	v_lshl_add_u64 v[210:211], v[210:211], 0, v[138:139]
	v_lshl_add_u64 v[218:219], v[210:211], 0, s[6:7]
	s_waitcnt vmcnt(0)
	v_pk_mul_f32 v[152:153], v[146:147], v[202:203]
	v_pk_mul_f32 v[154:155], v[148:149], v[198:199]
	v_pk_mul_f32 v[156:157], v[142:143], v[200:201]
	v_pk_mul_f32 v[158:159], v[144:145], v[194:195]
	s_nop 1
	v_permlane32_swap_b32_e32 v152, v156
	v_permlane32_swap_b32_e32 v153, v157
	v_permlane32_swap_b32_e32 v154, v158
	v_permlane32_swap_b32_e32 v155, v159
	s_nop 0
	global_store_dwordx4 v[204:205], v[152:155], off
	global_store_dwordx4 v[204:205], v[156:159], off offset:64
	v_pk_mul_f32 v[160:161], v[126:127], v[196:197]
	v_pk_mul_f32 v[162:163], v[128:129], v[190:191]
	v_pk_mul_f32 v[164:165], v[118:119], v[192:193]
	v_pk_mul_f32 v[166:167], v[120:121], v[188:189]
	s_nop 1
	v_permlane32_swap_b32_e32 v160, v164
	v_permlane32_swap_b32_e32 v161, v165
	v_permlane32_swap_b32_e32 v162, v166
	v_permlane32_swap_b32_e32 v163, v167
	s_nop 0
	global_store_dwordx4 v[204:205], v[160:163], off offset:512
	global_store_dwordx4 v[204:205], v[164:167], off offset:576
	v_pk_mul_f32 v[168:169], v[130:131], v[202:203]
	v_pk_mul_f32 v[170:171], v[132:133], v[198:199]
	v_pk_mul_f32 v[172:173], v[122:123], v[200:201]
	v_pk_mul_f32 v[174:175], v[124:125], v[194:195]
	s_nop 1
	v_permlane32_swap_b32_e32 v168, v172
	v_permlane32_swap_b32_e32 v169, v173
	v_permlane32_swap_b32_e32 v170, v174
	v_permlane32_swap_b32_e32 v171, v175
	s_nop 0
	global_store_dwordx4 v[206:207], v[168:171], off
	global_store_dwordx4 v[206:207], v[172:175], off offset:64
	v_pk_mul_f32 v[176:177], v[102:103], v[196:197]
	v_pk_mul_f32 v[178:179], v[104:105], v[190:191]
	v_pk_mul_f32 v[180:181], v[98:99], v[192:193]
	v_pk_mul_f32 v[182:183], v[100:101], v[188:189]
	s_nop 1
	v_permlane32_swap_b32_e32 v176, v180
	v_permlane32_swap_b32_e32 v177, v181
	v_permlane32_swap_b32_e32 v178, v182
	v_permlane32_swap_b32_e32 v179, v183
	s_nop 0
	global_store_dwordx4 v[206:207], v[176:179], off offset:512
	global_store_dwordx4 v[206:207], v[180:183], off offset:576
	v_pk_mul_f32 v[152:153], v[94:95], v[202:203]
	v_pk_mul_f32 v[154:155], v[96:97], v[198:199]
	v_pk_mul_f32 v[156:157], v[90:91], v[200:201]
	v_pk_mul_f32 v[158:159], v[92:93], v[194:195]
	s_nop 1
	v_permlane32_swap_b32_e32 v152, v156
	v_permlane32_swap_b32_e32 v153, v157
	v_permlane32_swap_b32_e32 v154, v158
	v_permlane32_swap_b32_e32 v155, v159
	s_nop 0
	global_store_dwordx4 v[208:209], v[152:155], off
	global_store_dwordx4 v[208:209], v[156:159], off offset:64
	v_pk_mul_f32 v[160:161], v[86:87], v[196:197]
	v_pk_mul_f32 v[162:163], v[88:89], v[190:191]
	v_pk_mul_f32 v[164:165], v[82:83], v[192:193]
	v_pk_mul_f32 v[166:167], v[84:85], v[188:189]
	s_nop 1
	v_permlane32_swap_b32_e32 v160, v164
	v_permlane32_swap_b32_e32 v161, v165
	v_permlane32_swap_b32_e32 v162, v166
	v_permlane32_swap_b32_e32 v163, v167
	s_nop 0
	global_store_dwordx4 v[208:209], v[160:163], off offset:512
	global_store_dwordx4 v[208:209], v[164:167], off offset:576
	v_pk_mul_f32 v[168:169], v[78:79], v[202:203]
	v_pk_mul_f32 v[170:171], v[80:81], v[198:199]
	v_pk_mul_f32 v[172:173], v[74:75], v[200:201]
	v_pk_mul_f32 v[174:175], v[76:77], v[194:195]
	s_nop 1
	v_permlane32_swap_b32_e32 v168, v172
	v_permlane32_swap_b32_e32 v169, v173
	v_permlane32_swap_b32_e32 v170, v174
	v_permlane32_swap_b32_e32 v171, v175
	s_nop 0
	global_store_dwordx4 v[210:211], v[168:171], off
	global_store_dwordx4 v[210:211], v[172:175], off offset:64
	v_pk_mul_f32 v[176:177], v[70:71], v[196:197]
	v_pk_mul_f32 v[178:179], v[72:73], v[190:191]
	v_pk_mul_f32 v[180:181], v[66:67], v[192:193]
	v_pk_mul_f32 v[182:183], v[68:69], v[188:189]
	s_nop 1
	v_permlane32_swap_b32_e32 v176, v180
	v_permlane32_swap_b32_e32 v177, v181
	v_permlane32_swap_b32_e32 v178, v182
	v_permlane32_swap_b32_e32 v179, v183
	s_nop 0
	global_store_dwordx4 v[210:211], v[176:179], off offset:512
	global_store_dwordx4 v[210:211], v[180:183], off offset:576
	v_pk_mul_f32 v[152:153], v[62:63], v[202:203]
	v_pk_mul_f32 v[154:155], v[64:65], v[198:199]
	v_pk_mul_f32 v[156:157], v[58:59], v[200:201]
	v_pk_mul_f32 v[158:159], v[60:61], v[194:195]
	s_nop 1
	v_permlane32_swap_b32_e32 v152, v156
	v_permlane32_swap_b32_e32 v153, v157
	v_permlane32_swap_b32_e32 v154, v158
	v_permlane32_swap_b32_e32 v155, v159
	s_nop 0
	global_store_dwordx4 v[212:213], v[152:155], off
	global_store_dwordx4 v[212:213], v[156:159], off offset:64
	v_pk_mul_f32 v[160:161], v[54:55], v[196:197]
	v_pk_mul_f32 v[162:163], v[56:57], v[190:191]
	v_pk_mul_f32 v[164:165], v[50:51], v[192:193]
	v_pk_mul_f32 v[166:167], v[52:53], v[188:189]
	s_nop 1
	v_permlane32_swap_b32_e32 v160, v164
	v_permlane32_swap_b32_e32 v161, v165
	v_permlane32_swap_b32_e32 v162, v166
	v_permlane32_swap_b32_e32 v163, v167
	s_nop 0
	global_store_dwordx4 v[212:213], v[160:163], off offset:512
	global_store_dwordx4 v[212:213], v[164:167], off offset:576
	v_pk_mul_f32 v[168:169], v[46:47], v[202:203]
	v_pk_mul_f32 v[170:171], v[48:49], v[198:199]
	v_pk_mul_f32 v[172:173], v[42:43], v[200:201]
	v_pk_mul_f32 v[174:175], v[44:45], v[194:195]
	s_nop 1
	v_permlane32_swap_b32_e32 v168, v172
	v_permlane32_swap_b32_e32 v169, v173
	v_permlane32_swap_b32_e32 v170, v174
	v_permlane32_swap_b32_e32 v171, v175
	s_nop 0
	global_store_dwordx4 v[214:215], v[168:171], off
	global_store_dwordx4 v[214:215], v[172:175], off offset:64
	v_pk_mul_f32 v[176:177], v[38:39], v[196:197]
	v_pk_mul_f32 v[178:179], v[40:41], v[190:191]
	v_pk_mul_f32 v[180:181], v[34:35], v[192:193]
	v_pk_mul_f32 v[182:183], v[36:37], v[188:189]
	s_nop 1
	v_permlane32_swap_b32_e32 v176, v180
	v_permlane32_swap_b32_e32 v177, v181
	v_permlane32_swap_b32_e32 v178, v182
	v_permlane32_swap_b32_e32 v179, v183
	s_nop 0
	global_store_dwordx4 v[214:215], v[176:179], off offset:512
	global_store_dwordx4 v[214:215], v[180:183], off offset:576
	v_pk_mul_f32 v[152:153], v[28:29], v[202:203]
	v_pk_mul_f32 v[154:155], v[30:31], v[198:199]
	v_pk_mul_f32 v[156:157], v[24:25], v[200:201]
	v_pk_mul_f32 v[158:159], v[26:27], v[194:195]
	s_nop 1
	v_permlane32_swap_b32_e32 v152, v156
	v_permlane32_swap_b32_e32 v153, v157
	v_permlane32_swap_b32_e32 v154, v158
	v_permlane32_swap_b32_e32 v155, v159
	s_nop 0
	global_store_dwordx4 v[216:217], v[152:155], off
	global_store_dwordx4 v[216:217], v[156:159], off offset:64
	v_pk_mul_f32 v[160:161], v[20:21], v[196:197]
	v_pk_mul_f32 v[162:163], v[22:23], v[190:191]
	v_pk_mul_f32 v[164:165], v[16:17], v[192:193]
	v_pk_mul_f32 v[166:167], v[18:19], v[188:189]
	s_nop 1
	v_permlane32_swap_b32_e32 v160, v164
	v_permlane32_swap_b32_e32 v161, v165
	v_permlane32_swap_b32_e32 v162, v166
	v_permlane32_swap_b32_e32 v163, v167
	s_nop 0
	global_store_dwordx4 v[216:217], v[160:163], off offset:512
	global_store_dwordx4 v[216:217], v[164:167], off offset:576
	v_pk_mul_f32 v[168:169], v[12:13], v[202:203]
	v_pk_mul_f32 v[170:171], v[14:15], v[198:199]
	v_pk_mul_f32 v[172:173], v[8:9], v[200:201]
	v_pk_mul_f32 v[174:175], v[10:11], v[194:195]
	s_nop 1
	v_permlane32_swap_b32_e32 v168, v172
	v_permlane32_swap_b32_e32 v169, v173
	v_permlane32_swap_b32_e32 v170, v174
	v_permlane32_swap_b32_e32 v171, v175
	s_nop 0
	global_store_dwordx4 v[218:219], v[168:171], off
	global_store_dwordx4 v[218:219], v[172:175], off offset:64
	v_pk_mul_f32 v[176:177], v[4:5], v[196:197]
	v_pk_mul_f32 v[178:179], v[6:7], v[190:191]
	v_pk_mul_f32 v[180:181], v[0:1], v[192:193]
	v_pk_mul_f32 v[182:183], v[2:3], v[188:189]
	s_nop 1
	v_permlane32_swap_b32_e32 v176, v180
	v_permlane32_swap_b32_e32 v177, v181
	v_permlane32_swap_b32_e32 v178, v182
	v_permlane32_swap_b32_e32 v179, v183
	s_nop 0
	global_store_dwordx4 v[218:219], v[176:179], off offset:512
	global_store_dwordx4 v[218:219], v[180:183], off offset:576
	s_cbranch_execnz .LBB0_1352
	s_branch .LBB0_1351
